# GEMM K loops: per-phase counted vmcnt(10) one phase before each half-tile's first read instead of two vmcnt(6) per iteration
# baseline (speedup 1.0000x reference)
; #define STG(P, GB) do { const char* _gb = (GB); \
;     _Pragma("unroll") for (int _i = 0; _i < 2; ++_i) { \
;       __builtin_amdgcn_global_load_lds((const unsigned*)(_gb + voff[_i]), \
;         (LAS unsigned*)((LAS char*)(P) + ldsw + _i * 8192), 16, 0, 0); } } while (0)
; #define LDA(dst, b, h) _Pragma("unroll") for (int m = 0; m < 4; ++m) _Pragma("unroll") for (int k = 0; k < 2; ++k) \
;     dst[m][k] = *(const LAS bf16x8*)((LAS char*)SA(b, h) + aoff + m * 2048 + k * 1024)
; #define LDB(dst, b, h) _Pragma("unroll") for (int n = 0; n < 2; ++n) _Pragma("unroll") for (int k = 0; k < 2; ++k) \
;     dst[n][k] = *(const LAS bf16x8*)((LAS char*)SB(b, h) + boff + n * 2048 + k * 1024)
; #define MMA(ai, bj, At_, Bt_) do { __builtin_amdgcn_s_setprio(1); \
;     _Pragma("unroll") for (int m = 0; m < 4; ++m) _Pragma("unroll") for (int n = 0; n < 2; ++n) _Pragma("unroll") for (int k = 0; k < 2; ++k) \
;       acc[ai][bj][m][n] = __builtin_amdgcn_mfma_f32_16x16x32_bf16(Bt_[n][k], At_[m][k], acc[ai][bj][m][n], 0, 0, 0); \
;     __builtin_amdgcn_s_setprio(0); } while (0)
; #define WAIT_V(n) asm volatile("s_waitcnt vmcnt(" #n ")" ::: "memory")
; #define WAIT_L(n) asm volatile("s_waitcnt lgkmcnt(" #n ")" ::: "memory")
; #define BAR __builtin_amdgcn_s_barrier()
; #define SCHED __builtin_amdgcn_sched_barrier(0)
; __device__ __forceinline__ void gemm_phase(const bf16_t* __restrict__ A, const bf16_t* __restrict__ Bt, bf16_t* __restrict__ C, int M, int N, int K,
;                                            int ldc, const int EPI, char* smem, const int wid_u) {
;     ...
;       LDB(B0, 0, 0); SCHED; LDA(At, 0, 0); STG(SA(1, 1), a1 + hstep);
;       WAIT_L(8); BAR; WAIT_L(0); MMA(0, 0, At, B0); BAR; SCHED;
;       LDB(B1, 0, 1); STG(SB(0, 0), b2);
;       BAR; WAIT_L(0); MMA(0, 1, At, B1); BAR;
;       LDA(At, 0, 1); STG(SA(0, 0), a2);
;       BAR; WAIT_L(0); MMA(1, 0, At, B0); BAR; SCHED;
;       STG(SB(0, 1), b2 + hstep);
;       WAIT_V(6); BAR; MMA(1, 1, At, B1); BAR;
;       LDB(B0, 1, 0); SCHED; LDA(At, 1, 0); STG(SA(0, 1), a2 + hstep);
;       WAIT_L(8); BAR; WAIT_L(0); MMA(0, 0, At, B0); BAR; SCHED;
.LBB0_145:
	ds_read_b128 v[150:153], v146
	ds_read_b128 v[154:157], v146 offset:1024
	ds_read_b128 v[158:161], v146 offset:2048
	ds_read_b128 v[162:165], v146 offset:3072
	s_add_u32 s18, s16, 0x100
	s_addc_u32 s19, s17, 0
	s_cmp_eq_u32 s49, 12
	s_cselect_b32 s23, s44, s19
	s_cselect_b32 s22, s45, s18
	s_cselect_b32 s21, s11, s48
	s_cselect_b32 s20, s46, s47
	v_lshl_add_u64 v[142:143], s[16:17], 0, v[136:137]
	s_add_i32 m0, s28, 0xc000
	ds_read_b128 v[166:169], v147
	ds_read_b128 v[170:173], v147 offset:1024
	ds_read_b128 v[174:177], v147 offset:2048
	ds_read_b128 v[178:181], v147 offset:3072
	ds_read_b128 v[182:185], v147 offset:4096
	ds_read_b128 v[186:189], v147 offset:5120
	ds_read_b128 v[190:193], v147 offset:6144
	ds_read_b128 v[194:197], v147 offset:7168
	global_load_lds_dwordx4 v[142:143], off
	v_lshl_add_u64 v[142:143], s[16:17], 0, v[134:135]
	s_add_i32 m0, s28, 0xe000
	s_nop 0
	global_load_lds_dwordx4 v[142:143], off
	s_waitcnt vmcnt(10)
	s_waitcnt lgkmcnt(8)
	s_barrier
	s_waitcnt lgkmcnt(0)
	s_waitcnt lgkmcnt(0)
	v_mfma_f32_16x16x32_bf16 v[124:127], v[150:153], v[166:169], v[124:127]
	v_mfma_f32_16x16x32_bf16 v[120:123], v[158:161], v[166:169], v[120:123]
	v_mfma_f32_16x16x32_bf16 v[108:111], v[150:153], v[174:177], v[108:111]
	v_mfma_f32_16x16x32_bf16 v[104:107], v[158:161], v[174:177], v[104:107]
	v_mfma_f32_16x16x32_bf16 v[92:95], v[150:153], v[182:185], v[92:95]
	v_mfma_f32_16x16x32_bf16 v[88:91], v[158:161], v[182:185], v[88:91]
	v_mfma_f32_16x16x32_bf16 v[76:79], v[150:153], v[190:193], v[76:79]
	v_mfma_f32_16x16x32_bf16 v[72:75], v[158:161], v[190:193], v[72:75]
	v_mfma_f32_16x16x32_bf16 v[124:127], v[154:157], v[170:173], v[124:127]
	v_mfma_f32_16x16x32_bf16 v[120:123], v[162:165], v[170:173], v[120:123]
	v_mfma_f32_16x16x32_bf16 v[108:111], v[154:157], v[178:181], v[108:111]
	v_mfma_f32_16x16x32_bf16 v[104:107], v[162:165], v[178:181], v[104:107]
	v_mfma_f32_16x16x32_bf16 v[92:95], v[154:157], v[186:189], v[92:95]
	v_mfma_f32_16x16x32_bf16 v[88:91], v[162:165], v[186:189], v[88:91]
	v_mfma_f32_16x16x32_bf16 v[76:79], v[154:157], v[194:197], v[76:79]
	v_mfma_f32_16x16x32_bf16 v[72:75], v[162:165], v[194:197], v[72:75]
	s_barrier
	s_add_i32 s16, s36, s27
	v_lshl_add_u64 v[142:143], s[20:21], 0, v[130:131]
	s_mov_b32 m0, s16
	ds_read_b128 v[198:201], v148
	ds_read_b128 v[202:205], v148 offset:1024
	ds_read_b128 v[206:209], v148 offset:2048
	ds_read_b128 v[210:213], v148 offset:3072
	global_load_lds_dwordx4 v[142:143], off
	v_lshl_add_u64 v[214:215], s[20:21], 0, v[128:129]
	s_add_i32 m0, s16, 0x2000
	s_nop 0
	global_load_lds_dwordx4 v[214:215], off
	s_waitcnt vmcnt(10)
	s_barrier
	s_waitcnt lgkmcnt(0)
	s_waitcnt lgkmcnt(0)
	v_mfma_f32_16x16x32_bf16 v[116:119], v[198:201], v[166:169], v[116:119]
	v_mfma_f32_16x16x32_bf16 v[112:115], v[206:209], v[166:169], v[112:115]
	v_mfma_f32_16x16x32_bf16 v[100:103], v[198:201], v[174:177], v[100:103]
	v_mfma_f32_16x16x32_bf16 v[96:99], v[206:209], v[174:177], v[96:99]
	v_mfma_f32_16x16x32_bf16 v[84:87], v[198:201], v[182:185], v[84:87]
	v_mfma_f32_16x16x32_bf16 v[80:83], v[206:209], v[182:185], v[80:83]
	v_mfma_f32_16x16x32_bf16 v[68:71], v[198:201], v[190:193], v[68:71]
	v_mfma_f32_16x16x32_bf16 v[64:67], v[206:209], v[190:193], v[64:67]
	v_mfma_f32_16x16x32_bf16 v[116:119], v[202:205], v[170:173], v[116:119]
	v_mfma_f32_16x16x32_bf16 v[112:115], v[210:213], v[170:173], v[112:115]
	v_mfma_f32_16x16x32_bf16 v[100:103], v[202:205], v[178:181], v[100:103]
	v_mfma_f32_16x16x32_bf16 v[96:99], v[210:213], v[178:181], v[96:99]
	v_mfma_f32_16x16x32_bf16 v[84:87], v[202:205], v[186:189], v[84:87]
	v_mfma_f32_16x16x32_bf16 v[80:83], v[210:213], v[186:189], v[80:83]
	v_mfma_f32_16x16x32_bf16 v[68:71], v[202:205], v[194:197], v[68:71]
	v_mfma_f32_16x16x32_bf16 v[64:67], v[210:213], v[194:197], v[64:67]
	s_mov_b32 m0, s28
	v_lshl_add_u64 v[216:217], s[22:23], 0, v[130:131]
	s_barrier
	ds_read_b128 v[166:169], v147 offset:16384
	ds_read_b128 v[170:173], v147 offset:17408
	ds_read_b128 v[174:177], v147 offset:18432
	ds_read_b128 v[178:181], v147 offset:19456
	ds_read_b128 v[182:185], v147 offset:20480
	ds_read_b128 v[186:189], v147 offset:21504
	ds_read_b128 v[190:193], v147 offset:22528
	ds_read_b128 v[194:197], v147 offset:23552
	global_load_lds_dwordx4 v[216:217], off
	v_lshl_add_u64 v[218:219], s[22:23], 0, v[128:129]
	s_mov_b32 m0, s29
	s_nop 0
	global_load_lds_dwordx4 v[218:219], off
	s_barrier
	s_waitcnt lgkmcnt(0)
	s_waitcnt lgkmcnt(0)
	v_mfma_f32_16x16x32_bf16 v[60:63], v[150:153], v[166:169], v[60:63]
	v_mfma_f32_16x16x32_bf16 v[56:59], v[158:161], v[166:169], v[56:59]
	v_mfma_f32_16x16x32_bf16 v[44:47], v[150:153], v[174:177], v[44:47]
	v_mfma_f32_16x16x32_bf16 v[40:43], v[158:161], v[174:177], v[40:43]
	v_mfma_f32_16x16x32_bf16 v[28:31], v[150:153], v[182:185], v[28:31]
	v_mfma_f32_16x16x32_bf16 v[24:27], v[158:161], v[182:185], v[24:27]
	v_mfma_f32_16x16x32_bf16 v[12:15], v[150:153], v[190:193], v[12:15]
	v_mfma_f32_16x16x32_bf16 v[8:11], v[158:161], v[190:193], v[8:11]
	v_mfma_f32_16x16x32_bf16 v[60:63], v[154:157], v[170:173], v[60:63]
	v_mfma_f32_16x16x32_bf16 v[56:59], v[162:165], v[170:173], v[56:59]
	v_mfma_f32_16x16x32_bf16 v[44:47], v[154:157], v[178:181], v[44:47]
	v_mfma_f32_16x16x32_bf16 v[40:43], v[162:165], v[178:181], v[40:43]
	v_mfma_f32_16x16x32_bf16 v[28:31], v[154:157], v[186:189], v[28:31]
	v_mfma_f32_16x16x32_bf16 v[24:27], v[162:165], v[186:189], v[24:27]
	v_mfma_f32_16x16x32_bf16 v[12:15], v[154:157], v[194:197], v[12:15]
	v_mfma_f32_16x16x32_bf16 v[8:11], v[162:165], v[194:197], v[8:11]
	s_barrier
; #define STG(P, GB) do { const char* _gb = (GB); \
;     _Pragma("unroll") for (int _i = 0; _i < 2; ++_i) { \
;       __builtin_amdgcn_global_load_lds((const unsigned*)(_gb + voff[_i]), \
;         (LAS unsigned*)((LAS char*)(P) + ldsw + _i * 8192), 16, 0, 0); } } while (0)
; #define LDA(dst, b, h) _Pragma("unroll") for (int m = 0; m < 4; ++m) _Pragma("unroll") for (int k = 0; k < 2; ++k) \
;     dst[m][k] = *(const LAS bf16x8*)((LAS char*)SA(b, h) + aoff + m * 2048 + k * 1024)
; #define LDB(dst, b, h) _Pragma("unroll") for (int n = 0; n < 2; ++n) _Pragma("unroll") for (int k = 0; k < 2; ++k) \
;     dst[n][k] = *(const LAS bf16x8*)((LAS char*)SB(b, h) + boff + n * 2048 + k * 1024)
; #define MMA(ai, bj, At_, Bt_) do { __builtin_amdgcn_s_setprio(1); \
;     _Pragma("unroll") for (int m = 0; m < 4; ++m) _Pragma("unroll") for (int n = 0; n < 2; ++n) _Pragma("unroll") for (int k = 0; k < 2; ++k) \
;       acc[ai][bj][m][n] = __builtin_amdgcn_mfma_f32_16x16x32_bf16(Bt_[n][k], At_[m][k], acc[ai][bj][m][n], 0, 0, 0); \
;     __builtin_amdgcn_s_setprio(0); } while (0)
; #define WAIT_V(n) asm volatile("s_waitcnt vmcnt(" #n ")" ::: "memory")
; #define WAIT_L(n) asm volatile("s_waitcnt lgkmcnt(" #n ")" ::: "memory")
; #define BAR __builtin_amdgcn_s_barrier()
; #define SCHED __builtin_amdgcn_sched_barrier(0)
; __device__ __forceinline__ void gemm_phase(const bf16_t* __restrict__ A, const bf16_t* __restrict__ Bt, bf16_t* __restrict__ C, int M, int N, int K,
;                                            int ldc, const int EPI, char* smem, const int wid_u) {
;     ...
;       WAIT_V(6); BAR; MMA(1, 1, At, B1); BAR;
;       LDB(B0, 1, 0); SCHED; LDA(At, 1, 0); STG(SA(0, 1), a2 + hstep);
;       WAIT_L(8); BAR; WAIT_L(0); MMA(0, 0, At, B0); BAR; SCHED;
;       LDB(B1, 1, 1); STG(SB(1, 0), b3);
;       BAR; WAIT_L(0); MMA(0, 1, At, B1); BAR;
;       LDA(At, 1, 1); STG(SA(1, 0), a3);
	s_add_u32 s16, s20, 0x40000
	s_addc_u32 s17, s21, 0
	s_add_i32 s50, s37, s27
	v_lshl_add_u64 v[150:151], s[16:17], 0, v[130:131]
	s_mov_b32 m0, s50
	s_nop 0
	global_load_lds_dwordx4 v[150:151], off
	v_lshl_add_u64 v[150:151], s[16:17], 0, v[128:129]
	s_add_i32 m0, s50, 0x2000
	s_nop 0
	global_load_lds_dwordx4 v[150:151], off
	s_waitcnt vmcnt(10)
	s_barrier
	v_mfma_f32_16x16x32_bf16 v[52:55], v[198:201], v[166:169], v[52:55]
	v_mfma_f32_16x16x32_bf16 v[48:51], v[206:209], v[166:169], v[48:51]
	v_mfma_f32_16x16x32_bf16 v[36:39], v[198:201], v[174:177], v[36:39]
	v_mfma_f32_16x16x32_bf16 v[32:35], v[206:209], v[174:177], v[32:35]
	v_mfma_f32_16x16x32_bf16 v[20:23], v[198:201], v[182:185], v[20:23]
	v_mfma_f32_16x16x32_bf16 v[16:19], v[206:209], v[182:185], v[16:19]
	v_mfma_f32_16x16x32_bf16 v[4:7], v[198:201], v[190:193], v[4:7]
	v_mfma_f32_16x16x32_bf16 v[0:3], v[206:209], v[190:193], v[0:3]
	v_mfma_f32_16x16x32_bf16 v[52:55], v[202:205], v[170:173], v[52:55]
	v_mfma_f32_16x16x32_bf16 v[48:51], v[210:213], v[170:173], v[48:51]
	v_mfma_f32_16x16x32_bf16 v[36:39], v[202:205], v[178:181], v[36:39]
	v_mfma_f32_16x16x32_bf16 v[32:35], v[210:213], v[178:181], v[32:35]
	v_mfma_f32_16x16x32_bf16 v[20:23], v[202:205], v[186:189], v[20:23]
	v_mfma_f32_16x16x32_bf16 v[16:19], v[210:213], v[186:189], v[16:19]
	v_mfma_f32_16x16x32_bf16 v[4:7], v[202:205], v[194:197], v[4:7]
	v_mfma_f32_16x16x32_bf16 v[0:3], v[210:213], v[194:197], v[0:3]
	s_add_i32 s50, 0, 0x18000
	v_add_u32_e32 v149, s50, v145
	s_barrier
	ds_read_b128 v[150:153], v149
	ds_read_b128 v[154:157], v149 offset:1024
	ds_read_b128 v[158:161], v149 offset:2048
	ds_read_b128 v[162:165], v149 offset:3072
	s_add_u32 s16, s22, 0x40000
	s_addc_u32 s17, s23, 0
	s_mov_b32 m0, s30
	v_lshl_add_u64 v[198:199], s[16:17], 0, v[130:131]
	ds_read_b128 v[166:169], v147 offset:32768
	ds_read_b128 v[170:173], v147 offset:33792
	ds_read_b128 v[174:177], v147 offset:34816
	ds_read_b128 v[178:181], v147 offset:35840
	ds_read_b128 v[182:185], v147 offset:36864
	ds_read_b128 v[186:189], v147 offset:37888
	ds_read_b128 v[190:193], v147 offset:38912
	ds_read_b128 v[194:197], v147 offset:39936
	global_load_lds_dwordx4 v[198:199], off
	v_lshl_add_u64 v[198:199], s[16:17], 0, v[128:129]
	s_mov_b32 m0, s31
	s_nop 0
	global_load_lds_dwordx4 v[198:199], off
	s_waitcnt vmcnt(10)
	s_waitcnt lgkmcnt(8)
	s_barrier
	s_waitcnt lgkmcnt(0)
	s_waitcnt lgkmcnt(0)
	v_mfma_f32_16x16x32_bf16 v[124:127], v[150:153], v[166:169], v[124:127]
	v_mfma_f32_16x16x32_bf16 v[120:123], v[158:161], v[166:169], v[120:123]
	v_mfma_f32_16x16x32_bf16 v[108:111], v[150:153], v[174:177], v[108:111]
	v_mfma_f32_16x16x32_bf16 v[104:107], v[158:161], v[174:177], v[104:107]
	v_mfma_f32_16x16x32_bf16 v[92:95], v[150:153], v[182:185], v[92:95]
	v_mfma_f32_16x16x32_bf16 v[88:91], v[158:161], v[182:185], v[88:91]
	v_mfma_f32_16x16x32_bf16 v[76:79], v[150:153], v[190:193], v[76:79]
	v_mfma_f32_16x16x32_bf16 v[72:75], v[158:161], v[190:193], v[72:75]
	v_mfma_f32_16x16x32_bf16 v[124:127], v[154:157], v[170:173], v[124:127]
	v_mfma_f32_16x16x32_bf16 v[120:123], v[162:165], v[170:173], v[120:123]
	v_mfma_f32_16x16x32_bf16 v[108:111], v[154:157], v[178:181], v[108:111]
	v_mfma_f32_16x16x32_bf16 v[104:107], v[162:165], v[178:181], v[104:107]
	v_mfma_f32_16x16x32_bf16 v[92:95], v[154:157], v[186:189], v[92:95]
	v_mfma_f32_16x16x32_bf16 v[88:91], v[162:165], v[186:189], v[88:91]
	v_mfma_f32_16x16x32_bf16 v[76:79], v[154:157], v[194:197], v[76:79]
	v_mfma_f32_16x16x32_bf16 v[72:75], v[162:165], v[194:197], v[72:75]
	s_barrier
	s_add_i32 s22, 0, 0x1c000
	s_add_i32 s16, s50, s27
	v_add_u32_e32 v149, s22, v145
	v_lshl_add_u64 v[142:143], v[142:143], 0, s[6:7]
	s_mov_b32 m0, s16
	ds_read_b128 v[198:201], v149
	ds_read_b128 v[202:205], v149 offset:1024
	ds_read_b128 v[206:209], v149 offset:2048
	ds_read_b128 v[210:213], v149 offset:3072
	global_load_lds_dwordx4 v[142:143], off
	v_lshl_add_u64 v[142:143], v[214:215], 0, s[6:7]
	s_add_i32 m0, s16, 0x2000
	s_nop 0
	global_load_lds_dwordx4 v[142:143], off
	s_waitcnt vmcnt(10)
	s_barrier
	s_waitcnt lgkmcnt(0)
	s_waitcnt lgkmcnt(0)
	v_mfma_f32_16x16x32_bf16 v[116:119], v[198:201], v[166:169], v[116:119]
	v_mfma_f32_16x16x32_bf16 v[112:115], v[206:209], v[166:169], v[112:115]
	v_mfma_f32_16x16x32_bf16 v[100:103], v[198:201], v[174:177], v[100:103]
	v_mfma_f32_16x16x32_bf16 v[96:99], v[206:209], v[174:177], v[96:99]
	v_mfma_f32_16x16x32_bf16 v[84:87], v[198:201], v[182:185], v[84:87]
	v_mfma_f32_16x16x32_bf16 v[80:83], v[206:209], v[182:185], v[80:83]
	v_mfma_f32_16x16x32_bf16 v[68:71], v[198:201], v[190:193], v[68:71]
	v_mfma_f32_16x16x32_bf16 v[64:67], v[206:209], v[190:193], v[64:67]
	v_mfma_f32_16x16x32_bf16 v[116:119], v[202:205], v[170:173], v[116:119]
	v_mfma_f32_16x16x32_bf16 v[112:115], v[210:213], v[170:173], v[112:115]
	v_mfma_f32_16x16x32_bf16 v[100:103], v[202:205], v[178:181], v[100:103]
	v_mfma_f32_16x16x32_bf16 v[96:99], v[210:213], v[178:181], v[96:99]
	v_mfma_f32_16x16x32_bf16 v[84:87], v[202:205], v[186:189], v[84:87]
	v_mfma_f32_16x16x32_bf16 v[80:83], v[210:213], v[186:189], v[80:83]
	v_mfma_f32_16x16x32_bf16 v[68:71], v[202:205], v[194:197], v[68:71]
	v_mfma_f32_16x16x32_bf16 v[64:67], v[210:213], v[194:197], v[64:67]
	s_mov_b32 m0, s34
	v_lshl_add_u64 v[142:143], v[216:217], 0, s[6:7]
	s_barrier
	ds_read_b128 v[166:169], v147 offset:49152
	ds_read_b128 v[170:173], v147 offset:50176
	ds_read_b128 v[174:177], v147 offset:51200
	ds_read_b128 v[178:181], v147 offset:52224
	ds_read_b128 v[182:185], v147 offset:53248
	ds_read_b128 v[186:189], v147 offset:54272
	ds_read_b128 v[190:193], v147 offset:55296
	ds_read_b128 v[194:197], v147 offset:56320
	global_load_lds_dwordx4 v[142:143], off
	v_lshl_add_u64 v[142:143], v[218:219], 0, s[6:7]
	s_mov_b32 m0, s35
	s_nop 0
	global_load_lds_dwordx4 v[142:143], off
	s_barrier
; #define STG(P, GB) do { const char* _gb = (GB); \
;     _Pragma("unroll") for (int _i = 0; _i < 2; ++_i) { \
;       __builtin_amdgcn_global_load_lds((const unsigned*)(_gb + voff[_i]), \
;         (LAS unsigned*)((LAS char*)(P) + ldsw + _i * 8192), 16, 0, 0); } } while (0)
; #define MMA(ai, bj, At_, Bt_) do { __builtin_amdgcn_s_setprio(1); \
;     _Pragma("unroll") for (int m = 0; m < 4; ++m) _Pragma("unroll") for (int n = 0; n < 2; ++n) _Pragma("unroll") for (int k = 0; k < 2; ++k) \
;       acc[ai][bj][m][n] = __builtin_amdgcn_mfma_f32_16x16x32_bf16(Bt_[n][k], At_[m][k], acc[ai][bj][m][n], 0, 0, 0); \
;     __builtin_amdgcn_s_setprio(0); } while (0)
; #define WAIT_V(n) asm volatile("s_waitcnt vmcnt(" #n ")" ::: "memory")
; #define WAIT_L(n) asm volatile("s_waitcnt lgkmcnt(" #n ")" ::: "memory")
; #define BAR __builtin_amdgcn_s_barrier()
; #define SCHED __builtin_amdgcn_sched_barrier(0)
; __device__ __forceinline__ void gemm_phase(const bf16_t* __restrict__ A, const bf16_t* __restrict__ Bt, bf16_t* __restrict__ C, int M, int N, int K,
;                                            int ldc, const int EPI, char* smem, const int wid_u) {
;     ...
;       BAR; WAIT_L(0); MMA(1, 0, At, B0); BAR; SCHED;
;       STG(SB(1, 1), b3 + hstep);
;       WAIT_V(6); BAR; MMA(1, 1, At, B1); BAR;
;     ...
;             float o[8];
; #pragma unroll
;             for (int n = 0; n < 2; ++n) {
;               const f32x4 a = acc[ai][0][m][n], b = acc[ai][1][m][n];
; #pragma unroll
;               for (int j = 0; j < 4; ++j) o[n * 4 + j] = a[j] * __builtin_amdgcn_rcpf(1.f + __expf(-a[j])) * b[j];
;             }
;             *(uint4*)(C + row * ldc + (bcol >> 1) + wc * 32 + fq * 8) = pack8(o);
	s_waitcnt lgkmcnt(0)
	s_waitcnt lgkmcnt(0)
	v_mfma_f32_16x16x32_bf16 v[60:63], v[150:153], v[166:169], v[60:63]
	v_mfma_f32_16x16x32_bf16 v[56:59], v[158:161], v[166:169], v[56:59]
	v_mfma_f32_16x16x32_bf16 v[44:47], v[150:153], v[174:177], v[44:47]
	v_mfma_f32_16x16x32_bf16 v[40:43], v[158:161], v[174:177], v[40:43]
	v_mfma_f32_16x16x32_bf16 v[28:31], v[150:153], v[182:185], v[28:31]
	v_mfma_f32_16x16x32_bf16 v[24:27], v[158:161], v[182:185], v[24:27]
	v_mfma_f32_16x16x32_bf16 v[12:15], v[150:153], v[190:193], v[12:15]
	v_mfma_f32_16x16x32_bf16 v[8:11], v[158:161], v[190:193], v[8:11]
	v_mfma_f32_16x16x32_bf16 v[60:63], v[154:157], v[170:173], v[60:63]
	v_mfma_f32_16x16x32_bf16 v[56:59], v[162:165], v[170:173], v[56:59]
	v_mfma_f32_16x16x32_bf16 v[44:47], v[154:157], v[178:181], v[44:47]
	v_mfma_f32_16x16x32_bf16 v[40:43], v[162:165], v[178:181], v[40:43]
	v_mfma_f32_16x16x32_bf16 v[28:31], v[154:157], v[186:189], v[28:31]
	v_mfma_f32_16x16x32_bf16 v[24:27], v[162:165], v[186:189], v[24:27]
	v_mfma_f32_16x16x32_bf16 v[12:15], v[154:157], v[194:197], v[12:15]
	v_mfma_f32_16x16x32_bf16 v[8:11], v[162:165], v[194:197], v[8:11]
	s_barrier
	s_add_u32 s16, s20, 0x40080
	s_addc_u32 s17, s21, 0
	s_add_i32 s20, s22, s27
	v_lshl_add_u64 v[142:143], s[16:17], 0, v[130:131]
	s_mov_b32 m0, s20
	s_nop 0
	global_load_lds_dwordx4 v[142:143], off
	v_lshl_add_u64 v[142:143], s[16:17], 0, v[128:129]
	s_add_i32 m0, s20, 0x2000
	s_nop 0
	global_load_lds_dwordx4 v[142:143], off
	s_waitcnt vmcnt(10)
	s_barrier
	v_mfma_f32_16x16x32_bf16 v[52:55], v[198:201], v[166:169], v[52:55]
	v_mfma_f32_16x16x32_bf16 v[48:51], v[206:209], v[166:169], v[48:51]
	v_mfma_f32_16x16x32_bf16 v[36:39], v[198:201], v[174:177], v[36:39]
	v_mfma_f32_16x16x32_bf16 v[32:35], v[206:209], v[174:177], v[32:35]
	v_mfma_f32_16x16x32_bf16 v[20:23], v[198:201], v[182:185], v[20:23]
	v_mfma_f32_16x16x32_bf16 v[16:19], v[206:209], v[182:185], v[16:19]
	v_mfma_f32_16x16x32_bf16 v[4:7], v[198:201], v[190:193], v[4:7]
	v_mfma_f32_16x16x32_bf16 v[0:3], v[206:209], v[190:193], v[0:3]
	v_mfma_f32_16x16x32_bf16 v[52:55], v[202:205], v[170:173], v[52:55]
	v_mfma_f32_16x16x32_bf16 v[48:51], v[210:213], v[170:173], v[48:51]
	v_mfma_f32_16x16x32_bf16 v[36:39], v[202:205], v[178:181], v[36:39]
	v_mfma_f32_16x16x32_bf16 v[32:35], v[210:213], v[178:181], v[32:35]
	v_mfma_f32_16x16x32_bf16 v[20:23], v[202:205], v[186:189], v[20:23]
	v_mfma_f32_16x16x32_bf16 v[16:19], v[210:213], v[186:189], v[16:19]
	v_mfma_f32_16x16x32_bf16 v[4:7], v[202:205], v[194:197], v[4:7]
	v_mfma_f32_16x16x32_bf16 v[0:3], v[210:213], v[194:197], v[0:3]
	s_add_i32 s49, s49, 2
	s_add_u32 s47, s47, 0x100
	s_addc_u32 s48, s48, 0
	s_cmp_gt_u32 s49, 13
	s_mov_b64 s[16:17], s[18:19]
	s_barrier
	s_cbranch_scc0 .LBB0_145
	v_mul_f32_e32 v142, 0xbfb8aa3b, v124
	v_exp_f32_e32 v142, v142
	v_mul_f32_e32 v143, 0xbfb8aa3b, v125
	v_exp_f32_e32 v143, v143
	s_lshl_b32 s16, s40, 8
	v_add_f32_e32 v142, 1.0, v142
	v_rcp_f32_e32 v150, v142
	v_add_f32_e32 v142, 1.0, v143
	v_rcp_f32_e32 v151, v142
	s_mov_b32 s17, s9
	v_lshl_add_u32 v149, s41, 8, v144
	v_lshl_add_u64 v[142:143], v[132:133], 0, s[16:17]
	v_pk_mul_f32 v[124:125], v[124:125], v[150:151]
	v_mul_f32_e32 v150, 0xbfb8aa3b, v126
	v_mul_f32_e32 v151, 0xbfb8aa3b, v127
	v_exp_f32_e32 v150, v150
	v_exp_f32_e32 v151, v151
	v_pk_mul_f32 v[116:117], v[124:125], v[116:117]
	s_and_b64 vcc, exec, s[2:3]
	v_add_f32_e32 v124, 1.0, v150
	v_add_f32_e32 v125, 1.0, v151
	v_mul_f32_e32 v150, 0xbfb8aa3b, v120
	v_mul_f32_e32 v151, 0xbfb8aa3b, v121
	v_rcp_f32_e32 v124, v124
	v_rcp_f32_e32 v125, v125
	v_exp_f32_e32 v150, v150
	v_exp_f32_e32 v151, v151
	s_mov_b32 s41, s8
	v_pk_mul_f32 v[124:125], v[126:127], v[124:125]
	v_add_f32_e32 v126, 1.0, v150
	v_add_f32_e32 v127, 1.0, v151
	v_mul_f32_e32 v150, 0xbfb8aa3b, v122
	v_mul_f32_e32 v151, 0xbfb8aa3b, v123
	v_exp_f32_e32 v150, v150
	v_exp_f32_e32 v151, v151
	v_rcp_f32_e32 v126, v126
	v_rcp_f32_e32 v127, v127
	v_add_f32_e32 v150, 1.0, v150
	v_add_f32_e32 v151, 1.0, v151
	v_rcp_f32_e32 v150, v150
	v_rcp_f32_e32 v151, v151
	v_pk_mul_f32 v[120:121], v[120:121], v[126:127]
	v_pk_mul_f32 v[118:119], v[124:125], v[118:119]
	v_pk_mul_f32 v[120:121], v[120:121], v[112:113]
	v_pk_mul_f32 v[112:113], v[122:123], v[150:151]
	s_mov_b32 s40, s10
	v_pk_mul_f32 v[122:123], v[112:113], v[114:115]
	v_mul_f32_e32 v115, 0xbfb8aa3b, v108
	v_cvt_pk_bf16_f32 v112, v116, v117
	v_exp_f32_e32 v116, v115
	v_mul_f32_e32 v115, 0xbfb8aa3b, v109
	v_exp_f32_e32 v117, v115
	v_cvt_pk_bf16_f32 v113, v118, v119
	v_cvt_pk_bf16_f32 v114, v120, v121
	v_cvt_pk_bf16_f32 v115, v122, v123
	v_add_f32_e32 v116, 1.0, v116
	v_add_f32_e32 v117, 1.0, v117
	v_mad_i64_i32 v[118:119], s[16:17], v149, s38, v[142:143]
	v_rcp_f32_e32 v116, v116
	v_rcp_f32_e32 v117, v117
	global_store_dwordx4 v[118:119], v[112:115], off
	s_mov_b64 s[18:19], s[14:15]
	v_pk_mul_f32 v[108:109], v[108:109], v[116:117]
	v_mul_f32_e32 v112, 0xbfb8aa3b, v110
	v_mul_f32_e32 v113, 0xbfb8aa3b, v111
	v_exp_f32_e32 v112, v112
	v_exp_f32_e32 v113, v113
	v_pk_mul_f32 v[100:101], v[108:109], v[100:101]
	v_or_b32_e32 v114, 16, v149
	v_add_f32_e32 v108, 1.0, v112
	v_add_f32_e32 v109, 1.0, v113
	v_mul_f32_e32 v112, 0xbfb8aa3b, v104
	v_mul_f32_e32 v113, 0xbfb8aa3b, v105
	v_rcp_f32_e32 v108, v108
	v_rcp_f32_e32 v109, v109
	v_exp_f32_e32 v112, v112
	v_exp_f32_e32 v113, v113
	v_pk_mul_f32 v[108:109], v[110:111], v[108:109]
	v_add_f32_e32 v110, 1.0, v112
	v_add_f32_e32 v111, 1.0, v113
	v_mul_f32_e32 v112, 0xbfb8aa3b, v106
	v_mul_f32_e32 v113, 0xbfb8aa3b, v107
	v_exp_f32_e32 v112, v112
	v_exp_f32_e32 v113, v113
	v_rcp_f32_e32 v110, v110
	v_rcp_f32_e32 v111, v111
; __device__ __forceinline__ void gemm_phase(const bf16_t* __restrict__ A, const bf16_t* __restrict__ Bt, bf16_t* __restrict__ C, int M, int N, int K,
;                                            int ldc, const int EPI, char* smem, const int wid_u) {
;     ...
;             float o[8];
; #pragma unroll
;             for (int n = 0; n < 2; ++n) {
;               const f32x4 a = acc[ai][0][m][n], b = acc[ai][1][m][n];
; #pragma unroll
;               for (int j = 0; j < 4; ++j) o[n * 4 + j] = a[j] * __builtin_amdgcn_rcpf(1.f + __expf(-a[j])) * b[j];
;             }
;             *(uint4*)(C + row * ldc + (bcol >> 1) + wc * 32 + fq * 8) = pack8(o);
	v_add_f32_e32 v112, 1.0, v112
	v_add_f32_e32 v113, 1.0, v113
	v_rcp_f32_e32 v112, v112
	v_rcp_f32_e32 v113, v113
	v_pk_mul_f32 v[104:105], v[104:105], v[110:111]
	v_pk_mul_f32 v[102:103], v[108:109], v[102:103]
	v_pk_mul_f32 v[104:105], v[104:105], v[96:97]
	v_pk_mul_f32 v[96:97], v[106:107], v[112:113]
	s_nop 0
	v_pk_mul_f32 v[106:107], v[96:97], v[98:99]
	v_mul_f32_e32 v99, 0xbfb8aa3b, v92
	v_cvt_pk_bf16_f32 v96, v100, v101
	v_exp_f32_e32 v100, v99
	v_mul_f32_e32 v99, 0xbfb8aa3b, v93
	v_exp_f32_e32 v101, v99
	v_cvt_pk_bf16_f32 v97, v102, v103
	v_cvt_pk_bf16_f32 v98, v104, v105
	v_cvt_pk_bf16_f32 v99, v106, v107
	v_add_f32_e32 v100, 1.0, v100
	v_add_f32_e32 v101, 1.0, v101
	v_mad_i64_i32 v[102:103], s[16:17], v114, s38, v[142:143]
	v_rcp_f32_e32 v100, v100
	v_rcp_f32_e32 v101, v101
	global_store_dwordx4 v[102:103], v[96:99], off
	v_pk_mul_f32 v[92:93], v[92:93], v[100:101]
	s_nop 0
	v_mul_f32_e32 v96, 0xbfb8aa3b, v94
	v_mul_f32_e32 v97, 0xbfb8aa3b, v95
	v_exp_f32_e32 v96, v96
	v_exp_f32_e32 v97, v97
	v_pk_mul_f32 v[84:85], v[92:93], v[84:85]
	v_or_b32_e32 v98, 32, v149
	v_add_f32_e32 v92, 1.0, v96
	v_add_f32_e32 v93, 1.0, v97
	v_mul_f32_e32 v96, 0xbfb8aa3b, v88
	v_mul_f32_e32 v97, 0xbfb8aa3b, v89
	v_rcp_f32_e32 v92, v92
	v_rcp_f32_e32 v93, v93
	v_exp_f32_e32 v96, v96
	v_exp_f32_e32 v97, v97
	v_pk_mul_f32 v[92:93], v[94:95], v[92:93]
	v_add_f32_e32 v94, 1.0, v96
	v_add_f32_e32 v95, 1.0, v97
	v_mul_f32_e32 v96, 0xbfb8aa3b, v90
	v_mul_f32_e32 v97, 0xbfb8aa3b, v91
	v_exp_f32_e32 v96, v96
	v_exp_f32_e32 v97, v97
	v_rcp_f32_e32 v94, v94
	v_rcp_f32_e32 v95, v95
	v_add_f32_e32 v96, 1.0, v96
	v_add_f32_e32 v97, 1.0, v97
	v_rcp_f32_e32 v96, v96
	v_rcp_f32_e32 v97, v97
	v_pk_mul_f32 v[88:89], v[88:89], v[94:95]
	v_pk_mul_f32 v[86:87], v[92:93], v[86:87]
	v_pk_mul_f32 v[88:89], v[88:89], v[80:81]
	v_pk_mul_f32 v[80:81], v[90:91], v[96:97]
	s_nop 0
	v_pk_mul_f32 v[90:91], v[80:81], v[82:83]
	v_mul_f32_e32 v83, 0xbfb8aa3b, v76
	v_cvt_pk_bf16_f32 v80, v84, v85
	v_exp_f32_e32 v84, v83
	v_mul_f32_e32 v83, 0xbfb8aa3b, v77
	v_exp_f32_e32 v85, v83
	v_cvt_pk_bf16_f32 v81, v86, v87
	v_cvt_pk_bf16_f32 v82, v88, v89
	v_cvt_pk_bf16_f32 v83, v90, v91
	v_add_f32_e32 v84, 1.0, v84
	v_add_f32_e32 v85, 1.0, v85
	v_mad_i64_i32 v[86:87], s[16:17], v98, s38, v[142:143]
	v_rcp_f32_e32 v84, v84
	v_rcp_f32_e32 v85, v85
	global_store_dwordx4 v[86:87], v[80:83], off
	v_pk_mul_f32 v[76:77], v[76:77], v[84:85]
	s_nop 0
	v_mul_f32_e32 v80, 0xbfb8aa3b, v78
	v_mul_f32_e32 v81, 0xbfb8aa3b, v79
	v_exp_f32_e32 v80, v80
	v_exp_f32_e32 v81, v81
	v_pk_mul_f32 v[68:69], v[76:77], v[68:69]
	v_or_b32_e32 v82, 48, v149
	v_add_f32_e32 v76, 1.0, v80
	v_add_f32_e32 v77, 1.0, v81
	v_mul_f32_e32 v80, 0xbfb8aa3b, v72
	v_mul_f32_e32 v81, 0xbfb8aa3b, v73
	v_rcp_f32_e32 v76, v76
	v_rcp_f32_e32 v77, v77
	v_exp_f32_e32 v80, v80
	v_exp_f32_e32 v81, v81
	v_pk_mul_f32 v[76:77], v[78:79], v[76:77]
	v_add_f32_e32 v78, 1.0, v80
	v_add_f32_e32 v79, 1.0, v81
	v_mul_f32_e32 v80, 0xbfb8aa3b, v74
	v_mul_f32_e32 v81, 0xbfb8aa3b, v75
	v_exp_f32_e32 v80, v80
	v_exp_f32_e32 v81, v81
	v_rcp_f32_e32 v78, v78
	v_rcp_f32_e32 v79, v79
	v_add_f32_e32 v80, 1.0, v80
	v_add_f32_e32 v81, 1.0, v81
	v_rcp_f32_e32 v80, v80
	v_rcp_f32_e32 v81, v81
	v_pk_mul_f32 v[72:73], v[72:73], v[78:79]
	v_pk_mul_f32 v[70:71], v[76:77], v[70:71]
	v_pk_mul_f32 v[72:73], v[72:73], v[64:65]
	v_pk_mul_f32 v[64:65], v[74:75], v[80:81]
	s_nop 0
	v_pk_mul_f32 v[74:75], v[64:65], v[66:67]
	v_mul_f32_e32 v67, 0xbfb8aa3b, v60
	v_cvt_pk_bf16_f32 v64, v68, v69
	v_exp_f32_e32 v68, v67
	v_mul_f32_e32 v67, 0xbfb8aa3b, v61
	v_exp_f32_e32 v69, v67
	v_cvt_pk_bf16_f32 v65, v70, v71
	v_cvt_pk_bf16_f32 v66, v72, v73
	v_cvt_pk_bf16_f32 v67, v74, v75
	v_add_f32_e32 v68, 1.0, v68
	v_add_f32_e32 v69, 1.0, v69
	v_mad_i64_i32 v[70:71], s[16:17], v82, s38, v[142:143]
	v_rcp_f32_e32 v68, v68
	v_rcp_f32_e32 v69, v69
	global_store_dwordx4 v[70:71], v[64:67], off
	v_pk_mul_f32 v[60:61], v[60:61], v[68:69]
	s_nop 0
	v_mul_f32_e32 v64, 0xbfb8aa3b, v62
	v_mul_f32_e32 v65, 0xbfb8aa3b, v63
	v_exp_f32_e32 v64, v64
	v_exp_f32_e32 v65, v65
	v_pk_mul_f32 v[52:53], v[60:61], v[52:53]
	v_add_u32_e32 v66, 0x80, v149
	v_add_f32_e32 v60, 1.0, v64
	v_add_f32_e32 v61, 1.0, v65
	v_mul_f32_e32 v64, 0xbfb8aa3b, v56
	v_mul_f32_e32 v65, 0xbfb8aa3b, v57
	v_rcp_f32_e32 v60, v60
	v_rcp_f32_e32 v61, v61
	v_exp_f32_e32 v64, v64
	v_exp_f32_e32 v65, v65
	v_pk_mul_f32 v[60:61], v[62:63], v[60:61]
	v_add_f32_e32 v62, 1.0, v64
	v_add_f32_e32 v63, 1.0, v65
	v_mul_f32_e32 v64, 0xbfb8aa3b, v58
	v_mul_f32_e32 v65, 0xbfb8aa3b, v59
	v_exp_f32_e32 v64, v64
	v_exp_f32_e32 v65, v65
	v_rcp_f32_e32 v62, v62
	v_rcp_f32_e32 v63, v63
	v_add_f32_e32 v64, 1.0, v64
	v_add_f32_e32 v65, 1.0, v65
	v_rcp_f32_e32 v64, v64
	v_rcp_f32_e32 v65, v65
	v_pk_mul_f32 v[56:57], v[56:57], v[62:63]
	v_pk_mul_f32 v[54:55], v[60:61], v[54:55]
	v_pk_mul_f32 v[56:57], v[56:57], v[48:49]
	v_pk_mul_f32 v[48:49], v[58:59], v[64:65]
	s_nop 0
; #define WAIT_V(n) asm volatile("s_waitcnt vmcnt(" #n ")" ::: "memory")
; #define BAR __builtin_amdgcn_s_barrier()
; __device__ __forceinline__ void gemm_phase(const bf16_t* __restrict__ A, const bf16_t* __restrict__ Bt, bf16_t* __restrict__ C, int M, int N, int K,
;                                            int ldc, const int EPI, char* smem, const int wid_u) {
;     ...
;             float o[8];
; #pragma unroll
;             for (int n = 0; n < 2; ++n) {
;               const f32x4 a = acc[ai][0][m][n], b = acc[ai][1][m][n];
; #pragma unroll
;               for (int j = 0; j < 4; ++j) o[n * 4 + j] = a[j] * __builtin_amdgcn_rcpf(1.f + __expf(-a[j])) * b[j];
;             }
;             *(uint4*)(C + row * ldc + (bcol >> 1) + wc * 32 + fq * 8) = pack8(o);
;     ...
;     if (!has_next) break;
; #pragma unroll
;     for (int a = 0; a < 2; ++a)
; #pragma unroll
;       for (int b = 0; b < 2; ++b)
; #pragma unroll
;         for (int m = 0; m < 4; ++m)
; #pragma unroll
;           for (int n = 0; n < 2; ++n) acc[a][b][m][n] = (f32x4){0.f, 0.f, 0.f, 0.f};
;     pm = npm; pn = npn; cA = nA; cB = nB; ++ui;
;   }
;   WAIT_V(0);
;   if (wr == 0) BAR;
;   BAR;
	v_pk_mul_f32 v[58:59], v[48:49], v[50:51]
	v_mul_f32_e32 v51, 0xbfb8aa3b, v44
	v_cvt_pk_bf16_f32 v48, v52, v53
	v_exp_f32_e32 v52, v51
	v_mul_f32_e32 v51, 0xbfb8aa3b, v45
	v_exp_f32_e32 v53, v51
	v_cvt_pk_bf16_f32 v49, v54, v55
	v_cvt_pk_bf16_f32 v50, v56, v57
	v_cvt_pk_bf16_f32 v51, v58, v59
	v_add_f32_e32 v52, 1.0, v52
	v_add_f32_e32 v53, 1.0, v53
	v_mad_i64_i32 v[54:55], s[16:17], v66, s38, v[142:143]
	v_rcp_f32_e32 v52, v52
	v_rcp_f32_e32 v53, v53
	global_store_dwordx4 v[54:55], v[48:51], off
	v_pk_mul_f32 v[44:45], v[44:45], v[52:53]
	s_nop 0
	v_mul_f32_e32 v48, 0xbfb8aa3b, v46
	v_mul_f32_e32 v49, 0xbfb8aa3b, v47
	v_exp_f32_e32 v48, v48
	v_exp_f32_e32 v49, v49
	v_pk_mul_f32 v[36:37], v[44:45], v[36:37]
	v_add_u32_e32 v50, 0x90, v149
	v_add_f32_e32 v44, 1.0, v48
	v_add_f32_e32 v45, 1.0, v49
	v_mul_f32_e32 v48, 0xbfb8aa3b, v40
	v_mul_f32_e32 v49, 0xbfb8aa3b, v41
	v_rcp_f32_e32 v44, v44
	v_rcp_f32_e32 v45, v45
	v_exp_f32_e32 v48, v48
	v_exp_f32_e32 v49, v49
	v_pk_mul_f32 v[44:45], v[46:47], v[44:45]
	v_add_f32_e32 v46, 1.0, v48
	v_add_f32_e32 v47, 1.0, v49
	v_mul_f32_e32 v48, 0xbfb8aa3b, v42
	v_mul_f32_e32 v49, 0xbfb8aa3b, v43
	v_exp_f32_e32 v48, v48
	v_exp_f32_e32 v49, v49
	v_rcp_f32_e32 v46, v46
	v_rcp_f32_e32 v47, v47
	v_add_f32_e32 v48, 1.0, v48
	v_add_f32_e32 v49, 1.0, v49
	v_rcp_f32_e32 v48, v48
	v_rcp_f32_e32 v49, v49
	v_pk_mul_f32 v[40:41], v[40:41], v[46:47]
	v_pk_mul_f32 v[38:39], v[44:45], v[38:39]
	v_pk_mul_f32 v[40:41], v[40:41], v[32:33]
	v_pk_mul_f32 v[32:33], v[42:43], v[48:49]
	s_nop 0
	v_pk_mul_f32 v[42:43], v[32:33], v[34:35]
	v_mul_f32_e32 v35, 0xbfb8aa3b, v28
	v_cvt_pk_bf16_f32 v32, v36, v37
	v_exp_f32_e32 v36, v35
	v_mul_f32_e32 v35, 0xbfb8aa3b, v29
	v_exp_f32_e32 v37, v35
	v_cvt_pk_bf16_f32 v33, v38, v39
	v_cvt_pk_bf16_f32 v34, v40, v41
	v_cvt_pk_bf16_f32 v35, v42, v43
	v_add_f32_e32 v36, 1.0, v36
	v_add_f32_e32 v37, 1.0, v37
	v_mad_i64_i32 v[38:39], s[16:17], v50, s38, v[142:143]
	v_rcp_f32_e32 v36, v36
	v_rcp_f32_e32 v37, v37
	global_store_dwordx4 v[38:39], v[32:35], off
	v_pk_mul_f32 v[28:29], v[28:29], v[36:37]
	s_nop 0
	v_mul_f32_e32 v32, 0xbfb8aa3b, v30
	v_mul_f32_e32 v33, 0xbfb8aa3b, v31
	v_exp_f32_e32 v32, v32
	v_exp_f32_e32 v33, v33
	v_pk_mul_f32 v[20:21], v[28:29], v[20:21]
	v_add_u32_e32 v34, 0xa0, v149
	v_add_f32_e32 v28, 1.0, v32
	v_add_f32_e32 v29, 1.0, v33
	v_mul_f32_e32 v32, 0xbfb8aa3b, v24
	v_mul_f32_e32 v33, 0xbfb8aa3b, v25
	v_rcp_f32_e32 v28, v28
	v_rcp_f32_e32 v29, v29
	v_exp_f32_e32 v32, v32
	v_exp_f32_e32 v33, v33
	v_pk_mul_f32 v[28:29], v[30:31], v[28:29]
	v_add_f32_e32 v30, 1.0, v32
	v_add_f32_e32 v31, 1.0, v33
	v_mul_f32_e32 v32, 0xbfb8aa3b, v26
	v_mul_f32_e32 v33, 0xbfb8aa3b, v27
	v_exp_f32_e32 v32, v32
	v_exp_f32_e32 v33, v33
	v_rcp_f32_e32 v30, v30
	v_rcp_f32_e32 v31, v31
	v_add_f32_e32 v32, 1.0, v32
	v_add_f32_e32 v33, 1.0, v33
	v_rcp_f32_e32 v32, v32
	v_rcp_f32_e32 v33, v33
	v_pk_mul_f32 v[24:25], v[24:25], v[30:31]
	v_pk_mul_f32 v[22:23], v[28:29], v[22:23]
	v_pk_mul_f32 v[24:25], v[24:25], v[16:17]
	v_pk_mul_f32 v[16:17], v[26:27], v[32:33]
	s_nop 0
	v_pk_mul_f32 v[26:27], v[16:17], v[18:19]
	v_mul_f32_e32 v19, 0xbfb8aa3b, v12
	v_cvt_pk_bf16_f32 v16, v20, v21
	v_exp_f32_e32 v20, v19
	v_mul_f32_e32 v19, 0xbfb8aa3b, v13
	v_exp_f32_e32 v21, v19
	v_cvt_pk_bf16_f32 v17, v22, v23
	v_cvt_pk_bf16_f32 v18, v24, v25
	v_cvt_pk_bf16_f32 v19, v26, v27
	v_add_f32_e32 v20, 1.0, v20
	v_add_f32_e32 v21, 1.0, v21
	v_mad_i64_i32 v[22:23], s[16:17], v34, s38, v[142:143]
	v_rcp_f32_e32 v20, v20
	v_rcp_f32_e32 v21, v21
	global_store_dwordx4 v[22:23], v[16:19], off
	v_pk_mul_f32 v[12:13], v[12:13], v[20:21]
	s_nop 0
	v_mul_f32_e32 v16, 0xbfb8aa3b, v14
	v_mul_f32_e32 v17, 0xbfb8aa3b, v15
	v_exp_f32_e32 v16, v16
	v_exp_f32_e32 v17, v17
	v_pk_mul_f32 v[4:5], v[12:13], v[4:5]
	v_add_u32_e32 v18, 0xb0, v149
	v_add_f32_e32 v12, 1.0, v16
	v_add_f32_e32 v13, 1.0, v17
	v_mul_f32_e32 v16, 0xbfb8aa3b, v8
	v_mul_f32_e32 v17, 0xbfb8aa3b, v9
	v_rcp_f32_e32 v12, v12
	v_rcp_f32_e32 v13, v13
	v_exp_f32_e32 v16, v16
	v_exp_f32_e32 v17, v17
	v_pk_mul_f32 v[12:13], v[14:15], v[12:13]
	v_add_f32_e32 v14, 1.0, v16
	v_add_f32_e32 v15, 1.0, v17
	v_mul_f32_e32 v16, 0xbfb8aa3b, v10
	v_mul_f32_e32 v17, 0xbfb8aa3b, v11
	v_exp_f32_e32 v16, v16
	v_exp_f32_e32 v17, v17
	v_rcp_f32_e32 v14, v14
	v_rcp_f32_e32 v15, v15
	v_add_f32_e32 v16, 1.0, v16
	v_add_f32_e32 v17, 1.0, v17
	v_rcp_f32_e32 v16, v16
	v_rcp_f32_e32 v17, v17
	v_pk_mul_f32 v[8:9], v[8:9], v[14:15]
	v_pk_mul_f32 v[6:7], v[12:13], v[6:7]
	v_pk_mul_f32 v[8:9], v[8:9], v[0:1]
	v_pk_mul_f32 v[0:1], v[10:11], v[16:17]
	s_nop 0
	v_pk_mul_f32 v[10:11], v[0:1], v[2:3]
	v_cvt_pk_bf16_f32 v0, v4, v5
	v_mad_i64_i32 v[4:5], s[16:17], v18, s38, v[142:143]
	v_cvt_pk_bf16_f32 v1, v6, v7
	v_cvt_pk_bf16_f32 v2, v8, v9
	v_cvt_pk_bf16_f32 v3, v10, v11
	s_mov_b64 s[16:17], s[12:13]
	global_store_dwordx4 v[4:5], v[0:3], off
	s_cbranch_vccz .LBB0_142
	s_waitcnt vmcnt(0)
	s_cmpk_gt_u32 s24, 0xff
	s_cbranch_scc1 .LBB0_149
	s_barrier

; #define STG(P, GB) do { const char* _gb = (GB); \
;     _Pragma("unroll") for (int _i = 0; _i < 2; ++_i) { \
;       __builtin_amdgcn_global_load_lds((const unsigned*)(_gb + voff[_i]), \
;         (LAS unsigned*)((LAS char*)(P) + ldsw + _i * 8192), 16, 0, 0); } } while (0)
; #define LDA(dst, b, h) _Pragma("unroll") for (int m = 0; m < 4; ++m) _Pragma("unroll") for (int k = 0; k < 2; ++k) \
;     dst[m][k] = *(const LAS bf16x8*)((LAS char*)SA(b, h) + aoff + m * 2048 + k * 1024)
; #define LDB(dst, b, h) _Pragma("unroll") for (int n = 0; n < 2; ++n) _Pragma("unroll") for (int k = 0; k < 2; ++k) \
;     dst[n][k] = *(const LAS bf16x8*)((LAS char*)SB(b, h) + boff + n * 2048 + k * 1024)
; #define MMA(ai, bj, At_, Bt_) do { __builtin_amdgcn_s_setprio(1); \
;     _Pragma("unroll") for (int m = 0; m < 4; ++m) _Pragma("unroll") for (int n = 0; n < 2; ++n) _Pragma("unroll") for (int k = 0; k < 2; ++k) \
;       acc[ai][bj][m][n] = __builtin_amdgcn_mfma_f32_16x16x32_bf16(Bt_[n][k], At_[m][k], acc[ai][bj][m][n], 0, 0, 0); \
;     __builtin_amdgcn_s_setprio(0); } while (0)
; #define WAIT_V(n) asm volatile("s_waitcnt vmcnt(" #n ")" ::: "memory")
; #define WAIT_L(n) asm volatile("s_waitcnt lgkmcnt(" #n ")" ::: "memory")
; #define BAR __builtin_amdgcn_s_barrier()
; #define SCHED __builtin_amdgcn_sched_barrier(0)
; __device__ __forceinline__ void gemm_phase(const bf16_t* __restrict__ A, const bf16_t* __restrict__ Bt, bf16_t* __restrict__ C, int M, int N, int K,
;                                            int ldc, const int EPI, char* smem, const int wid_u) {
;     ...
;       LDB(B0, 0, 0); SCHED; LDA(At, 0, 0); STG(SA(1, 1), a1 + hstep);
;       WAIT_L(8); BAR; WAIT_L(0); MMA(0, 0, At, B0); BAR; SCHED;
;       LDB(B1, 0, 1); STG(SB(0, 0), b2);
;       BAR; WAIT_L(0); MMA(0, 1, At, B1); BAR;
;       LDA(At, 0, 1); STG(SA(0, 0), a2);
;       BAR; WAIT_L(0); MMA(1, 0, At, B0); BAR; SCHED;
;       STG(SB(0, 1), b2 + hstep);
;       WAIT_V(6); BAR; MMA(1, 1, At, B1); BAR;
;       LDB(B0, 1, 0); SCHED; LDA(At, 1, 0); STG(SA(0, 1), a2 + hstep);
;       WAIT_L(8); BAR; WAIT_L(0); MMA(0, 0, At, B0); BAR; SCHED;
.LBB0_213:
	ds_read_b128 v[148:151], v143
	ds_read_b128 v[152:155], v143 offset:1024
	ds_read_b128 v[156:159], v143 offset:2048
	ds_read_b128 v[160:163], v143 offset:3072
	s_add_u32 s16, s14, 0x100
	s_addc_u32 s17, s15, 0
	s_cmp_eq_u32 s53, 40
	s_cselect_b32 s21, s5, s17
	s_cselect_b32 s20, s4, s16
	s_cselect_b32 s19, s7, s52
	s_cselect_b32 s18, s6, s51
	s_mov_b32 m0, s36
	v_lshl_add_u64 v[196:197], s[14:15], 0, v[136:137]
	ds_read_b128 v[164:167], v144
	ds_read_b128 v[168:171], v144 offset:1024
	ds_read_b128 v[172:175], v144 offset:2048
	ds_read_b128 v[176:179], v144 offset:3072
	ds_read_b128 v[180:183], v144 offset:4096
	ds_read_b128 v[184:187], v144 offset:5120
	ds_read_b128 v[188:191], v144 offset:6144
	ds_read_b128 v[192:195], v144 offset:7168
	global_load_lds_dwordx4 v[196:197], off
	v_lshl_add_u64 v[196:197], s[14:15], 0, v[134:135]
	s_mov_b32 m0, s37
	s_nop 0
	global_load_lds_dwordx4 v[196:197], off
	s_waitcnt vmcnt(10)
	s_waitcnt lgkmcnt(8)
	s_barrier
	s_waitcnt lgkmcnt(0)
	s_waitcnt lgkmcnt(0)
	v_mfma_f32_16x16x32_bf16 v[124:127], v[148:151], v[164:167], v[124:127]
	v_mfma_f32_16x16x32_bf16 v[120:123], v[156:159], v[164:167], v[120:123]
	v_mfma_f32_16x16x32_bf16 v[116:119], v[148:151], v[172:175], v[116:119]
	v_mfma_f32_16x16x32_bf16 v[112:115], v[156:159], v[172:175], v[112:115]
	v_mfma_f32_16x16x32_bf16 v[100:103], v[148:151], v[180:183], v[100:103]
	v_mfma_f32_16x16x32_bf16 v[96:99], v[156:159], v[180:183], v[96:99]
	v_mfma_f32_16x16x32_bf16 v[84:87], v[148:151], v[188:191], v[84:87]
	v_mfma_f32_16x16x32_bf16 v[80:83], v[156:159], v[188:191], v[80:83]
	v_mfma_f32_16x16x32_bf16 v[124:127], v[152:155], v[168:171], v[124:127]
	v_mfma_f32_16x16x32_bf16 v[120:123], v[160:163], v[168:171], v[120:123]
	v_mfma_f32_16x16x32_bf16 v[116:119], v[152:155], v[176:179], v[116:119]
	v_mfma_f32_16x16x32_bf16 v[112:115], v[160:163], v[176:179], v[112:115]
	v_mfma_f32_16x16x32_bf16 v[100:103], v[152:155], v[184:187], v[100:103]
	v_mfma_f32_16x16x32_bf16 v[96:99], v[160:163], v[184:187], v[96:99]
	v_mfma_f32_16x16x32_bf16 v[84:87], v[152:155], v[192:195], v[84:87]
	v_mfma_f32_16x16x32_bf16 v[80:83], v[160:163], v[192:195], v[80:83]
	s_barrier
	s_mov_b32 m0, s38
	v_lshl_add_u64 v[212:213], s[18:19], 0, v[130:131]
	ds_read_b128 v[196:199], v145
	ds_read_b128 v[200:203], v145 offset:1024
	ds_read_b128 v[204:207], v145 offset:2048
	ds_read_b128 v[208:211], v145 offset:3072
	global_load_lds_dwordx4 v[212:213], off
	v_lshl_add_u64 v[214:215], s[18:19], 0, v[128:129]
	s_mov_b32 m0, s39
	s_nop 0
	global_load_lds_dwordx4 v[214:215], off
	s_waitcnt vmcnt(10)
	s_barrier
	s_waitcnt lgkmcnt(0)
	s_waitcnt lgkmcnt(0)
	v_mfma_f32_16x16x32_bf16 v[108:111], v[196:199], v[164:167], v[108:111]
	v_mfma_f32_16x16x32_bf16 v[104:107], v[204:207], v[164:167], v[104:107]
	v_mfma_f32_16x16x32_bf16 v[92:95], v[196:199], v[172:175], v[92:95]
	v_mfma_f32_16x16x32_bf16 v[88:91], v[204:207], v[172:175], v[88:91]
	v_mfma_f32_16x16x32_bf16 v[76:79], v[196:199], v[180:183], v[76:79]
	v_mfma_f32_16x16x32_bf16 v[72:75], v[204:207], v[180:183], v[72:75]
	v_mfma_f32_16x16x32_bf16 v[68:71], v[196:199], v[188:191], v[68:71]
	v_mfma_f32_16x16x32_bf16 v[64:67], v[204:207], v[188:191], v[64:67]
	v_mfma_f32_16x16x32_bf16 v[108:111], v[200:203], v[168:171], v[108:111]
	v_mfma_f32_16x16x32_bf16 v[104:107], v[208:211], v[168:171], v[104:107]
	v_mfma_f32_16x16x32_bf16 v[92:95], v[200:203], v[176:179], v[92:95]
	v_mfma_f32_16x16x32_bf16 v[88:91], v[208:211], v[176:179], v[88:91]
	v_mfma_f32_16x16x32_bf16 v[76:79], v[200:203], v[184:187], v[76:79]
	v_mfma_f32_16x16x32_bf16 v[72:75], v[208:211], v[184:187], v[72:75]
	v_mfma_f32_16x16x32_bf16 v[68:71], v[200:203], v[192:195], v[68:71]
	v_mfma_f32_16x16x32_bf16 v[64:67], v[208:211], v[192:195], v[64:67]
	s_mov_b32 m0, s28
	v_lshl_add_u64 v[216:217], s[20:21], 0, v[130:131]
	s_barrier
	ds_read_b128 v[164:167], v144 offset:16384
	ds_read_b128 v[168:171], v144 offset:17408
	ds_read_b128 v[172:175], v144 offset:18432
	ds_read_b128 v[176:179], v144 offset:19456
	ds_read_b128 v[180:183], v144 offset:20480
	ds_read_b128 v[184:187], v144 offset:21504
	ds_read_b128 v[188:191], v144 offset:22528
	ds_read_b128 v[192:195], v144 offset:23552
	global_load_lds_dwordx4 v[216:217], off
	v_lshl_add_u64 v[218:219], s[20:21], 0, v[128:129]
	s_mov_b32 m0, s29
	s_nop 0
	global_load_lds_dwordx4 v[218:219], off
	s_barrier
	s_waitcnt lgkmcnt(0)
	s_waitcnt lgkmcnt(0)
	v_mfma_f32_16x16x32_bf16 v[60:63], v[148:151], v[164:167], v[60:63]
	v_mfma_f32_16x16x32_bf16 v[56:59], v[156:159], v[164:167], v[56:59]
	v_mfma_f32_16x16x32_bf16 v[52:55], v[148:151], v[172:175], v[52:55]
	v_mfma_f32_16x16x32_bf16 v[48:51], v[156:159], v[172:175], v[48:51]
	v_mfma_f32_16x16x32_bf16 v[36:39], v[148:151], v[180:183], v[36:39]
	v_mfma_f32_16x16x32_bf16 v[32:35], v[156:159], v[180:183], v[32:35]
	v_mfma_f32_16x16x32_bf16 v[20:23], v[148:151], v[188:191], v[20:23]
	v_mfma_f32_16x16x32_bf16 v[16:19], v[156:159], v[188:191], v[16:19]
	v_mfma_f32_16x16x32_bf16 v[60:63], v[152:155], v[168:171], v[60:63]
	v_mfma_f32_16x16x32_bf16 v[56:59], v[160:163], v[168:171], v[56:59]
	v_mfma_f32_16x16x32_bf16 v[52:55], v[152:155], v[176:179], v[52:55]
	v_mfma_f32_16x16x32_bf16 v[48:51], v[160:163], v[176:179], v[48:51]
	v_mfma_f32_16x16x32_bf16 v[36:39], v[152:155], v[184:187], v[36:39]
	v_mfma_f32_16x16x32_bf16 v[32:35], v[160:163], v[184:187], v[32:35]
	v_mfma_f32_16x16x32_bf16 v[20:23], v[152:155], v[192:195], v[20:23]
	v_mfma_f32_16x16x32_bf16 v[16:19], v[160:163], v[192:195], v[16:19]
	s_barrier
; #define STG(P, GB) do { const char* _gb = (GB); \
;     _Pragma("unroll") for (int _i = 0; _i < 2; ++_i) { \
;       __builtin_amdgcn_global_load_lds((const unsigned*)(_gb + voff[_i]), \
;         (LAS unsigned*)((LAS char*)(P) + ldsw + _i * 8192), 16, 0, 0); } } while (0)
; #define LDA(dst, b, h) _Pragma("unroll") for (int m = 0; m < 4; ++m) _Pragma("unroll") for (int k = 0; k < 2; ++k) \
;     dst[m][k] = *(const LAS bf16x8*)((LAS char*)SA(b, h) + aoff + m * 2048 + k * 1024)
; #define LDB(dst, b, h) _Pragma("unroll") for (int n = 0; n < 2; ++n) _Pragma("unroll") for (int k = 0; k < 2; ++k) \
;     dst[n][k] = *(const LAS bf16x8*)((LAS char*)SB(b, h) + boff + n * 2048 + k * 1024)
; #define MMA(ai, bj, At_, Bt_) do { __builtin_amdgcn_s_setprio(1); \
;     _Pragma("unroll") for (int m = 0; m < 4; ++m) _Pragma("unroll") for (int n = 0; n < 2; ++n) _Pragma("unroll") for (int k = 0; k < 2; ++k) \
;       acc[ai][bj][m][n] = __builtin_amdgcn_mfma_f32_16x16x32_bf16(Bt_[n][k], At_[m][k], acc[ai][bj][m][n], 0, 0, 0); \
;     __builtin_amdgcn_s_setprio(0); } while (0)
; #define WAIT_V(n) asm volatile("s_waitcnt vmcnt(" #n ")" ::: "memory")
; #define WAIT_L(n) asm volatile("s_waitcnt lgkmcnt(" #n ")" ::: "memory")
; #define BAR __builtin_amdgcn_s_barrier()
; #define SCHED __builtin_amdgcn_sched_barrier(0)
; __device__ __forceinline__ void gemm_phase(const bf16_t* __restrict__ A, const bf16_t* __restrict__ Bt, bf16_t* __restrict__ C, int M, int N, int K,
;                                            int ldc, const int EPI, char* smem, const int wid_u) {
;     ...
;       WAIT_V(6); BAR; MMA(1, 1, At, B1); BAR;
;       LDB(B0, 1, 0); SCHED; LDA(At, 1, 0); STG(SA(0, 1), a2 + hstep);
;       WAIT_L(8); BAR; WAIT_L(0); MMA(0, 0, At, B0); BAR; SCHED;
;       LDB(B1, 1, 1); STG(SB(1, 0), b3);
;       BAR; WAIT_L(0); MMA(0, 1, At, B1); BAR;
;       LDA(At, 1, 1); STG(SA(1, 0), a3);
	s_add_u32 s14, s18, 0xb0000
	s_addc_u32 s15, s19, 0
	s_mov_b32 m0, s40
	v_lshl_add_u64 v[148:149], s[14:15], 0, v[130:131]
	global_load_lds_dwordx4 v[148:149], off
	v_lshl_add_u64 v[148:149], s[14:15], 0, v[128:129]
	s_mov_b32 m0, s41
	s_nop 0
	global_load_lds_dwordx4 v[148:149], off
	s_waitcnt vmcnt(10)
	s_barrier
	v_mfma_f32_16x16x32_bf16 v[44:47], v[196:199], v[164:167], v[44:47]
	v_mfma_f32_16x16x32_bf16 v[40:43], v[204:207], v[164:167], v[40:43]
	v_mfma_f32_16x16x32_bf16 v[28:31], v[196:199], v[172:175], v[28:31]
	v_mfma_f32_16x16x32_bf16 v[24:27], v[204:207], v[172:175], v[24:27]
	v_mfma_f32_16x16x32_bf16 v[12:15], v[196:199], v[180:183], v[12:15]
	v_mfma_f32_16x16x32_bf16 v[8:11], v[204:207], v[180:183], v[8:11]
	v_mfma_f32_16x16x32_bf16 v[4:7], v[196:199], v[188:191], v[4:7]
	v_mfma_f32_16x16x32_bf16 v[0:3], v[204:207], v[188:191], v[0:3]
	v_mfma_f32_16x16x32_bf16 v[44:47], v[200:203], v[168:171], v[44:47]
	v_mfma_f32_16x16x32_bf16 v[40:43], v[208:211], v[168:171], v[40:43]
	v_mfma_f32_16x16x32_bf16 v[28:31], v[200:203], v[176:179], v[28:31]
	v_mfma_f32_16x16x32_bf16 v[24:27], v[208:211], v[176:179], v[24:27]
	v_mfma_f32_16x16x32_bf16 v[12:15], v[200:203], v[184:187], v[12:15]
	v_mfma_f32_16x16x32_bf16 v[8:11], v[208:211], v[184:187], v[8:11]
	v_mfma_f32_16x16x32_bf16 v[4:7], v[200:203], v[192:195], v[4:7]
	v_mfma_f32_16x16x32_bf16 v[0:3], v[208:211], v[192:195], v[0:3]
	s_barrier
	ds_read_b128 v[148:151], v146
	ds_read_b128 v[152:155], v146 offset:1024
	ds_read_b128 v[156:159], v146 offset:2048
	ds_read_b128 v[160:163], v146 offset:3072
	s_add_u32 s14, s20, 0xb0000
	s_addc_u32 s15, s21, 0
	s_mov_b32 m0, s30
	v_lshl_add_u64 v[196:197], s[14:15], 0, v[130:131]
	ds_read_b128 v[164:167], v144 offset:32768
	ds_read_b128 v[168:171], v144 offset:33792
	ds_read_b128 v[172:175], v144 offset:34816
	ds_read_b128 v[176:179], v144 offset:35840
	ds_read_b128 v[180:183], v144 offset:36864
	ds_read_b128 v[184:187], v144 offset:37888
	ds_read_b128 v[188:191], v144 offset:38912
	ds_read_b128 v[192:195], v144 offset:39936
	global_load_lds_dwordx4 v[196:197], off
	v_lshl_add_u64 v[196:197], s[14:15], 0, v[128:129]
	s_mov_b32 m0, s31
	s_nop 0
	global_load_lds_dwordx4 v[196:197], off
	s_waitcnt vmcnt(10)
	s_waitcnt lgkmcnt(8)
	s_barrier
	s_waitcnt lgkmcnt(0)
	s_waitcnt lgkmcnt(0)
	v_mfma_f32_16x16x32_bf16 v[124:127], v[148:151], v[164:167], v[124:127]
	v_mfma_f32_16x16x32_bf16 v[120:123], v[156:159], v[164:167], v[120:123]
	v_mfma_f32_16x16x32_bf16 v[116:119], v[148:151], v[172:175], v[116:119]
	v_mfma_f32_16x16x32_bf16 v[112:115], v[156:159], v[172:175], v[112:115]
	v_mfma_f32_16x16x32_bf16 v[100:103], v[148:151], v[180:183], v[100:103]
	v_mfma_f32_16x16x32_bf16 v[96:99], v[156:159], v[180:183], v[96:99]
	v_mfma_f32_16x16x32_bf16 v[84:87], v[148:151], v[188:191], v[84:87]
	v_mfma_f32_16x16x32_bf16 v[80:83], v[156:159], v[188:191], v[80:83]
	v_mfma_f32_16x16x32_bf16 v[124:127], v[152:155], v[168:171], v[124:127]
	v_mfma_f32_16x16x32_bf16 v[120:123], v[160:163], v[168:171], v[120:123]
	v_mfma_f32_16x16x32_bf16 v[116:119], v[152:155], v[176:179], v[116:119]
	v_mfma_f32_16x16x32_bf16 v[112:115], v[160:163], v[176:179], v[112:115]
	v_mfma_f32_16x16x32_bf16 v[100:103], v[152:155], v[184:187], v[100:103]
	v_mfma_f32_16x16x32_bf16 v[96:99], v[160:163], v[184:187], v[96:99]
	v_mfma_f32_16x16x32_bf16 v[84:87], v[152:155], v[192:195], v[84:87]
	v_mfma_f32_16x16x32_bf16 v[80:83], v[160:163], v[192:195], v[80:83]
	s_barrier
	s_mov_b32 m0, s45
	v_lshl_add_u64 v[212:213], v[212:213], 0, s[12:13]
	ds_read_b128 v[196:199], v147
	ds_read_b128 v[200:203], v147 offset:1024
	ds_read_b128 v[204:207], v147 offset:2048
	ds_read_b128 v[208:211], v147 offset:3072
	global_load_lds_dwordx4 v[212:213], off
	v_lshl_add_u64 v[212:213], v[214:215], 0, s[12:13]
	s_mov_b32 m0, s46
	s_nop 0
	global_load_lds_dwordx4 v[212:213], off
	s_waitcnt vmcnt(10)
	s_barrier
	s_waitcnt lgkmcnt(0)
	s_waitcnt lgkmcnt(0)
	v_mfma_f32_16x16x32_bf16 v[108:111], v[196:199], v[164:167], v[108:111]
	v_mfma_f32_16x16x32_bf16 v[104:107], v[204:207], v[164:167], v[104:107]
	v_mfma_f32_16x16x32_bf16 v[92:95], v[196:199], v[172:175], v[92:95]
	v_mfma_f32_16x16x32_bf16 v[88:91], v[204:207], v[172:175], v[88:91]
	v_mfma_f32_16x16x32_bf16 v[76:79], v[196:199], v[180:183], v[76:79]
	v_mfma_f32_16x16x32_bf16 v[72:75], v[204:207], v[180:183], v[72:75]
	v_mfma_f32_16x16x32_bf16 v[68:71], v[196:199], v[188:191], v[68:71]
	v_mfma_f32_16x16x32_bf16 v[64:67], v[204:207], v[188:191], v[64:67]
	v_mfma_f32_16x16x32_bf16 v[108:111], v[200:203], v[168:171], v[108:111]
	v_mfma_f32_16x16x32_bf16 v[104:107], v[208:211], v[168:171], v[104:107]
	v_mfma_f32_16x16x32_bf16 v[92:95], v[200:203], v[176:179], v[92:95]
	v_mfma_f32_16x16x32_bf16 v[88:91], v[208:211], v[176:179], v[88:91]
	v_mfma_f32_16x16x32_bf16 v[76:79], v[200:203], v[184:187], v[76:79]
	v_mfma_f32_16x16x32_bf16 v[72:75], v[208:211], v[184:187], v[72:75]
	v_mfma_f32_16x16x32_bf16 v[68:71], v[200:203], v[192:195], v[68:71]
	v_mfma_f32_16x16x32_bf16 v[64:67], v[208:211], v[192:195], v[64:67]
	s_mov_b32 m0, s34
	v_lshl_add_u64 v[212:213], v[216:217], 0, s[12:13]
	s_barrier
	ds_read_b128 v[164:167], v144 offset:49152
	ds_read_b128 v[168:171], v144 offset:50176
	ds_read_b128 v[172:175], v144 offset:51200
	ds_read_b128 v[176:179], v144 offset:52224
	ds_read_b128 v[180:183], v144 offset:53248
	ds_read_b128 v[184:187], v144 offset:54272
	ds_read_b128 v[188:191], v144 offset:55296
	ds_read_b128 v[192:195], v144 offset:56320
	global_load_lds_dwordx4 v[212:213], off
	v_lshl_add_u64 v[212:213], v[218:219], 0, s[12:13]
	s_mov_b32 m0, s35
	s_nop 0
	global_load_lds_dwordx4 v[212:213], off
	s_barrier
; #define STG(P, GB) do { const char* _gb = (GB); \
;     _Pragma("unroll") for (int _i = 0; _i < 2; ++_i) { \
;       __builtin_amdgcn_global_load_lds((const unsigned*)(_gb + voff[_i]), \
;         (LAS unsigned*)((LAS char*)(P) + ldsw + _i * 8192), 16, 0, 0); } } while (0)
; #define MMA(ai, bj, At_, Bt_) do { __builtin_amdgcn_s_setprio(1); \
;     _Pragma("unroll") for (int m = 0; m < 4; ++m) _Pragma("unroll") for (int n = 0; n < 2; ++n) _Pragma("unroll") for (int k = 0; k < 2; ++k) \
;       acc[ai][bj][m][n] = __builtin_amdgcn_mfma_f32_16x16x32_bf16(Bt_[n][k], At_[m][k], acc[ai][bj][m][n], 0, 0, 0); \
;     __builtin_amdgcn_s_setprio(0); } while (0)
; #define WAIT_V(n) asm volatile("s_waitcnt vmcnt(" #n ")" ::: "memory")
; #define WAIT_L(n) asm volatile("s_waitcnt lgkmcnt(" #n ")" ::: "memory")
; #define BAR __builtin_amdgcn_s_barrier()
; #define SCHED __builtin_amdgcn_sched_barrier(0)
; __device__ __forceinline__ void gemm_phase(const bf16_t* __restrict__ A, const bf16_t* __restrict__ Bt, bf16_t* __restrict__ C, int M, int N, int K,
;                                            int ldc, const int EPI, char* smem, const int wid_u) {
;     ...
;       BAR; WAIT_L(0); MMA(1, 0, At, B0); BAR; SCHED;
;       STG(SB(1, 1), b3 + hstep);
;       WAIT_V(6); BAR; MMA(1, 1, At, B1); BAR;
	s_waitcnt lgkmcnt(0)
	s_waitcnt lgkmcnt(0)
	v_mfma_f32_16x16x32_bf16 v[60:63], v[148:151], v[164:167], v[60:63]
	v_mfma_f32_16x16x32_bf16 v[56:59], v[156:159], v[164:167], v[56:59]
	v_mfma_f32_16x16x32_bf16 v[52:55], v[148:151], v[172:175], v[52:55]
	v_mfma_f32_16x16x32_bf16 v[48:51], v[156:159], v[172:175], v[48:51]
	v_mfma_f32_16x16x32_bf16 v[36:39], v[148:151], v[180:183], v[36:39]
	v_mfma_f32_16x16x32_bf16 v[32:35], v[156:159], v[180:183], v[32:35]
	v_mfma_f32_16x16x32_bf16 v[20:23], v[148:151], v[188:191], v[20:23]
	v_mfma_f32_16x16x32_bf16 v[16:19], v[156:159], v[188:191], v[16:19]
	v_mfma_f32_16x16x32_bf16 v[60:63], v[152:155], v[168:171], v[60:63]
	v_mfma_f32_16x16x32_bf16 v[56:59], v[160:163], v[168:171], v[56:59]
	v_mfma_f32_16x16x32_bf16 v[52:55], v[152:155], v[176:179], v[52:55]
	v_mfma_f32_16x16x32_bf16 v[48:51], v[160:163], v[176:179], v[48:51]
	v_mfma_f32_16x16x32_bf16 v[36:39], v[152:155], v[184:187], v[36:39]
	v_mfma_f32_16x16x32_bf16 v[32:35], v[160:163], v[184:187], v[32:35]
	v_mfma_f32_16x16x32_bf16 v[20:23], v[152:155], v[192:195], v[20:23]
	v_mfma_f32_16x16x32_bf16 v[16:19], v[160:163], v[192:195], v[16:19]
	s_barrier
	s_add_u32 s14, s18, 0xb0080
	s_addc_u32 s15, s19, 0
	s_add_i32 s18, s44, s27
	v_lshl_add_u64 v[148:149], s[14:15], 0, v[130:131]
	s_mov_b32 m0, s18
	s_nop 0
	global_load_lds_dwordx4 v[148:149], off
	v_lshl_add_u64 v[148:149], s[14:15], 0, v[128:129]
	s_add_i32 m0, s18, 0x2000
	s_nop 0
	global_load_lds_dwordx4 v[148:149], off
	s_waitcnt vmcnt(10)
	s_barrier
	v_mfma_f32_16x16x32_bf16 v[44:47], v[196:199], v[164:167], v[44:47]
	v_mfma_f32_16x16x32_bf16 v[40:43], v[204:207], v[164:167], v[40:43]
	v_mfma_f32_16x16x32_bf16 v[28:31], v[196:199], v[172:175], v[28:31]
	v_mfma_f32_16x16x32_bf16 v[24:27], v[204:207], v[172:175], v[24:27]
	v_mfma_f32_16x16x32_bf16 v[12:15], v[196:199], v[180:183], v[12:15]
	v_mfma_f32_16x16x32_bf16 v[8:11], v[204:207], v[180:183], v[8:11]
	v_mfma_f32_16x16x32_bf16 v[4:7], v[196:199], v[188:191], v[4:7]
	v_mfma_f32_16x16x32_bf16 v[0:3], v[204:207], v[188:191], v[0:3]
	v_mfma_f32_16x16x32_bf16 v[44:47], v[200:203], v[168:171], v[44:47]
	v_mfma_f32_16x16x32_bf16 v[40:43], v[208:211], v[168:171], v[40:43]
	v_mfma_f32_16x16x32_bf16 v[28:31], v[200:203], v[176:179], v[28:31]
	v_mfma_f32_16x16x32_bf16 v[24:27], v[208:211], v[176:179], v[24:27]
	v_mfma_f32_16x16x32_bf16 v[12:15], v[200:203], v[184:187], v[12:15]
	v_mfma_f32_16x16x32_bf16 v[8:11], v[208:211], v[184:187], v[8:11]
	v_mfma_f32_16x16x32_bf16 v[4:7], v[200:203], v[192:195], v[4:7]
	v_mfma_f32_16x16x32_bf16 v[0:3], v[208:211], v[192:195], v[0:3]
	s_add_i32 s53, s53, 2
	s_add_u32 s51, s51, 0x100
	s_addc_u32 s52, s52, 0
	s_cmp_gt_u32 s53, 41
	s_mov_b64 s[14:15], s[16:17]
	s_barrier
	s_cbranch_scc0 .LBB0_213
; #define WAIT_V(n) asm volatile("s_waitcnt vmcnt(" #n ")" ::: "memory")
; #define BAR __builtin_amdgcn_s_barrier()
; __device__ __forceinline__ void gemm_phase(const bf16_t* __restrict__ A, const bf16_t* __restrict__ Bt, bf16_t* __restrict__ C, int M, int N, int K,
;                                            int ldc, const int EPI, char* smem, const int wid_u) {
;     ...
;           if (EPI == 0) {
; #pragma unroll
;             for (int bj = 0; bj < 2; ++bj) {
;               const f32x4 v0 = acc[ai][bj][m][0], v1 = acc[ai][bj][m][1];
;               uint4 u; u.x = cvt_pk_bf16(v0[0], v0[1]); u.y = cvt_pk_bf16(v0[2], v0[3]); u.z = cvt_pk_bf16(v1[0], v1[1]); u.w = cvt_pk_bf16(v1[2], v1[3]);
;               *(uint4*)(C + row * ldc + bcol + bj * HALF + wc * 32 + fq * 8) = u;
;             }
;     ...
;     if (!has_next) break;
; #pragma unroll
;     for (int a = 0; a < 2; ++a)
; #pragma unroll
;       for (int b = 0; b < 2; ++b)
; #pragma unroll
;         for (int m = 0; m < 4; ++m)
; #pragma unroll
;           for (int n = 0; n < 2; ++n) acc[a][b][m][n] = (f32x4){0.f, 0.f, 0.f, 0.f};
;     pm = npm; pn = npn; cA = nA; cB = nB; ++ui;
;   }
;   WAIT_V(0);
;   if (wr == 0) BAR;
;   BAR;
	v_lshl_add_u32 v148, s10, 8, v142
	v_cvt_pk_bf16_f32 v68, v68, v69
	v_cvt_pk_bf16_f32 v69, v70, v71
	v_cvt_pk_bf16_f32 v70, v64, v65
	v_add_u32_e32 v64, 0x80, v148
	s_lshl_b32 s10, s50, 9
	v_ashrrev_i32_e32 v149, 31, v148
	v_cvt_pk_bf16_f32 v108, v108, v109
	v_cvt_pk_bf16_f32 v109, v110, v111
	v_cvt_pk_bf16_f32 v110, v104, v105
	v_or_b32_e32 v104, 16, v148
	v_ashrrev_i32_e32 v65, 31, v64
	v_cvt_pk_bf16_f32 v44, v44, v45
	v_cvt_pk_bf16_f32 v45, v46, v47
	v_cvt_pk_bf16_f32 v46, v40, v41
	v_add_u32_e32 v40, 0x90, v148
	v_lshl_add_u64 v[150:151], v[132:133], 0, s[10:11]
	v_lshlrev_b64 v[152:153], 11, v[148:149]
	v_ashrrev_i32_e32 v105, 31, v104
	v_cvt_pk_bf16_f32 v92, v92, v93
	v_cvt_pk_bf16_f32 v93, v94, v95
	v_cvt_pk_bf16_f32 v94, v88, v89
	v_or_b32_e32 v88, 32, v148
	v_lshlrev_b64 v[64:65], 11, v[64:65]
	v_ashrrev_i32_e32 v41, 31, v40
	v_cvt_pk_bf16_f32 v28, v28, v29
	v_cvt_pk_bf16_f32 v29, v30, v31
	v_cvt_pk_bf16_f32 v30, v24, v25
	v_add_u32_e32 v24, 0xa0, v148
	v_lshl_add_u64 v[152:153], v[150:151], 0, v[152:153]
	v_cvt_pk_bf16_f32 v111, v106, v107
	v_lshlrev_b64 v[104:105], 11, v[104:105]
	v_ashrrev_i32_e32 v89, 31, v88
	v_cvt_pk_bf16_f32 v76, v76, v77
	v_cvt_pk_bf16_f32 v77, v78, v79
	v_cvt_pk_bf16_f32 v78, v72, v73
	v_or_b32_e32 v72, 48, v148
	v_lshl_add_u64 v[64:65], v[150:151], 0, v[64:65]
	v_cvt_pk_bf16_f32 v47, v42, v43
	v_lshlrev_b64 v[40:41], 11, v[40:41]
	v_ashrrev_i32_e32 v25, 31, v24
	v_cvt_pk_bf16_f32 v12, v12, v13
	v_cvt_pk_bf16_f32 v13, v14, v15
	v_cvt_pk_bf16_f32 v14, v8, v9
	v_add_u32_e32 v8, 0xb0, v148
	global_store_dwordx4 v[152:153], v[108:111], off offset:256
	v_cvt_pk_bf16_f32 v95, v90, v91
	v_lshlrev_b64 v[88:89], 11, v[88:89]
	v_lshl_add_u64 v[108:109], v[150:151], 0, v[104:105]
	v_ashrrev_i32_e32 v73, 31, v72
	global_store_dwordx4 v[64:65], v[44:47], off offset:256
	v_cvt_pk_bf16_f32 v31, v26, v27
	v_lshlrev_b64 v[24:25], 11, v[24:25]
	v_lshl_add_u64 v[44:45], v[150:151], 0, v[40:41]
	v_ashrrev_i32_e32 v9, 31, v8
	global_store_dwordx4 v[108:109], v[92:95], off offset:256
	v_cvt_pk_bf16_f32 v79, v74, v75
	v_lshlrev_b64 v[72:73], 11, v[72:73]
	v_lshl_add_u64 v[92:93], v[150:151], 0, v[88:89]
	global_store_dwordx4 v[44:45], v[28:31], off offset:256
	v_cvt_pk_bf16_f32 v15, v10, v11
	v_lshlrev_b64 v[8:9], 11, v[8:9]
	v_lshl_add_u64 v[28:29], v[150:151], 0, v[24:25]
	v_cvt_pk_bf16_f32 v124, v124, v125
	v_cvt_pk_bf16_f32 v125, v126, v127
	v_cvt_pk_bf16_f32 v126, v120, v121
	v_cvt_pk_bf16_f32 v127, v122, v123
	v_cvt_pk_bf16_f32 v104, v116, v117
	v_cvt_pk_bf16_f32 v105, v118, v119
	v_cvt_pk_bf16_f32 v106, v112, v113
	v_cvt_pk_bf16_f32 v107, v114, v115
	v_cvt_pk_bf16_f32 v88, v100, v101
	v_cvt_pk_bf16_f32 v89, v102, v103
	v_cvt_pk_bf16_f32 v90, v96, v97
	v_cvt_pk_bf16_f32 v91, v98, v99
	global_store_dwordx4 v[92:93], v[76:79], off offset:256
	v_cvt_pk_bf16_f32 v74, v80, v81
	v_cvt_pk_bf16_f32 v75, v82, v83
	v_lshl_add_u64 v[76:77], v[150:151], 0, v[72:73]
	v_cvt_pk_bf16_f32 v72, v84, v85
	v_cvt_pk_bf16_f32 v73, v86, v87
	v_cvt_pk_bf16_f32 v71, v66, v67
	v_cvt_pk_bf16_f32 v60, v60, v61
	v_cvt_pk_bf16_f32 v61, v62, v63
	v_cvt_pk_bf16_f32 v62, v56, v57
	v_cvt_pk_bf16_f32 v63, v58, v59
	v_cvt_pk_bf16_f32 v40, v52, v53
	v_cvt_pk_bf16_f32 v41, v54, v55
	v_cvt_pk_bf16_f32 v42, v48, v49
	v_cvt_pk_bf16_f32 v43, v50, v51
	v_cvt_pk_bf16_f32 v24, v36, v37
	v_cvt_pk_bf16_f32 v25, v38, v39
	v_cvt_pk_bf16_f32 v26, v32, v33
	v_cvt_pk_bf16_f32 v27, v34, v35
	global_store_dwordx4 v[28:29], v[12:15], off offset:256
	v_cvt_pk_bf16_f32 v10, v16, v17
	v_cvt_pk_bf16_f32 v11, v18, v19
	v_lshl_add_u64 v[12:13], v[150:151], 0, v[8:9]
	v_cvt_pk_bf16_f32 v8, v20, v21
	v_cvt_pk_bf16_f32 v9, v22, v23
	v_cvt_pk_bf16_f32 v4, v4, v5
	v_cvt_pk_bf16_f32 v5, v6, v7
	v_cvt_pk_bf16_f32 v6, v0, v1
	v_cvt_pk_bf16_f32 v7, v2, v3
	s_and_b64 vcc, exec, s[2:3]
	s_mov_b32 s10, s48
	s_mov_b32 s50, s49
	s_mov_b64 s[16:17], s[6:7]
	s_mov_b64 s[14:15], s[4:5]
	global_store_dwordx4 v[152:153], v[124:127], off
	global_store_dwordx4 v[108:109], v[104:107], off
	global_store_dwordx4 v[92:93], v[88:91], off
	global_store_dwordx4 v[76:77], v[72:75], off
	global_store_dwordx4 v[76:77], v[68:71], off offset:256
	global_store_dwordx4 v[64:65], v[60:63], off
	global_store_dwordx4 v[44:45], v[40:43], off
	global_store_dwordx4 v[28:29], v[24:27], off
	global_store_dwordx4 v[12:13], v[8:11], off
	global_store_dwordx4 v[12:13], v[4:7], off offset:256
	s_cbranch_vccz .LBB0_206
	s_waitcnt vmcnt(0)
	s_cmpk_gt_u32 s22, 0xff
	s_cbranch_scc1 .LBB0_217
	s_barrier

; #define STG(P, GB) do { const char* _gb = (GB); \
;     _Pragma("unroll") for (int _i = 0; _i < 2; ++_i) { \
;       __builtin_amdgcn_global_load_lds((const unsigned*)(_gb + voff[_i]), \
;         (LAS unsigned*)((LAS char*)(P) + ldsw + _i * 8192), 16, 0, 0); } } while (0)
; #define LDA(dst, b, h) _Pragma("unroll") for (int m = 0; m < 4; ++m) _Pragma("unroll") for (int k = 0; k < 2; ++k) \
;     dst[m][k] = *(const LAS bf16x8*)((LAS char*)SA(b, h) + aoff + m * 2048 + k * 1024)
; #define LDB(dst, b, h) _Pragma("unroll") for (int n = 0; n < 2; ++n) _Pragma("unroll") for (int k = 0; k < 2; ++k) \
;     dst[n][k] = *(const LAS bf16x8*)((LAS char*)SB(b, h) + boff + n * 2048 + k * 1024)
; #define MMA(ai, bj, At_, Bt_) do { __builtin_amdgcn_s_setprio(1); \
;     _Pragma("unroll") for (int m = 0; m < 4; ++m) _Pragma("unroll") for (int n = 0; n < 2; ++n) _Pragma("unroll") for (int k = 0; k < 2; ++k) \
;       acc[ai][bj][m][n] = __builtin_amdgcn_mfma_f32_16x16x32_bf16(Bt_[n][k], At_[m][k], acc[ai][bj][m][n], 0, 0, 0); \
;     __builtin_amdgcn_s_setprio(0); } while (0)
; #define WAIT_V(n) asm volatile("s_waitcnt vmcnt(" #n ")" ::: "memory")
; #define WAIT_L(n) asm volatile("s_waitcnt lgkmcnt(" #n ")" ::: "memory")
; #define BAR __builtin_amdgcn_s_barrier()
; #define SCHED __builtin_amdgcn_sched_barrier(0)
; __device__ __forceinline__ void gemm_phase(const bf16_t* __restrict__ A, const bf16_t* __restrict__ Bt, bf16_t* __restrict__ C, int M, int N, int K,
;                                            int ldc, const int EPI, char* smem, const int wid_u) {
;     ...
;       LDB(B0, 0, 0); SCHED; LDA(At, 0, 0); STG(SA(1, 1), a1 + hstep);
;       WAIT_L(8); BAR; WAIT_L(0); MMA(0, 0, At, B0); BAR; SCHED;
;       LDB(B1, 0, 1); STG(SB(0, 0), b2);
;       BAR; WAIT_L(0); MMA(0, 1, At, B1); BAR;
;       LDA(At, 0, 1); STG(SA(0, 0), a2);
;       BAR; WAIT_L(0); MMA(1, 0, At, B0); BAR; SCHED;
;       STG(SB(0, 1), b2 + hstep);
;       WAIT_V(6); BAR; MMA(1, 1, At, B1); BAR;
;       LDB(B0, 1, 0); SCHED; LDA(At, 1, 0); STG(SA(0, 1), a2 + hstep);
;       WAIT_L(8); BAR; WAIT_L(0); MMA(0, 0, At, B0); BAR; SCHED;
.LBB0_334:
	ds_read_b128 v[148:151], v144
	ds_read_b128 v[152:155], v144 offset:1024
	ds_read_b128 v[156:159], v144 offset:2048
	ds_read_b128 v[160:163], v144 offset:3072
	s_add_u32 s18, s16, 0x100
	s_addc_u32 s19, s17, 0
	s_cmp_eq_u32 s51, 12
	s_cselect_b32 s23, s46, s19
	s_cselect_b32 s22, s47, s18
	s_cselect_b32 s21, s11, s50
	s_cselect_b32 s20, s48, s49
	v_lshl_add_u64 v[196:197], s[16:17], 0, v[136:137]
	s_add_i32 m0, s30, 0xc000
	ds_read_b128 v[164:167], v145
	ds_read_b128 v[168:171], v145 offset:1024
	ds_read_b128 v[172:175], v145 offset:2048
	ds_read_b128 v[176:179], v145 offset:3072
	ds_read_b128 v[180:183], v145 offset:4096
	ds_read_b128 v[184:187], v145 offset:5120
	ds_read_b128 v[188:191], v145 offset:6144
	ds_read_b128 v[192:195], v145 offset:7168
	global_load_lds_dwordx4 v[196:197], off
	v_lshl_add_u64 v[196:197], s[16:17], 0, v[134:135]
	s_add_i32 m0, s30, 0xe000
	s_nop 0
	global_load_lds_dwordx4 v[196:197], off
	s_waitcnt vmcnt(10)
	s_waitcnt lgkmcnt(8)
	s_barrier
	s_waitcnt lgkmcnt(0)
	s_waitcnt lgkmcnt(0)
	v_mfma_f32_16x16x32_bf16 v[124:127], v[148:151], v[164:167], v[124:127]
	v_mfma_f32_16x16x32_bf16 v[120:123], v[156:159], v[164:167], v[120:123]
	v_mfma_f32_16x16x32_bf16 v[116:119], v[148:151], v[172:175], v[116:119]
	v_mfma_f32_16x16x32_bf16 v[112:115], v[156:159], v[172:175], v[112:115]
	v_mfma_f32_16x16x32_bf16 v[100:103], v[148:151], v[180:183], v[100:103]
	v_mfma_f32_16x16x32_bf16 v[96:99], v[156:159], v[180:183], v[96:99]
	v_mfma_f32_16x16x32_bf16 v[84:87], v[148:151], v[188:191], v[84:87]
	v_mfma_f32_16x16x32_bf16 v[80:83], v[156:159], v[188:191], v[80:83]
	v_mfma_f32_16x16x32_bf16 v[124:127], v[152:155], v[168:171], v[124:127]
	v_mfma_f32_16x16x32_bf16 v[120:123], v[160:163], v[168:171], v[120:123]
	v_mfma_f32_16x16x32_bf16 v[116:119], v[152:155], v[176:179], v[116:119]
	v_mfma_f32_16x16x32_bf16 v[112:115], v[160:163], v[176:179], v[112:115]
	v_mfma_f32_16x16x32_bf16 v[100:103], v[152:155], v[184:187], v[100:103]
	v_mfma_f32_16x16x32_bf16 v[96:99], v[160:163], v[184:187], v[96:99]
	v_mfma_f32_16x16x32_bf16 v[84:87], v[152:155], v[192:195], v[84:87]
	v_mfma_f32_16x16x32_bf16 v[80:83], v[160:163], v[192:195], v[80:83]
	s_barrier
	s_add_i32 s16, s38, s29
	v_lshl_add_u64 v[212:213], s[20:21], 0, v[130:131]
	s_mov_b32 m0, s16
	ds_read_b128 v[196:199], v146
	ds_read_b128 v[200:203], v146 offset:1024
	ds_read_b128 v[204:207], v146 offset:2048
	ds_read_b128 v[208:211], v146 offset:3072
	global_load_lds_dwordx4 v[212:213], off
	v_lshl_add_u64 v[214:215], s[20:21], 0, v[128:129]
	s_add_i32 m0, s16, 0x2000
	s_nop 0
	global_load_lds_dwordx4 v[214:215], off
	s_waitcnt vmcnt(10)
	s_barrier
	s_waitcnt lgkmcnt(0)
	s_waitcnt lgkmcnt(0)
	v_mfma_f32_16x16x32_bf16 v[108:111], v[196:199], v[164:167], v[108:111]
	v_mfma_f32_16x16x32_bf16 v[104:107], v[204:207], v[164:167], v[104:107]
	v_mfma_f32_16x16x32_bf16 v[92:95], v[196:199], v[172:175], v[92:95]
	v_mfma_f32_16x16x32_bf16 v[88:91], v[204:207], v[172:175], v[88:91]
	v_mfma_f32_16x16x32_bf16 v[76:79], v[196:199], v[180:183], v[76:79]
	v_mfma_f32_16x16x32_bf16 v[72:75], v[204:207], v[180:183], v[72:75]
	v_mfma_f32_16x16x32_bf16 v[68:71], v[196:199], v[188:191], v[68:71]
	v_mfma_f32_16x16x32_bf16 v[64:67], v[204:207], v[188:191], v[64:67]
	v_mfma_f32_16x16x32_bf16 v[108:111], v[200:203], v[168:171], v[108:111]
	v_mfma_f32_16x16x32_bf16 v[104:107], v[208:211], v[168:171], v[104:107]
	v_mfma_f32_16x16x32_bf16 v[92:95], v[200:203], v[176:179], v[92:95]
	v_mfma_f32_16x16x32_bf16 v[88:91], v[208:211], v[176:179], v[88:91]
	v_mfma_f32_16x16x32_bf16 v[76:79], v[200:203], v[184:187], v[76:79]
	v_mfma_f32_16x16x32_bf16 v[72:75], v[208:211], v[184:187], v[72:75]
	v_mfma_f32_16x16x32_bf16 v[68:71], v[200:203], v[192:195], v[68:71]
	v_mfma_f32_16x16x32_bf16 v[64:67], v[208:211], v[192:195], v[64:67]
	s_mov_b32 m0, s30
	v_lshl_add_u64 v[216:217], s[22:23], 0, v[130:131]
	s_barrier
	ds_read_b128 v[164:167], v145 offset:16384
	ds_read_b128 v[168:171], v145 offset:17408
	ds_read_b128 v[172:175], v145 offset:18432
	ds_read_b128 v[176:179], v145 offset:19456
	ds_read_b128 v[180:183], v145 offset:20480
	ds_read_b128 v[184:187], v145 offset:21504
	ds_read_b128 v[188:191], v145 offset:22528
	ds_read_b128 v[192:195], v145 offset:23552
	global_load_lds_dwordx4 v[216:217], off
	v_lshl_add_u64 v[218:219], s[22:23], 0, v[128:129]
	s_mov_b32 m0, s31
	s_nop 0
	global_load_lds_dwordx4 v[218:219], off
	s_barrier
	s_waitcnt lgkmcnt(0)
	s_waitcnt lgkmcnt(0)
	v_mfma_f32_16x16x32_bf16 v[60:63], v[148:151], v[164:167], v[60:63]
	v_mfma_f32_16x16x32_bf16 v[56:59], v[156:159], v[164:167], v[56:59]
	v_mfma_f32_16x16x32_bf16 v[52:55], v[148:151], v[172:175], v[52:55]
	v_mfma_f32_16x16x32_bf16 v[48:51], v[156:159], v[172:175], v[48:51]
	v_mfma_f32_16x16x32_bf16 v[36:39], v[148:151], v[180:183], v[36:39]
	v_mfma_f32_16x16x32_bf16 v[32:35], v[156:159], v[180:183], v[32:35]
	v_mfma_f32_16x16x32_bf16 v[20:23], v[148:151], v[188:191], v[20:23]
	v_mfma_f32_16x16x32_bf16 v[16:19], v[156:159], v[188:191], v[16:19]
	v_mfma_f32_16x16x32_bf16 v[60:63], v[152:155], v[168:171], v[60:63]
	v_mfma_f32_16x16x32_bf16 v[56:59], v[160:163], v[168:171], v[56:59]
	v_mfma_f32_16x16x32_bf16 v[52:55], v[152:155], v[176:179], v[52:55]
	v_mfma_f32_16x16x32_bf16 v[48:51], v[160:163], v[176:179], v[48:51]
	v_mfma_f32_16x16x32_bf16 v[36:39], v[152:155], v[184:187], v[36:39]
	v_mfma_f32_16x16x32_bf16 v[32:35], v[160:163], v[184:187], v[32:35]
	v_mfma_f32_16x16x32_bf16 v[20:23], v[152:155], v[192:195], v[20:23]
	v_mfma_f32_16x16x32_bf16 v[16:19], v[160:163], v[192:195], v[16:19]
	s_barrier
; #define STG(P, GB) do { const char* _gb = (GB); \
;     _Pragma("unroll") for (int _i = 0; _i < 2; ++_i) { \
;       __builtin_amdgcn_global_load_lds((const unsigned*)(_gb + voff[_i]), \
;         (LAS unsigned*)((LAS char*)(P) + ldsw + _i * 8192), 16, 0, 0); } } while (0)
; #define LDA(dst, b, h) _Pragma("unroll") for (int m = 0; m < 4; ++m) _Pragma("unroll") for (int k = 0; k < 2; ++k) \
;     dst[m][k] = *(const LAS bf16x8*)((LAS char*)SA(b, h) + aoff + m * 2048 + k * 1024)
; #define LDB(dst, b, h) _Pragma("unroll") for (int n = 0; n < 2; ++n) _Pragma("unroll") for (int k = 0; k < 2; ++k) \
;     dst[n][k] = *(const LAS bf16x8*)((LAS char*)SB(b, h) + boff + n * 2048 + k * 1024)
; #define MMA(ai, bj, At_, Bt_) do { __builtin_amdgcn_s_setprio(1); \
;     _Pragma("unroll") for (int m = 0; m < 4; ++m) _Pragma("unroll") for (int n = 0; n < 2; ++n) _Pragma("unroll") for (int k = 0; k < 2; ++k) \
;       acc[ai][bj][m][n] = __builtin_amdgcn_mfma_f32_16x16x32_bf16(Bt_[n][k], At_[m][k], acc[ai][bj][m][n], 0, 0, 0); \
;     __builtin_amdgcn_s_setprio(0); } while (0)
; #define WAIT_V(n) asm volatile("s_waitcnt vmcnt(" #n ")" ::: "memory")
; #define WAIT_L(n) asm volatile("s_waitcnt lgkmcnt(" #n ")" ::: "memory")
; #define BAR __builtin_amdgcn_s_barrier()
; #define SCHED __builtin_amdgcn_sched_barrier(0)
; __device__ __forceinline__ void gemm_phase(const bf16_t* __restrict__ A, const bf16_t* __restrict__ Bt, bf16_t* __restrict__ C, int M, int N, int K,
;                                            int ldc, const int EPI, char* smem, const int wid_u) {
;     ...
;       STG(SB(0, 1), b2 + hstep);
;       WAIT_V(6); BAR; MMA(1, 1, At, B1); BAR;
;       LDB(B0, 1, 0); SCHED; LDA(At, 1, 0); STG(SA(0, 1), a2 + hstep);
;       WAIT_L(8); BAR; WAIT_L(0); MMA(0, 0, At, B0); BAR; SCHED;
;       LDB(B1, 1, 1); STG(SB(1, 0), b3);
;       BAR; WAIT_L(0); MMA(0, 1, At, B1); BAR;
;       LDA(At, 1, 1); STG(SA(1, 0), a3);
	s_add_u32 s16, s20, 0x40000
	s_addc_u32 s17, s21, 0
	s_add_i32 s52, s39, s29
	v_lshl_add_u64 v[148:149], s[16:17], 0, v[130:131]
	s_mov_b32 m0, s52
	s_nop 0
	global_load_lds_dwordx4 v[148:149], off
	v_lshl_add_u64 v[148:149], s[16:17], 0, v[128:129]
	s_add_i32 m0, s52, 0x2000
	s_nop 0
	global_load_lds_dwordx4 v[148:149], off
	s_waitcnt vmcnt(10)
	s_barrier
	v_mfma_f32_16x16x32_bf16 v[44:47], v[196:199], v[164:167], v[44:47]
	v_mfma_f32_16x16x32_bf16 v[40:43], v[204:207], v[164:167], v[40:43]
	v_mfma_f32_16x16x32_bf16 v[28:31], v[196:199], v[172:175], v[28:31]
	v_mfma_f32_16x16x32_bf16 v[24:27], v[204:207], v[172:175], v[24:27]
	v_mfma_f32_16x16x32_bf16 v[12:15], v[196:199], v[180:183], v[12:15]
	v_mfma_f32_16x16x32_bf16 v[8:11], v[204:207], v[180:183], v[8:11]
	v_mfma_f32_16x16x32_bf16 v[4:7], v[196:199], v[188:191], v[4:7]
	v_mfma_f32_16x16x32_bf16 v[0:3], v[204:207], v[188:191], v[0:3]
	v_mfma_f32_16x16x32_bf16 v[44:47], v[200:203], v[168:171], v[44:47]
	v_mfma_f32_16x16x32_bf16 v[40:43], v[208:211], v[168:171], v[40:43]
	v_mfma_f32_16x16x32_bf16 v[28:31], v[200:203], v[176:179], v[28:31]
	v_mfma_f32_16x16x32_bf16 v[24:27], v[208:211], v[176:179], v[24:27]
	v_mfma_f32_16x16x32_bf16 v[12:15], v[200:203], v[184:187], v[12:15]
	v_mfma_f32_16x16x32_bf16 v[8:11], v[208:211], v[184:187], v[8:11]
	v_mfma_f32_16x16x32_bf16 v[4:7], v[200:203], v[192:195], v[4:7]
	v_mfma_f32_16x16x32_bf16 v[0:3], v[208:211], v[192:195], v[0:3]
	s_add_i32 s52, 0, 0x18000
	v_add_u32_e32 v147, s52, v143
	s_barrier
	ds_read_b128 v[148:151], v147
	ds_read_b128 v[152:155], v147 offset:1024
	ds_read_b128 v[156:159], v147 offset:2048
	ds_read_b128 v[160:163], v147 offset:3072
	s_add_u32 s16, s22, 0x40000
	s_addc_u32 s17, s23, 0
	s_mov_b32 m0, s34
	v_lshl_add_u64 v[196:197], s[16:17], 0, v[130:131]
	ds_read_b128 v[164:167], v145 offset:32768
	ds_read_b128 v[168:171], v145 offset:33792
	ds_read_b128 v[172:175], v145 offset:34816
	ds_read_b128 v[176:179], v145 offset:35840
	ds_read_b128 v[180:183], v145 offset:36864
	ds_read_b128 v[184:187], v145 offset:37888
	ds_read_b128 v[188:191], v145 offset:38912
	ds_read_b128 v[192:195], v145 offset:39936
	global_load_lds_dwordx4 v[196:197], off
	v_lshl_add_u64 v[196:197], s[16:17], 0, v[128:129]
	s_mov_b32 m0, s35
	s_nop 0
	global_load_lds_dwordx4 v[196:197], off
	s_waitcnt vmcnt(10)
	s_waitcnt lgkmcnt(8)
	s_barrier
	s_waitcnt lgkmcnt(0)
	s_waitcnt lgkmcnt(0)
	v_mfma_f32_16x16x32_bf16 v[124:127], v[148:151], v[164:167], v[124:127]
	v_mfma_f32_16x16x32_bf16 v[120:123], v[156:159], v[164:167], v[120:123]
	v_mfma_f32_16x16x32_bf16 v[116:119], v[148:151], v[172:175], v[116:119]
	v_mfma_f32_16x16x32_bf16 v[112:115], v[156:159], v[172:175], v[112:115]
	v_mfma_f32_16x16x32_bf16 v[100:103], v[148:151], v[180:183], v[100:103]
	v_mfma_f32_16x16x32_bf16 v[96:99], v[156:159], v[180:183], v[96:99]
	v_mfma_f32_16x16x32_bf16 v[84:87], v[148:151], v[188:191], v[84:87]
	v_mfma_f32_16x16x32_bf16 v[80:83], v[156:159], v[188:191], v[80:83]
	v_mfma_f32_16x16x32_bf16 v[124:127], v[152:155], v[168:171], v[124:127]
	v_mfma_f32_16x16x32_bf16 v[120:123], v[160:163], v[168:171], v[120:123]
	v_mfma_f32_16x16x32_bf16 v[116:119], v[152:155], v[176:179], v[116:119]
	v_mfma_f32_16x16x32_bf16 v[112:115], v[160:163], v[176:179], v[112:115]
	v_mfma_f32_16x16x32_bf16 v[100:103], v[152:155], v[184:187], v[100:103]
	v_mfma_f32_16x16x32_bf16 v[96:99], v[160:163], v[184:187], v[96:99]
	v_mfma_f32_16x16x32_bf16 v[84:87], v[152:155], v[192:195], v[84:87]
	v_mfma_f32_16x16x32_bf16 v[80:83], v[160:163], v[192:195], v[80:83]
	s_barrier
	s_add_i32 s22, 0, 0x1c000
	s_add_i32 s16, s52, s29
	v_add_u32_e32 v147, s22, v143
	v_lshl_add_u64 v[212:213], v[212:213], 0, s[8:9]
	s_mov_b32 m0, s16
	ds_read_b128 v[196:199], v147
	ds_read_b128 v[200:203], v147 offset:1024
	ds_read_b128 v[204:207], v147 offset:2048
	ds_read_b128 v[208:211], v147 offset:3072
	global_load_lds_dwordx4 v[212:213], off
	v_lshl_add_u64 v[212:213], v[214:215], 0, s[8:9]
	s_add_i32 m0, s16, 0x2000
	s_nop 0
	global_load_lds_dwordx4 v[212:213], off
	s_waitcnt vmcnt(10)
	s_barrier
	s_waitcnt lgkmcnt(0)
	s_waitcnt lgkmcnt(0)
	v_mfma_f32_16x16x32_bf16 v[108:111], v[196:199], v[164:167], v[108:111]
	v_mfma_f32_16x16x32_bf16 v[104:107], v[204:207], v[164:167], v[104:107]
	v_mfma_f32_16x16x32_bf16 v[92:95], v[196:199], v[172:175], v[92:95]
	v_mfma_f32_16x16x32_bf16 v[88:91], v[204:207], v[172:175], v[88:91]
	v_mfma_f32_16x16x32_bf16 v[76:79], v[196:199], v[180:183], v[76:79]
	v_mfma_f32_16x16x32_bf16 v[72:75], v[204:207], v[180:183], v[72:75]
	v_mfma_f32_16x16x32_bf16 v[68:71], v[196:199], v[188:191], v[68:71]
	v_mfma_f32_16x16x32_bf16 v[64:67], v[204:207], v[188:191], v[64:67]
	v_mfma_f32_16x16x32_bf16 v[108:111], v[200:203], v[168:171], v[108:111]
	v_mfma_f32_16x16x32_bf16 v[104:107], v[208:211], v[168:171], v[104:107]
	v_mfma_f32_16x16x32_bf16 v[92:95], v[200:203], v[176:179], v[92:95]
	v_mfma_f32_16x16x32_bf16 v[88:91], v[208:211], v[176:179], v[88:91]
	v_mfma_f32_16x16x32_bf16 v[76:79], v[200:203], v[184:187], v[76:79]
	v_mfma_f32_16x16x32_bf16 v[72:75], v[208:211], v[184:187], v[72:75]
	v_mfma_f32_16x16x32_bf16 v[68:71], v[200:203], v[192:195], v[68:71]
	v_mfma_f32_16x16x32_bf16 v[64:67], v[208:211], v[192:195], v[64:67]
	s_mov_b32 m0, s36
	v_lshl_add_u64 v[212:213], v[216:217], 0, s[8:9]
	s_barrier
	ds_read_b128 v[164:167], v145 offset:49152
	ds_read_b128 v[168:171], v145 offset:50176
	ds_read_b128 v[172:175], v145 offset:51200
	ds_read_b128 v[176:179], v145 offset:52224
	ds_read_b128 v[180:183], v145 offset:53248
	ds_read_b128 v[184:187], v145 offset:54272
	ds_read_b128 v[188:191], v145 offset:55296
	ds_read_b128 v[192:195], v145 offset:56320
	global_load_lds_dwordx4 v[212:213], off
	v_lshl_add_u64 v[212:213], v[218:219], 0, s[8:9]
	s_mov_b32 m0, s37
	s_nop 0
	global_load_lds_dwordx4 v[212:213], off
	s_barrier
; #define STG(P, GB) do { const char* _gb = (GB); \
;     _Pragma("unroll") for (int _i = 0; _i < 2; ++_i) { \
;       __builtin_amdgcn_global_load_lds((const unsigned*)(_gb + voff[_i]), \
;         (LAS unsigned*)((LAS char*)(P) + ldsw + _i * 8192), 16, 0, 0); } } while (0)
; #define MMA(ai, bj, At_, Bt_) do { __builtin_amdgcn_s_setprio(1); \
;     _Pragma("unroll") for (int m = 0; m < 4; ++m) _Pragma("unroll") for (int n = 0; n < 2; ++n) _Pragma("unroll") for (int k = 0; k < 2; ++k) \
;       acc[ai][bj][m][n] = __builtin_amdgcn_mfma_f32_16x16x32_bf16(Bt_[n][k], At_[m][k], acc[ai][bj][m][n], 0, 0, 0); \
;     __builtin_amdgcn_s_setprio(0); } while (0)
; #define WAIT_V(n) asm volatile("s_waitcnt vmcnt(" #n ")" ::: "memory")
; #define WAIT_L(n) asm volatile("s_waitcnt lgkmcnt(" #n ")" ::: "memory")
; __device__ __forceinline__ void gemm_phase(const bf16_t* __restrict__ A, const bf16_t* __restrict__ Bt, bf16_t* __restrict__ C, int M, int N, int K,
;                                            int ldc, const int EPI, char* smem, const int wid_u) {
;     ...
;       BAR; WAIT_L(0); MMA(1, 0, At, B0); BAR; SCHED;
;       STG(SB(1, 1), b3 + hstep);
;       WAIT_V(6); BAR; MMA(1, 1, At, B1); BAR;
;     }
;     {
;       const int brow = pm * BM, bcol = pn * BM;
; #pragma unroll
;       for (int ai = 0; ai < 2; ++ai)
; #pragma unroll
;         for (int m = 0; m < 4; ++m) {
;           const size_t row = (size_t)(brow + ai * HALF + wr * 64 + m * 16 + fr);
;           if (EPI == 0) {
; #pragma unroll
;             for (int bj = 0; bj < 2; ++bj) {
;               const f32x4 v0 = acc[ai][bj][m][0], v1 = acc[ai][bj][m][1];
;               uint4 u; u.x = cvt_pk_bf16(v0[0], v0[1]); u.y = cvt_pk_bf16(v0[2], v0[3]); u.z = cvt_pk_bf16(v1[0], v1[1]); u.w = cvt_pk_bf16(v1[2], v1[3]);
;               *(uint4*)(C + row * ldc + bcol + bj * HALF + wc * 32 + fq * 8) = u;
;             }
;           } else {
;             float o[8];
; #pragma unroll
;             for (int n = 0; n < 2; ++n) {
;               const f32x4 a = acc[ai][0][m][n], b = acc[ai][1][m][n];
; #pragma unroll
;               for (int j = 0; j < 4; ++j) o[n * 4 + j] = a[j] * __builtin_amdgcn_rcpf(1.f + __expf(-a[j])) * b[j];
;             }
;             *(uint4*)(C + row * ldc + (bcol >> 1) + wc * 32 + fq * 8) = pack8(o);
;           }
;         }
;     }
;     if (!has_next) break;
	s_waitcnt lgkmcnt(0)
	s_waitcnt lgkmcnt(0)
	v_mfma_f32_16x16x32_bf16 v[60:63], v[148:151], v[164:167], v[60:63]
	v_mfma_f32_16x16x32_bf16 v[56:59], v[156:159], v[164:167], v[56:59]
	v_mfma_f32_16x16x32_bf16 v[52:55], v[148:151], v[172:175], v[52:55]
	v_mfma_f32_16x16x32_bf16 v[48:51], v[156:159], v[172:175], v[48:51]
	v_mfma_f32_16x16x32_bf16 v[36:39], v[148:151], v[180:183], v[36:39]
	v_mfma_f32_16x16x32_bf16 v[32:35], v[156:159], v[180:183], v[32:35]
	v_mfma_f32_16x16x32_bf16 v[20:23], v[148:151], v[188:191], v[20:23]
	v_mfma_f32_16x16x32_bf16 v[16:19], v[156:159], v[188:191], v[16:19]
	v_mfma_f32_16x16x32_bf16 v[60:63], v[152:155], v[168:171], v[60:63]
	v_mfma_f32_16x16x32_bf16 v[56:59], v[160:163], v[168:171], v[56:59]
	v_mfma_f32_16x16x32_bf16 v[52:55], v[152:155], v[176:179], v[52:55]
	v_mfma_f32_16x16x32_bf16 v[48:51], v[160:163], v[176:179], v[48:51]
	v_mfma_f32_16x16x32_bf16 v[36:39], v[152:155], v[184:187], v[36:39]
	v_mfma_f32_16x16x32_bf16 v[32:35], v[160:163], v[184:187], v[32:35]
	v_mfma_f32_16x16x32_bf16 v[20:23], v[152:155], v[192:195], v[20:23]
	v_mfma_f32_16x16x32_bf16 v[16:19], v[160:163], v[192:195], v[16:19]
	s_barrier
	s_add_u32 s16, s20, 0x40080
	s_addc_u32 s17, s21, 0
	s_add_i32 s20, s22, s29
	v_lshl_add_u64 v[148:149], s[16:17], 0, v[130:131]
	s_mov_b32 m0, s20
	s_nop 0
	global_load_lds_dwordx4 v[148:149], off
	v_lshl_add_u64 v[148:149], s[16:17], 0, v[128:129]
	s_add_i32 m0, s20, 0x2000
	s_nop 0
	global_load_lds_dwordx4 v[148:149], off
	s_waitcnt vmcnt(10)
	s_barrier
	v_mfma_f32_16x16x32_bf16 v[44:47], v[196:199], v[164:167], v[44:47]
	v_mfma_f32_16x16x32_bf16 v[40:43], v[204:207], v[164:167], v[40:43]
	v_mfma_f32_16x16x32_bf16 v[28:31], v[196:199], v[172:175], v[28:31]
	v_mfma_f32_16x16x32_bf16 v[24:27], v[204:207], v[172:175], v[24:27]
	v_mfma_f32_16x16x32_bf16 v[12:15], v[196:199], v[180:183], v[12:15]
	v_mfma_f32_16x16x32_bf16 v[8:11], v[204:207], v[180:183], v[8:11]
	v_mfma_f32_16x16x32_bf16 v[4:7], v[196:199], v[188:191], v[4:7]
	v_mfma_f32_16x16x32_bf16 v[0:3], v[204:207], v[188:191], v[0:3]
	v_mfma_f32_16x16x32_bf16 v[44:47], v[200:203], v[168:171], v[44:47]
	v_mfma_f32_16x16x32_bf16 v[40:43], v[208:211], v[168:171], v[40:43]
	v_mfma_f32_16x16x32_bf16 v[28:31], v[200:203], v[176:179], v[28:31]
	v_mfma_f32_16x16x32_bf16 v[24:27], v[208:211], v[176:179], v[24:27]
	v_mfma_f32_16x16x32_bf16 v[12:15], v[200:203], v[184:187], v[12:15]
	v_mfma_f32_16x16x32_bf16 v[8:11], v[208:211], v[184:187], v[8:11]
	v_mfma_f32_16x16x32_bf16 v[4:7], v[200:203], v[192:195], v[4:7]
	v_mfma_f32_16x16x32_bf16 v[0:3], v[208:211], v[192:195], v[0:3]
	s_add_i32 s51, s51, 2
	s_add_u32 s49, s49, 0x100
	s_addc_u32 s50, s50, 0
	s_cmp_gt_u32 s51, 13
	s_mov_b64 s[16:17], s[18:19]
	s_barrier
	s_cbranch_scc0 .LBB0_334
	v_lshl_add_u32 v147, s44, 8, v142
	s_lshl_b32 s16, s45, 9
	s_mov_b32 s17, s7
	v_lshl_add_u64 v[148:149], v[132:133], 0, s[16:17]
	v_cvt_pk_bf16_f32 v68, v68, v69
	v_cvt_pk_bf16_f32 v69, v70, v71
	v_cvt_pk_bf16_f32 v70, v64, v65
	v_add_u32_e32 v64, 0x80, v147
	v_mad_i64_i32 v[150:151], s[16:17], v147, s40, v[148:149]
	v_cvt_pk_bf16_f32 v108, v108, v109
	v_cvt_pk_bf16_f32 v109, v110, v111
	v_cvt_pk_bf16_f32 v110, v104, v105
	v_cvt_pk_bf16_f32 v111, v106, v107
	v_or_b32_e32 v104, 16, v147
	v_mad_i64_i32 v[64:65], s[16:17], v64, s40, v[148:149]
	v_cvt_pk_bf16_f32 v44, v44, v45
	v_cvt_pk_bf16_f32 v45, v46, v47
	v_cvt_pk_bf16_f32 v46, v40, v41
	v_cvt_pk_bf16_f32 v47, v42, v43
	v_add_u32_e32 v40, 0x90, v147
	global_store_dwordx4 v[150:151], v[108:111], off offset:256
	v_cvt_pk_bf16_f32 v92, v92, v93
	v_cvt_pk_bf16_f32 v93, v94, v95
	v_mad_i64_i32 v[108:109], s[16:17], v104, s40, v[148:149]
	v_cvt_pk_bf16_f32 v94, v88, v89
	v_cvt_pk_bf16_f32 v95, v90, v91
	v_or_b32_e32 v88, 32, v147
	global_store_dwordx4 v[64:65], v[44:47], off offset:256
	v_cvt_pk_bf16_f32 v28, v28, v29
	v_cvt_pk_bf16_f32 v29, v30, v31
	v_mad_i64_i32 v[44:45], s[16:17], v40, s40, v[148:149]
	v_cvt_pk_bf16_f32 v30, v24, v25
	v_cvt_pk_bf16_f32 v31, v26, v27
	v_add_u32_e32 v24, 0xa0, v147
	global_store_dwordx4 v[108:109], v[92:95], off offset:256
	v_cvt_pk_bf16_f32 v76, v76, v77
	v_cvt_pk_bf16_f32 v77, v78, v79
	v_mad_i64_i32 v[92:93], s[16:17], v88, s40, v[148:149]
	v_cvt_pk_bf16_f32 v78, v72, v73
	v_cvt_pk_bf16_f32 v79, v74, v75
	v_or_b32_e32 v72, 48, v147
	global_store_dwordx4 v[44:45], v[28:31], off offset:256
	v_cvt_pk_bf16_f32 v12, v12, v13
	v_cvt_pk_bf16_f32 v13, v14, v15
	v_mad_i64_i32 v[28:29], s[16:17], v24, s40, v[148:149]
	v_cvt_pk_bf16_f32 v14, v8, v9
	v_cvt_pk_bf16_f32 v15, v10, v11
	v_add_u32_e32 v8, 0xb0, v147
	global_store_dwordx4 v[92:93], v[76:79], off offset:256
	global_store_dwordx4 v[28:29], v[12:15], off offset:256
	v_cvt_pk_bf16_f32 v124, v124, v125
	v_mad_i64_i32 v[76:77], s[16:17], v72, s40, v[148:149]
	v_mad_i64_i32 v[12:13], s[16:17], v8, s40, v[148:149]
	v_cvt_pk_bf16_f32 v125, v126, v127
	v_cvt_pk_bf16_f32 v126, v120, v121
	v_cvt_pk_bf16_f32 v127, v122, v123
	v_cvt_pk_bf16_f32 v104, v116, v117
	v_cvt_pk_bf16_f32 v105, v118, v119
	v_cvt_pk_bf16_f32 v106, v112, v113
	v_cvt_pk_bf16_f32 v107, v114, v115
	v_cvt_pk_bf16_f32 v88, v100, v101
	v_cvt_pk_bf16_f32 v89, v102, v103
	v_cvt_pk_bf16_f32 v90, v96, v97
	v_cvt_pk_bf16_f32 v91, v98, v99
	v_cvt_pk_bf16_f32 v72, v84, v85
	v_cvt_pk_bf16_f32 v73, v86, v87
	v_cvt_pk_bf16_f32 v74, v80, v81
	v_cvt_pk_bf16_f32 v75, v82, v83
	v_cvt_pk_bf16_f32 v71, v66, v67
	v_cvt_pk_bf16_f32 v60, v60, v61
	v_cvt_pk_bf16_f32 v61, v62, v63
	v_cvt_pk_bf16_f32 v62, v56, v57
	v_cvt_pk_bf16_f32 v63, v58, v59
	v_cvt_pk_bf16_f32 v40, v52, v53
	v_cvt_pk_bf16_f32 v41, v54, v55
	v_cvt_pk_bf16_f32 v42, v48, v49
	v_cvt_pk_bf16_f32 v43, v50, v51
	v_cvt_pk_bf16_f32 v24, v36, v37
	v_cvt_pk_bf16_f32 v25, v38, v39
	v_cvt_pk_bf16_f32 v26, v32, v33
	v_cvt_pk_bf16_f32 v27, v34, v35
	v_cvt_pk_bf16_f32 v8, v20, v21
	v_cvt_pk_bf16_f32 v9, v22, v23
	v_cvt_pk_bf16_f32 v10, v16, v17
	v_cvt_pk_bf16_f32 v11, v18, v19
	v_cvt_pk_bf16_f32 v4, v4, v5
	v_cvt_pk_bf16_f32 v5, v6, v7
	v_cvt_pk_bf16_f32 v6, v0, v1
	v_cvt_pk_bf16_f32 v7, v2, v3
	s_and_b64 vcc, exec, s[2:3]
	s_mov_b32 s44, s6
	s_mov_b32 s45, s10
	s_mov_b64 s[18:19], s[14:15]
	s_mov_b64 s[16:17], s[12:13]
	global_store_dwordx4 v[150:151], v[124:127], off
	global_store_dwordx4 v[108:109], v[104:107], off
	global_store_dwordx4 v[92:93], v[88:91], off
	global_store_dwordx4 v[76:77], v[72:75], off
	global_store_dwordx4 v[76:77], v[68:71], off offset:256
	global_store_dwordx4 v[64:65], v[60:63], off
	global_store_dwordx4 v[44:45], v[40:43], off
	global_store_dwordx4 v[28:29], v[24:27], off
	global_store_dwordx4 v[12:13], v[8:11], off
	global_store_dwordx4 v[12:13], v[4:7], off offset:256
	s_cbranch_vccz .LBB0_331
	s_waitcnt vmcnt(0)
	s_cmpk_gt_u32 s24, 0xff
	s_cbranch_scc1 .LBB0_338
	s_barrier

; #define STG(P, GB) do { const char* _gb = (GB); \
;     _Pragma("unroll") for (int _i = 0; _i < 2; ++_i) { \
;       __builtin_amdgcn_global_load_lds((const unsigned*)(_gb + voff[_i]), \
;         (LAS unsigned*)((LAS char*)(P) + ldsw + _i * 8192), 16, 0, 0); } } while (0)
; #define LDA(dst, b, h) _Pragma("unroll") for (int m = 0; m < 4; ++m) _Pragma("unroll") for (int k = 0; k < 2; ++k) \
;     dst[m][k] = *(const LAS bf16x8*)((LAS char*)SA(b, h) + aoff + m * 2048 + k * 1024)
; #define LDB(dst, b, h) _Pragma("unroll") for (int n = 0; n < 2; ++n) _Pragma("unroll") for (int k = 0; k < 2; ++k) \
;     dst[n][k] = *(const LAS bf16x8*)((LAS char*)SB(b, h) + boff + n * 2048 + k * 1024)
; #define MMA(ai, bj, At_, Bt_) do { __builtin_amdgcn_s_setprio(1); \
;     _Pragma("unroll") for (int m = 0; m < 4; ++m) _Pragma("unroll") for (int n = 0; n < 2; ++n) _Pragma("unroll") for (int k = 0; k < 2; ++k) \
;       acc[ai][bj][m][n] = __builtin_amdgcn_mfma_f32_16x16x32_bf16(Bt_[n][k], At_[m][k], acc[ai][bj][m][n], 0, 0, 0); \
;     __builtin_amdgcn_s_setprio(0); } while (0)
; #define WAIT_L(n) asm volatile("s_waitcnt lgkmcnt(" #n ")" ::: "memory")
; #define BAR __builtin_amdgcn_s_barrier()
; #define SCHED __builtin_amdgcn_sched_barrier(0)
; __device__ __forceinline__ void gemm_phase(const bf16_t* __restrict__ A, const bf16_t* __restrict__ Bt, bf16_t* __restrict__ C, int M, int N, int K,
;                                            int ldc, const int EPI, char* smem, const int wid_u) {
;     ...
;     const bool has_next = gemm_unit(ui + 1, nM, nN, nwg, npm, npn);
;     const char* nA = has_next ? (const char*)A + (size_t)npm * tstep : cA;
;     const char* nB = has_next ? (const char*)Bt + (size_t)npn * tstep : cB;
;     for (int t = 0; t < nt; t += 2) {
;       const bool last = (t == nt - 2);
;       const char* a1 = cA + (size_t)(t + 1) * kstep;
;       const char* a2 = last ? nA : cA + (size_t)(t + 2) * kstep;
;       const char* b2 = last ? nB : cB + (size_t)(t + 2) * kstep;
;       const char* a3 = a2 + kstep;
;       const char* b3 = b2 + kstep;
;       LDB(B0, 0, 0); SCHED; LDA(At, 0, 0); STG(SA(1, 1), a1 + hstep);
;       WAIT_L(8); BAR; WAIT_L(0); MMA(0, 0, At, B0); BAR; SCHED;
;       LDB(B1, 0, 1); STG(SB(0, 0), b2);
;       BAR; WAIT_L(0); MMA(0, 1, At, B1); BAR;
;       LDA(At, 0, 1); STG(SA(0, 0), a2);
;       BAR; WAIT_L(0); MMA(1, 0, At, B0); BAR; SCHED;
.LBB0_905:
	ds_read_b128 v[148:151], v144
	ds_read_b128 v[152:155], v144 offset:1024
	ds_read_b128 v[156:159], v144 offset:2048
	ds_read_b128 v[160:163], v144 offset:3072
	s_add_u32 s18, s16, 0x100
	s_addc_u32 s19, s17, 0
	s_cmp_eq_u32 s55, 12
	s_cselect_b32 s23, s49, s19
	s_cselect_b32 s22, s50, s18
	s_cselect_b32 s21, s51, s54
	s_cselect_b32 s20, s52, s53
	s_mov_b32 m0, s38
	v_lshl_add_u64 v[196:197], s[16:17], 0, v[136:137]
	ds_read_b128 v[164:167], v145
	ds_read_b128 v[168:171], v145 offset:1024
	ds_read_b128 v[172:175], v145 offset:2048
	ds_read_b128 v[176:179], v145 offset:3072
	ds_read_b128 v[180:183], v145 offset:4096
	ds_read_b128 v[184:187], v145 offset:5120
	ds_read_b128 v[188:191], v145 offset:6144
	ds_read_b128 v[192:195], v145 offset:7168
	global_load_lds_dwordx4 v[196:197], off
	v_lshl_add_u64 v[196:197], s[16:17], 0, v[134:135]
	s_mov_b32 m0, s39
	s_nop 0
	global_load_lds_dwordx4 v[196:197], off
	s_waitcnt vmcnt(10)
	s_waitcnt lgkmcnt(8)
	s_barrier
	s_waitcnt lgkmcnt(0)
	s_waitcnt lgkmcnt(0)
	v_mfma_f32_16x16x32_bf16 v[124:127], v[148:151], v[164:167], v[124:127]
	v_mfma_f32_16x16x32_bf16 v[120:123], v[156:159], v[164:167], v[120:123]
	v_mfma_f32_16x16x32_bf16 v[116:119], v[148:151], v[172:175], v[116:119]
	v_mfma_f32_16x16x32_bf16 v[112:115], v[156:159], v[172:175], v[112:115]
	v_mfma_f32_16x16x32_bf16 v[100:103], v[148:151], v[180:183], v[100:103]
	v_mfma_f32_16x16x32_bf16 v[96:99], v[156:159], v[180:183], v[96:99]
	v_mfma_f32_16x16x32_bf16 v[84:87], v[148:151], v[188:191], v[84:87]
	v_mfma_f32_16x16x32_bf16 v[80:83], v[156:159], v[188:191], v[80:83]
	v_mfma_f32_16x16x32_bf16 v[124:127], v[152:155], v[168:171], v[124:127]
	v_mfma_f32_16x16x32_bf16 v[120:123], v[160:163], v[168:171], v[120:123]
	v_mfma_f32_16x16x32_bf16 v[116:119], v[152:155], v[176:179], v[116:119]
	v_mfma_f32_16x16x32_bf16 v[112:115], v[160:163], v[176:179], v[112:115]
	v_mfma_f32_16x16x32_bf16 v[100:103], v[152:155], v[184:187], v[100:103]
	v_mfma_f32_16x16x32_bf16 v[96:99], v[160:163], v[184:187], v[96:99]
	v_mfma_f32_16x16x32_bf16 v[84:87], v[152:155], v[192:195], v[84:87]
	v_mfma_f32_16x16x32_bf16 v[80:83], v[160:163], v[192:195], v[80:83]
	s_barrier
	s_mov_b32 m0, s40
	v_lshl_add_u64 v[212:213], s[20:21], 0, v[130:131]
	ds_read_b128 v[196:199], v146
	ds_read_b128 v[200:203], v146 offset:1024
	ds_read_b128 v[204:207], v146 offset:2048
	ds_read_b128 v[208:211], v146 offset:3072
	global_load_lds_dwordx4 v[212:213], off
	v_lshl_add_u64 v[214:215], s[20:21], 0, v[128:129]
	s_mov_b32 m0, s41
	s_nop 0
	global_load_lds_dwordx4 v[214:215], off
	s_waitcnt vmcnt(10)
	s_barrier
	s_waitcnt lgkmcnt(0)
	s_waitcnt lgkmcnt(0)
	v_mfma_f32_16x16x32_bf16 v[108:111], v[196:199], v[164:167], v[108:111]
	v_mfma_f32_16x16x32_bf16 v[104:107], v[204:207], v[164:167], v[104:107]
	v_mfma_f32_16x16x32_bf16 v[92:95], v[196:199], v[172:175], v[92:95]
	v_mfma_f32_16x16x32_bf16 v[88:91], v[204:207], v[172:175], v[88:91]
	v_mfma_f32_16x16x32_bf16 v[76:79], v[196:199], v[180:183], v[76:79]
	v_mfma_f32_16x16x32_bf16 v[72:75], v[204:207], v[180:183], v[72:75]
	v_mfma_f32_16x16x32_bf16 v[68:71], v[196:199], v[188:191], v[68:71]
	v_mfma_f32_16x16x32_bf16 v[64:67], v[204:207], v[188:191], v[64:67]
	v_mfma_f32_16x16x32_bf16 v[108:111], v[200:203], v[168:171], v[108:111]
	v_mfma_f32_16x16x32_bf16 v[104:107], v[208:211], v[168:171], v[104:107]
	v_mfma_f32_16x16x32_bf16 v[92:95], v[200:203], v[176:179], v[92:95]
	v_mfma_f32_16x16x32_bf16 v[88:91], v[208:211], v[176:179], v[88:91]
	v_mfma_f32_16x16x32_bf16 v[76:79], v[200:203], v[184:187], v[76:79]
	v_mfma_f32_16x16x32_bf16 v[72:75], v[208:211], v[184:187], v[72:75]
	v_mfma_f32_16x16x32_bf16 v[68:71], v[200:203], v[192:195], v[68:71]
	v_mfma_f32_16x16x32_bf16 v[64:67], v[208:211], v[192:195], v[64:67]
	s_mov_b32 m0, s30
	v_lshl_add_u64 v[216:217], s[22:23], 0, v[130:131]
	s_barrier
	ds_read_b128 v[164:167], v145 offset:16384
	ds_read_b128 v[168:171], v145 offset:17408
	ds_read_b128 v[172:175], v145 offset:18432
	ds_read_b128 v[176:179], v145 offset:19456
	ds_read_b128 v[180:183], v145 offset:20480
	ds_read_b128 v[184:187], v145 offset:21504
	ds_read_b128 v[188:191], v145 offset:22528
	ds_read_b128 v[192:195], v145 offset:23552
	global_load_lds_dwordx4 v[216:217], off
	v_lshl_add_u64 v[218:219], s[22:23], 0, v[128:129]
	s_mov_b32 m0, s31
	s_nop 0
	global_load_lds_dwordx4 v[218:219], off
	s_barrier
	s_waitcnt lgkmcnt(0)
	s_waitcnt lgkmcnt(0)
	v_mfma_f32_16x16x32_bf16 v[60:63], v[148:151], v[164:167], v[60:63]
	v_mfma_f32_16x16x32_bf16 v[56:59], v[156:159], v[164:167], v[56:59]
	v_mfma_f32_16x16x32_bf16 v[52:55], v[148:151], v[172:175], v[52:55]
	v_mfma_f32_16x16x32_bf16 v[48:51], v[156:159], v[172:175], v[48:51]
	v_mfma_f32_16x16x32_bf16 v[36:39], v[148:151], v[180:183], v[36:39]
	v_mfma_f32_16x16x32_bf16 v[32:35], v[156:159], v[180:183], v[32:35]
	v_mfma_f32_16x16x32_bf16 v[20:23], v[148:151], v[188:191], v[20:23]
	v_mfma_f32_16x16x32_bf16 v[16:19], v[156:159], v[188:191], v[16:19]
	v_mfma_f32_16x16x32_bf16 v[60:63], v[152:155], v[168:171], v[60:63]
	v_mfma_f32_16x16x32_bf16 v[56:59], v[160:163], v[168:171], v[56:59]
	v_mfma_f32_16x16x32_bf16 v[52:55], v[152:155], v[176:179], v[52:55]
	v_mfma_f32_16x16x32_bf16 v[48:51], v[160:163], v[176:179], v[48:51]
	v_mfma_f32_16x16x32_bf16 v[36:39], v[152:155], v[184:187], v[36:39]
	v_mfma_f32_16x16x32_bf16 v[32:35], v[160:163], v[184:187], v[32:35]
	v_mfma_f32_16x16x32_bf16 v[20:23], v[152:155], v[192:195], v[20:23]
	v_mfma_f32_16x16x32_bf16 v[16:19], v[160:163], v[192:195], v[16:19]
	s_barrier
; #define STG(P, GB) do { const char* _gb = (GB); \
;     _Pragma("unroll") for (int _i = 0; _i < 2; ++_i) { \
;       __builtin_amdgcn_global_load_lds((const unsigned*)(_gb + voff[_i]), \
;         (LAS unsigned*)((LAS char*)(P) + ldsw + _i * 8192), 16, 0, 0); } } while (0)
; #define LDA(dst, b, h) _Pragma("unroll") for (int m = 0; m < 4; ++m) _Pragma("unroll") for (int k = 0; k < 2; ++k) \
;     dst[m][k] = *(const LAS bf16x8*)((LAS char*)SA(b, h) + aoff + m * 2048 + k * 1024)
; #define LDB(dst, b, h) _Pragma("unroll") for (int n = 0; n < 2; ++n) _Pragma("unroll") for (int k = 0; k < 2; ++k) \
;     dst[n][k] = *(const LAS bf16x8*)((LAS char*)SB(b, h) + boff + n * 2048 + k * 1024)
; #define MMA(ai, bj, At_, Bt_) do { __builtin_amdgcn_s_setprio(1); \
;     _Pragma("unroll") for (int m = 0; m < 4; ++m) _Pragma("unroll") for (int n = 0; n < 2; ++n) _Pragma("unroll") for (int k = 0; k < 2; ++k) \
;       acc[ai][bj][m][n] = __builtin_amdgcn_mfma_f32_16x16x32_bf16(Bt_[n][k], At_[m][k], acc[ai][bj][m][n], 0, 0, 0); \
;     __builtin_amdgcn_s_setprio(0); } while (0)
; #define WAIT_V(n) asm volatile("s_waitcnt vmcnt(" #n ")" ::: "memory")
; #define WAIT_L(n) asm volatile("s_waitcnt lgkmcnt(" #n ")" ::: "memory")
; #define BAR __builtin_amdgcn_s_barrier()
; #define SCHED __builtin_amdgcn_sched_barrier(0)
; __device__ __forceinline__ void gemm_phase(const bf16_t* __restrict__ A, const bf16_t* __restrict__ Bt, bf16_t* __restrict__ C, int M, int N, int K,
;                                            int ldc, const int EPI, char* smem, const int wid_u) {
;     ...
;       STG(SB(0, 1), b2 + hstep);
;       WAIT_V(6); BAR; MMA(1, 1, At, B1); BAR;
;       LDB(B0, 1, 0); SCHED; LDA(At, 1, 0); STG(SA(0, 1), a2 + hstep);
;       WAIT_L(8); BAR; WAIT_L(0); MMA(0, 0, At, B0); BAR; SCHED;
;       LDB(B1, 1, 1); STG(SB(1, 0), b3);
;       BAR; WAIT_L(0); MMA(0, 1, At, B1); BAR;
;       LDA(At, 1, 1); STG(SA(1, 0), a3);
	s_add_u32 s16, s20, 0x40000
	s_addc_u32 s17, s21, 0
	s_mov_b32 m0, s44
	v_lshl_add_u64 v[148:149], s[16:17], 0, v[130:131]
	global_load_lds_dwordx4 v[148:149], off
	v_lshl_add_u64 v[148:149], s[16:17], 0, v[128:129]
	s_add_i32 m0, s44, 0x2000
	s_nop 0
	global_load_lds_dwordx4 v[148:149], off
	s_waitcnt vmcnt(10)
	s_barrier
	v_mfma_f32_16x16x32_bf16 v[44:47], v[196:199], v[164:167], v[44:47]
	v_mfma_f32_16x16x32_bf16 v[40:43], v[204:207], v[164:167], v[40:43]
	v_mfma_f32_16x16x32_bf16 v[28:31], v[196:199], v[172:175], v[28:31]
	v_mfma_f32_16x16x32_bf16 v[24:27], v[204:207], v[172:175], v[24:27]
	v_mfma_f32_16x16x32_bf16 v[12:15], v[196:199], v[180:183], v[12:15]
	v_mfma_f32_16x16x32_bf16 v[8:11], v[204:207], v[180:183], v[8:11]
	v_mfma_f32_16x16x32_bf16 v[4:7], v[196:199], v[188:191], v[4:7]
	v_mfma_f32_16x16x32_bf16 v[0:3], v[204:207], v[188:191], v[0:3]
	v_mfma_f32_16x16x32_bf16 v[44:47], v[200:203], v[168:171], v[44:47]
	v_mfma_f32_16x16x32_bf16 v[40:43], v[208:211], v[168:171], v[40:43]
	v_mfma_f32_16x16x32_bf16 v[28:31], v[200:203], v[176:179], v[28:31]
	v_mfma_f32_16x16x32_bf16 v[24:27], v[208:211], v[176:179], v[24:27]
	v_mfma_f32_16x16x32_bf16 v[12:15], v[200:203], v[184:187], v[12:15]
	v_mfma_f32_16x16x32_bf16 v[8:11], v[208:211], v[184:187], v[8:11]
	v_mfma_f32_16x16x32_bf16 v[4:7], v[200:203], v[192:195], v[4:7]
	v_mfma_f32_16x16x32_bf16 v[0:3], v[208:211], v[192:195], v[0:3]
	s_add_i32 s56, 0, 0x18000
	v_add_u32_e32 v147, s56, v143
	s_barrier
	ds_read_b128 v[148:151], v147
	ds_read_b128 v[152:155], v147 offset:1024
	ds_read_b128 v[156:159], v147 offset:2048
	ds_read_b128 v[160:163], v147 offset:3072
	s_add_u32 s16, s22, 0x40000
	s_addc_u32 s17, s23, 0
	s_mov_b32 m0, s34
	v_lshl_add_u64 v[196:197], s[16:17], 0, v[130:131]
	ds_read_b128 v[164:167], v145 offset:32768
	ds_read_b128 v[168:171], v145 offset:33792
	ds_read_b128 v[172:175], v145 offset:34816
	ds_read_b128 v[176:179], v145 offset:35840
	ds_read_b128 v[180:183], v145 offset:36864
	ds_read_b128 v[184:187], v145 offset:37888
	ds_read_b128 v[188:191], v145 offset:38912
	ds_read_b128 v[192:195], v145 offset:39936
	global_load_lds_dwordx4 v[196:197], off
	v_lshl_add_u64 v[196:197], s[16:17], 0, v[128:129]
	s_mov_b32 m0, s35
	s_nop 0
	global_load_lds_dwordx4 v[196:197], off
	s_waitcnt vmcnt(10)
	s_waitcnt lgkmcnt(8)
	s_barrier
	s_waitcnt lgkmcnt(0)
	s_waitcnt lgkmcnt(0)
	v_mfma_f32_16x16x32_bf16 v[124:127], v[148:151], v[164:167], v[124:127]
	v_mfma_f32_16x16x32_bf16 v[120:123], v[156:159], v[164:167], v[120:123]
	v_mfma_f32_16x16x32_bf16 v[116:119], v[148:151], v[172:175], v[116:119]
	v_mfma_f32_16x16x32_bf16 v[112:115], v[156:159], v[172:175], v[112:115]
	v_mfma_f32_16x16x32_bf16 v[100:103], v[148:151], v[180:183], v[100:103]
	v_mfma_f32_16x16x32_bf16 v[96:99], v[156:159], v[180:183], v[96:99]
	v_mfma_f32_16x16x32_bf16 v[84:87], v[148:151], v[188:191], v[84:87]
	v_mfma_f32_16x16x32_bf16 v[80:83], v[156:159], v[188:191], v[80:83]
	v_mfma_f32_16x16x32_bf16 v[124:127], v[152:155], v[168:171], v[124:127]
	v_mfma_f32_16x16x32_bf16 v[120:123], v[160:163], v[168:171], v[120:123]
	v_mfma_f32_16x16x32_bf16 v[116:119], v[152:155], v[176:179], v[116:119]
	v_mfma_f32_16x16x32_bf16 v[112:115], v[160:163], v[176:179], v[112:115]
	v_mfma_f32_16x16x32_bf16 v[100:103], v[152:155], v[184:187], v[100:103]
	v_mfma_f32_16x16x32_bf16 v[96:99], v[160:163], v[184:187], v[96:99]
	v_mfma_f32_16x16x32_bf16 v[84:87], v[152:155], v[192:195], v[84:87]
	v_mfma_f32_16x16x32_bf16 v[80:83], v[160:163], v[192:195], v[80:83]
	s_barrier
	s_add_i32 s22, 0, 0x1c000
	s_add_i32 s16, s56, s29
	v_add_u32_e32 v147, s22, v143
	v_lshl_add_u64 v[212:213], v[212:213], 0, s[10:11]
	s_mov_b32 m0, s16
	ds_read_b128 v[196:199], v147
	ds_read_b128 v[200:203], v147 offset:1024
	ds_read_b128 v[204:207], v147 offset:2048
	ds_read_b128 v[208:211], v147 offset:3072
	global_load_lds_dwordx4 v[212:213], off
	v_lshl_add_u64 v[212:213], v[214:215], 0, s[10:11]
	s_add_i32 m0, s16, 0x2000
	s_nop 0
	global_load_lds_dwordx4 v[212:213], off
	s_waitcnt vmcnt(10)
	s_barrier
	s_waitcnt lgkmcnt(0)
	s_waitcnt lgkmcnt(0)
	v_mfma_f32_16x16x32_bf16 v[108:111], v[196:199], v[164:167], v[108:111]
	v_mfma_f32_16x16x32_bf16 v[104:107], v[204:207], v[164:167], v[104:107]
	v_mfma_f32_16x16x32_bf16 v[92:95], v[196:199], v[172:175], v[92:95]
	v_mfma_f32_16x16x32_bf16 v[88:91], v[204:207], v[172:175], v[88:91]
	v_mfma_f32_16x16x32_bf16 v[76:79], v[196:199], v[180:183], v[76:79]
	v_mfma_f32_16x16x32_bf16 v[72:75], v[204:207], v[180:183], v[72:75]
	v_mfma_f32_16x16x32_bf16 v[68:71], v[196:199], v[188:191], v[68:71]
	v_mfma_f32_16x16x32_bf16 v[64:67], v[204:207], v[188:191], v[64:67]
	v_mfma_f32_16x16x32_bf16 v[108:111], v[200:203], v[168:171], v[108:111]
	v_mfma_f32_16x16x32_bf16 v[104:107], v[208:211], v[168:171], v[104:107]
	v_mfma_f32_16x16x32_bf16 v[92:95], v[200:203], v[176:179], v[92:95]
	v_mfma_f32_16x16x32_bf16 v[88:91], v[208:211], v[176:179], v[88:91]
	v_mfma_f32_16x16x32_bf16 v[76:79], v[200:203], v[184:187], v[76:79]
	v_mfma_f32_16x16x32_bf16 v[72:75], v[208:211], v[184:187], v[72:75]
	v_mfma_f32_16x16x32_bf16 v[68:71], v[200:203], v[192:195], v[68:71]
	v_mfma_f32_16x16x32_bf16 v[64:67], v[208:211], v[192:195], v[64:67]
	s_mov_b32 m0, s36
	v_lshl_add_u64 v[212:213], v[216:217], 0, s[10:11]
	s_barrier
	ds_read_b128 v[164:167], v145 offset:49152
	ds_read_b128 v[168:171], v145 offset:50176
	ds_read_b128 v[172:175], v145 offset:51200
	ds_read_b128 v[176:179], v145 offset:52224
	ds_read_b128 v[180:183], v145 offset:53248
	ds_read_b128 v[184:187], v145 offset:54272
	ds_read_b128 v[188:191], v145 offset:55296
	ds_read_b128 v[192:195], v145 offset:56320
	global_load_lds_dwordx4 v[212:213], off
	v_lshl_add_u64 v[212:213], v[218:219], 0, s[10:11]
	s_mov_b32 m0, s37
	s_nop 0
	global_load_lds_dwordx4 v[212:213], off
	s_barrier
; #define STG(P, GB) do { const char* _gb = (GB); \
;     _Pragma("unroll") for (int _i = 0; _i < 2; ++_i) { \
;       __builtin_amdgcn_global_load_lds((const unsigned*)(_gb + voff[_i]), \
;         (LAS unsigned*)((LAS char*)(P) + ldsw + _i * 8192), 16, 0, 0); } } while (0)
; #define MMA(ai, bj, At_, Bt_) do { __builtin_amdgcn_s_setprio(1); \
;     _Pragma("unroll") for (int m = 0; m < 4; ++m) _Pragma("unroll") for (int n = 0; n < 2; ++n) _Pragma("unroll") for (int k = 0; k < 2; ++k) \
;       acc[ai][bj][m][n] = __builtin_amdgcn_mfma_f32_16x16x32_bf16(Bt_[n][k], At_[m][k], acc[ai][bj][m][n], 0, 0, 0); \
;     __builtin_amdgcn_s_setprio(0); } while (0)
; #define WAIT_V(n) asm volatile("s_waitcnt vmcnt(" #n ")" ::: "memory")
; #define WAIT_L(n) asm volatile("s_waitcnt lgkmcnt(" #n ")" ::: "memory")
; #define BAR __builtin_amdgcn_s_barrier()
; #define SCHED __builtin_amdgcn_sched_barrier(0)
; __device__ __forceinline__ void gemm_phase(const bf16_t* __restrict__ A, const bf16_t* __restrict__ Bt, bf16_t* __restrict__ C, int M, int N, int K,
;                                            int ldc, const int EPI, char* smem, const int wid_u) {
;     ...
;       BAR; WAIT_L(0); MMA(1, 0, At, B0); BAR; SCHED;
;       STG(SB(1, 1), b3 + hstep);
;       WAIT_V(6); BAR; MMA(1, 1, At, B1); BAR;
;     }
	s_waitcnt lgkmcnt(0)
	s_waitcnt lgkmcnt(0)
	v_mfma_f32_16x16x32_bf16 v[60:63], v[148:151], v[164:167], v[60:63]
	v_mfma_f32_16x16x32_bf16 v[56:59], v[156:159], v[164:167], v[56:59]
	v_mfma_f32_16x16x32_bf16 v[52:55], v[148:151], v[172:175], v[52:55]
	v_mfma_f32_16x16x32_bf16 v[48:51], v[156:159], v[172:175], v[48:51]
	v_mfma_f32_16x16x32_bf16 v[36:39], v[148:151], v[180:183], v[36:39]
	v_mfma_f32_16x16x32_bf16 v[32:35], v[156:159], v[180:183], v[32:35]
	v_mfma_f32_16x16x32_bf16 v[20:23], v[148:151], v[188:191], v[20:23]
	v_mfma_f32_16x16x32_bf16 v[16:19], v[156:159], v[188:191], v[16:19]
	v_mfma_f32_16x16x32_bf16 v[60:63], v[152:155], v[168:171], v[60:63]
	v_mfma_f32_16x16x32_bf16 v[56:59], v[160:163], v[168:171], v[56:59]
	v_mfma_f32_16x16x32_bf16 v[52:55], v[152:155], v[176:179], v[52:55]
	v_mfma_f32_16x16x32_bf16 v[48:51], v[160:163], v[176:179], v[48:51]
	v_mfma_f32_16x16x32_bf16 v[36:39], v[152:155], v[184:187], v[36:39]
	v_mfma_f32_16x16x32_bf16 v[32:35], v[160:163], v[184:187], v[32:35]
	v_mfma_f32_16x16x32_bf16 v[20:23], v[152:155], v[192:195], v[20:23]
	v_mfma_f32_16x16x32_bf16 v[16:19], v[160:163], v[192:195], v[16:19]
	s_barrier
	s_add_u32 s16, s20, 0x40080
	s_addc_u32 s17, s21, 0
	s_add_i32 s20, s22, s29
	v_lshl_add_u64 v[148:149], s[16:17], 0, v[130:131]
	s_mov_b32 m0, s20
	s_nop 0
	global_load_lds_dwordx4 v[148:149], off
	v_lshl_add_u64 v[148:149], s[16:17], 0, v[128:129]
	s_add_i32 m0, s20, 0x2000
	s_nop 0
	global_load_lds_dwordx4 v[148:149], off
	s_waitcnt vmcnt(10)
	s_barrier
	v_mfma_f32_16x16x32_bf16 v[44:47], v[196:199], v[164:167], v[44:47]
	v_mfma_f32_16x16x32_bf16 v[40:43], v[204:207], v[164:167], v[40:43]
	v_mfma_f32_16x16x32_bf16 v[28:31], v[196:199], v[172:175], v[28:31]
	v_mfma_f32_16x16x32_bf16 v[24:27], v[204:207], v[172:175], v[24:27]
	v_mfma_f32_16x16x32_bf16 v[12:15], v[196:199], v[180:183], v[12:15]
	v_mfma_f32_16x16x32_bf16 v[8:11], v[204:207], v[180:183], v[8:11]
	v_mfma_f32_16x16x32_bf16 v[4:7], v[196:199], v[188:191], v[4:7]
	v_mfma_f32_16x16x32_bf16 v[0:3], v[204:207], v[188:191], v[0:3]
	v_mfma_f32_16x16x32_bf16 v[44:47], v[200:203], v[168:171], v[44:47]
	v_mfma_f32_16x16x32_bf16 v[40:43], v[208:211], v[168:171], v[40:43]
	v_mfma_f32_16x16x32_bf16 v[28:31], v[200:203], v[176:179], v[28:31]
	v_mfma_f32_16x16x32_bf16 v[24:27], v[208:211], v[176:179], v[24:27]
	v_mfma_f32_16x16x32_bf16 v[12:15], v[200:203], v[184:187], v[12:15]
	v_mfma_f32_16x16x32_bf16 v[8:11], v[208:211], v[184:187], v[8:11]
	v_mfma_f32_16x16x32_bf16 v[4:7], v[200:203], v[192:195], v[4:7]
	v_mfma_f32_16x16x32_bf16 v[0:3], v[208:211], v[192:195], v[0:3]
	s_add_i32 s55, s55, 2
	s_add_u32 s53, s53, 0x100
	s_addc_u32 s54, s54, 0
	s_cmp_gt_u32 s55, 13
	s_mov_b64 s[16:17], s[18:19]
	s_barrier
	s_cbranch_scc0 .LBB0_905
; __device__ __forceinline__ void gemm_phase(const bf16_t* __restrict__ A, const bf16_t* __restrict__ Bt, bf16_t* __restrict__ C, int M, int N, int K,
;                                            int ldc, const int EPI, char* smem, const int wid_u) {
;     ...
;     {
;       const int brow = pm * BM, bcol = pn * BM;
; #pragma unroll
;       for (int ai = 0; ai < 2; ++ai)
; #pragma unroll
;         for (int m = 0; m < 4; ++m) {
;           const size_t row = (size_t)(brow + ai * HALF + wr * 64 + m * 16 + fr);
;           if (EPI == 0) {
; #pragma unroll
;             for (int bj = 0; bj < 2; ++bj) {
;               const f32x4 v0 = acc[ai][bj][m][0], v1 = acc[ai][bj][m][1];
;               uint4 u; u.x = cvt_pk_bf16(v0[0], v0[1]); u.y = cvt_pk_bf16(v0[2], v0[3]); u.z = cvt_pk_bf16(v1[0], v1[1]); u.w = cvt_pk_bf16(v1[2], v1[3]);
;               *(uint4*)(C + row * ldc + bcol + bj * HALF + wc * 32 + fq * 8) = u;
;             }
	v_lshl_add_u32 v148, s47, 8, v142
	v_cvt_pk_bf16_f32 v68, v68, v69
	v_cvt_pk_bf16_f32 v69, v70, v71
	v_cvt_pk_bf16_f32 v70, v64, v65
	v_add_u32_e32 v64, 0x80, v148
	s_lshl_b32 s16, s48, 9
	s_mov_b32 s17, s9
	v_ashrrev_i32_e32 v149, 31, v148
	v_cvt_pk_bf16_f32 v108, v108, v109
	v_cvt_pk_bf16_f32 v109, v110, v111
	v_cvt_pk_bf16_f32 v110, v104, v105
	v_or_b32_e32 v104, 16, v148
	v_ashrrev_i32_e32 v65, 31, v64
	v_cvt_pk_bf16_f32 v44, v44, v45
	v_cvt_pk_bf16_f32 v45, v46, v47
	v_cvt_pk_bf16_f32 v46, v40, v41
	v_add_u32_e32 v40, 0x90, v148
	v_lshl_add_u64 v[150:151], v[132:133], 0, s[16:17]
	v_lshlrev_b64 v[152:153], 11, v[148:149]
	v_ashrrev_i32_e32 v105, 31, v104
	v_cvt_pk_bf16_f32 v92, v92, v93
	v_cvt_pk_bf16_f32 v93, v94, v95
	v_cvt_pk_bf16_f32 v94, v88, v89
	v_or_b32_e32 v88, 32, v148
	v_lshlrev_b64 v[64:65], 11, v[64:65]
	v_ashrrev_i32_e32 v41, 31, v40
	v_cvt_pk_bf16_f32 v28, v28, v29
	v_cvt_pk_bf16_f32 v29, v30, v31
	v_cvt_pk_bf16_f32 v30, v24, v25
	v_add_u32_e32 v24, 0xa0, v148
	v_lshl_add_u64 v[152:153], v[150:151], 0, v[152:153]
	v_cvt_pk_bf16_f32 v111, v106, v107
	v_lshlrev_b64 v[104:105], 11, v[104:105]
	v_ashrrev_i32_e32 v89, 31, v88
	v_cvt_pk_bf16_f32 v76, v76, v77
	v_cvt_pk_bf16_f32 v77, v78, v79
	v_cvt_pk_bf16_f32 v78, v72, v73
	v_or_b32_e32 v72, 48, v148
	v_lshl_add_u64 v[64:65], v[150:151], 0, v[64:65]
	v_cvt_pk_bf16_f32 v47, v42, v43
	v_lshlrev_b64 v[40:41], 11, v[40:41]
	v_ashrrev_i32_e32 v25, 31, v24
	v_cvt_pk_bf16_f32 v12, v12, v13
	v_cvt_pk_bf16_f32 v13, v14, v15
	v_cvt_pk_bf16_f32 v14, v8, v9
	v_add_u32_e32 v8, 0xb0, v148
	global_store_dwordx4 v[152:153], v[108:111], off offset:256
	v_cvt_pk_bf16_f32 v95, v90, v91
	v_lshlrev_b64 v[88:89], 11, v[88:89]
	v_lshl_add_u64 v[108:109], v[150:151], 0, v[104:105]
	v_ashrrev_i32_e32 v73, 31, v72
	global_store_dwordx4 v[64:65], v[44:47], off offset:256
	v_cvt_pk_bf16_f32 v31, v26, v27
	v_lshlrev_b64 v[24:25], 11, v[24:25]
	v_lshl_add_u64 v[44:45], v[150:151], 0, v[40:41]
	v_ashrrev_i32_e32 v9, 31, v8
	global_store_dwordx4 v[108:109], v[92:95], off offset:256
	v_cvt_pk_bf16_f32 v79, v74, v75
	v_lshlrev_b64 v[72:73], 11, v[72:73]
	v_lshl_add_u64 v[92:93], v[150:151], 0, v[88:89]
	global_store_dwordx4 v[44:45], v[28:31], off offset:256
	v_cvt_pk_bf16_f32 v15, v10, v11
	v_lshlrev_b64 v[8:9], 11, v[8:9]
	v_lshl_add_u64 v[28:29], v[150:151], 0, v[24:25]
	v_cvt_pk_bf16_f32 v124, v124, v125
	v_cvt_pk_bf16_f32 v125, v126, v127
	v_cvt_pk_bf16_f32 v126, v120, v121
	v_cvt_pk_bf16_f32 v127, v122, v123
	v_cvt_pk_bf16_f32 v104, v116, v117
	v_cvt_pk_bf16_f32 v105, v118, v119
	v_cvt_pk_bf16_f32 v106, v112, v113
	v_cvt_pk_bf16_f32 v107, v114, v115
	v_cvt_pk_bf16_f32 v88, v100, v101
	v_cvt_pk_bf16_f32 v89, v102, v103
	v_cvt_pk_bf16_f32 v90, v96, v97
	v_cvt_pk_bf16_f32 v91, v98, v99
	global_store_dwordx4 v[92:93], v[76:79], off offset:256
	v_cvt_pk_bf16_f32 v74, v80, v81
	v_cvt_pk_bf16_f32 v75, v82, v83
	v_lshl_add_u64 v[76:77], v[150:151], 0, v[72:73]
	v_cvt_pk_bf16_f32 v72, v84, v85
	v_cvt_pk_bf16_f32 v73, v86, v87
	v_cvt_pk_bf16_f32 v71, v66, v67
	v_cvt_pk_bf16_f32 v60, v60, v61
	v_cvt_pk_bf16_f32 v61, v62, v63
	v_cvt_pk_bf16_f32 v62, v56, v57
	v_cvt_pk_bf16_f32 v63, v58, v59
	v_cvt_pk_bf16_f32 v40, v52, v53
	v_cvt_pk_bf16_f32 v41, v54, v55
	v_cvt_pk_bf16_f32 v42, v48, v49
	v_cvt_pk_bf16_f32 v43, v50, v51
	v_cvt_pk_bf16_f32 v24, v36, v37
	v_cvt_pk_bf16_f32 v25, v38, v39
	v_cvt_pk_bf16_f32 v26, v32, v33
	v_cvt_pk_bf16_f32 v27, v34, v35
	global_store_dwordx4 v[28:29], v[12:15], off offset:256
	v_cvt_pk_bf16_f32 v10, v16, v17
	v_cvt_pk_bf16_f32 v11, v18, v19
	v_lshl_add_u64 v[12:13], v[150:151], 0, v[8:9]
	v_cvt_pk_bf16_f32 v8, v20, v21
	v_cvt_pk_bf16_f32 v9, v22, v23
	v_cvt_pk_bf16_f32 v4, v4, v5
	v_cvt_pk_bf16_f32 v5, v6, v7
	v_cvt_pk_bf16_f32 v6, v0, v1
	v_cvt_pk_bf16_f32 v7, v2, v3
	s_and_b64 vcc, exec, s[4:5]
	s_mov_b32 s47, s8
	s_mov_b32 s48, s46
	s_mov_b64 s[18:19], s[14:15]
	s_mov_b64 s[16:17], s[12:13]
	global_store_dwordx4 v[152:153], v[124:127], off
	global_store_dwordx4 v[108:109], v[104:107], off
	global_store_dwordx4 v[92:93], v[88:91], off
	global_store_dwordx4 v[76:77], v[72:75], off
	global_store_dwordx4 v[76:77], v[68:71], off offset:256
	global_store_dwordx4 v[64:65], v[60:63], off
	global_store_dwordx4 v[44:45], v[40:43], off
	global_store_dwordx4 v[28:29], v[24:27], off
	global_store_dwordx4 v[12:13], v[8:11], off
	global_store_dwordx4 v[12:13], v[4:7], off offset:256
	s_cbranch_vccz .LBB0_902
	s_waitcnt vmcnt(0)
	s_cmpk_gt_u32 s24, 0xff
	s_cbranch_scc1 .LBB0_909
	s_barrier

; #define STG(P, GB) do { const char* _gb = (GB); \
;     _Pragma("unroll") for (int _i = 0; _i < 2; ++_i) { \
;       __builtin_amdgcn_global_load_lds((const unsigned*)(_gb + voff[_i]), \
;         (LAS unsigned*)((LAS char*)(P) + ldsw + _i * 8192), 16, 0, 0); } } while (0)
; #define LDA(dst, b, h) _Pragma("unroll") for (int m = 0; m < 4; ++m) _Pragma("unroll") for (int k = 0; k < 2; ++k) \
;     dst[m][k] = *(const LAS bf16x8*)((LAS char*)SA(b, h) + aoff + m * 2048 + k * 1024)
; #define LDB(dst, b, h) _Pragma("unroll") for (int n = 0; n < 2; ++n) _Pragma("unroll") for (int k = 0; k < 2; ++k) \
;     dst[n][k] = *(const LAS bf16x8*)((LAS char*)SB(b, h) + boff + n * 2048 + k * 1024)
; #define MMA(ai, bj, At_, Bt_) do { __builtin_amdgcn_s_setprio(1); \
;     _Pragma("unroll") for (int m = 0; m < 4; ++m) _Pragma("unroll") for (int n = 0; n < 2; ++n) _Pragma("unroll") for (int k = 0; k < 2; ++k) \
;       acc[ai][bj][m][n] = __builtin_amdgcn_mfma_f32_16x16x32_bf16(Bt_[n][k], At_[m][k], acc[ai][bj][m][n], 0, 0, 0); \
;     __builtin_amdgcn_s_setprio(0); } while (0)
; #define WAIT_L(n) asm volatile("s_waitcnt lgkmcnt(" #n ")" ::: "memory")
; #define BAR __builtin_amdgcn_s_barrier()
; #define SCHED __builtin_amdgcn_sched_barrier(0)
; __device__ __forceinline__ void gemm_phase(const bf16_t* __restrict__ A, const bf16_t* __restrict__ Bt, bf16_t* __restrict__ C, int M, int N, int K,
;                                            int ldc, const int EPI, char* smem, const int wid_u) {
;     ...
;     const bool has_next = gemm_unit(ui + 1, nM, nN, nwg, npm, npn);
;     const char* nA = has_next ? (const char*)A + (size_t)npm * tstep : cA;
;     const char* nB = has_next ? (const char*)Bt + (size_t)npn * tstep : cB;
;     for (int t = 0; t < nt; t += 2) {
;       const bool last = (t == nt - 2);
;       const char* a1 = cA + (size_t)(t + 1) * kstep;
;       const char* a2 = last ? nA : cA + (size_t)(t + 2) * kstep;
;       const char* b2 = last ? nB : cB + (size_t)(t + 2) * kstep;
;       const char* a3 = a2 + kstep;
;       const char* b3 = b2 + kstep;
;       LDB(B0, 0, 0); SCHED; LDA(At, 0, 0); STG(SA(1, 1), a1 + hstep);
;       WAIT_L(8); BAR; WAIT_L(0); MMA(0, 0, At, B0); BAR; SCHED;
;       LDB(B1, 0, 1); STG(SB(0, 0), b2);
;       BAR; WAIT_L(0); MMA(0, 1, At, B1); BAR;
;       LDA(At, 0, 1); STG(SA(0, 0), a2);
;       BAR; WAIT_L(0); MMA(1, 0, At, B0); BAR; SCHED;
.LBB0_1026:
	ds_read_b128 v[150:153], v146
	ds_read_b128 v[154:157], v146 offset:1024
	ds_read_b128 v[158:161], v146 offset:2048
	ds_read_b128 v[162:165], v146 offset:3072
	s_add_u32 s20, s18, 0x100
	s_addc_u32 s21, s19, 0
	s_cmp_eq_u32 s53, 12
	s_cselect_b32 s25, s48, s21
	s_cselect_b32 s24, s49, s20
	s_cselect_b32 s23, s13, s52
	s_cselect_b32 s22, s50, s51
	v_lshl_add_u64 v[142:143], s[18:19], 0, v[136:137]
	s_add_i32 m0, s34, 0xc000
	ds_read_b128 v[166:169], v147
	ds_read_b128 v[170:173], v147 offset:1024
	ds_read_b128 v[174:177], v147 offset:2048
	ds_read_b128 v[178:181], v147 offset:3072
	ds_read_b128 v[182:185], v147 offset:4096
	ds_read_b128 v[186:189], v147 offset:5120
	ds_read_b128 v[190:193], v147 offset:6144
	ds_read_b128 v[194:197], v147 offset:7168
	global_load_lds_dwordx4 v[142:143], off
	v_lshl_add_u64 v[142:143], s[18:19], 0, v[134:135]
	s_add_i32 m0, s34, 0xe000
	s_nop 0
	global_load_lds_dwordx4 v[142:143], off
	s_waitcnt vmcnt(10)
	s_waitcnt lgkmcnt(8)
	s_barrier
	s_waitcnt lgkmcnt(0)
	s_waitcnt lgkmcnt(0)
	v_mfma_f32_16x16x32_bf16 v[124:127], v[150:153], v[166:169], v[124:127]
	v_mfma_f32_16x16x32_bf16 v[120:123], v[158:161], v[166:169], v[120:123]
	v_mfma_f32_16x16x32_bf16 v[108:111], v[150:153], v[174:177], v[108:111]
	v_mfma_f32_16x16x32_bf16 v[104:107], v[158:161], v[174:177], v[104:107]
	v_mfma_f32_16x16x32_bf16 v[92:95], v[150:153], v[182:185], v[92:95]
	v_mfma_f32_16x16x32_bf16 v[88:91], v[158:161], v[182:185], v[88:91]
	v_mfma_f32_16x16x32_bf16 v[76:79], v[150:153], v[190:193], v[76:79]
	v_mfma_f32_16x16x32_bf16 v[72:75], v[158:161], v[190:193], v[72:75]
	v_mfma_f32_16x16x32_bf16 v[124:127], v[154:157], v[170:173], v[124:127]
	v_mfma_f32_16x16x32_bf16 v[120:123], v[162:165], v[170:173], v[120:123]
	v_mfma_f32_16x16x32_bf16 v[108:111], v[154:157], v[178:181], v[108:111]
	v_mfma_f32_16x16x32_bf16 v[104:107], v[162:165], v[178:181], v[104:107]
	v_mfma_f32_16x16x32_bf16 v[92:95], v[154:157], v[186:189], v[92:95]
	v_mfma_f32_16x16x32_bf16 v[88:91], v[162:165], v[186:189], v[88:91]
	v_mfma_f32_16x16x32_bf16 v[76:79], v[154:157], v[194:197], v[76:79]
	v_mfma_f32_16x16x32_bf16 v[72:75], v[162:165], v[194:197], v[72:75]
	s_barrier
	s_add_i32 s18, s40, s31
	v_lshl_add_u64 v[142:143], s[22:23], 0, v[130:131]
	s_mov_b32 m0, s18
	ds_read_b128 v[198:201], v148
	ds_read_b128 v[202:205], v148 offset:1024
	ds_read_b128 v[206:209], v148 offset:2048
	ds_read_b128 v[210:213], v148 offset:3072
	global_load_lds_dwordx4 v[142:143], off
	v_lshl_add_u64 v[214:215], s[22:23], 0, v[128:129]
	s_add_i32 m0, s18, 0x2000
	s_nop 0
	global_load_lds_dwordx4 v[214:215], off
	s_waitcnt vmcnt(10)
	s_barrier
	s_waitcnt lgkmcnt(0)
	s_waitcnt lgkmcnt(0)
	v_mfma_f32_16x16x32_bf16 v[116:119], v[198:201], v[166:169], v[116:119]
	v_mfma_f32_16x16x32_bf16 v[112:115], v[206:209], v[166:169], v[112:115]
	v_mfma_f32_16x16x32_bf16 v[100:103], v[198:201], v[174:177], v[100:103]
	v_mfma_f32_16x16x32_bf16 v[96:99], v[206:209], v[174:177], v[96:99]
	v_mfma_f32_16x16x32_bf16 v[84:87], v[198:201], v[182:185], v[84:87]
	v_mfma_f32_16x16x32_bf16 v[80:83], v[206:209], v[182:185], v[80:83]
	v_mfma_f32_16x16x32_bf16 v[68:71], v[198:201], v[190:193], v[68:71]
	v_mfma_f32_16x16x32_bf16 v[64:67], v[206:209], v[190:193], v[64:67]
	v_mfma_f32_16x16x32_bf16 v[116:119], v[202:205], v[170:173], v[116:119]
	v_mfma_f32_16x16x32_bf16 v[112:115], v[210:213], v[170:173], v[112:115]
	v_mfma_f32_16x16x32_bf16 v[100:103], v[202:205], v[178:181], v[100:103]
	v_mfma_f32_16x16x32_bf16 v[96:99], v[210:213], v[178:181], v[96:99]
	v_mfma_f32_16x16x32_bf16 v[84:87], v[202:205], v[186:189], v[84:87]
	v_mfma_f32_16x16x32_bf16 v[80:83], v[210:213], v[186:189], v[80:83]
	v_mfma_f32_16x16x32_bf16 v[68:71], v[202:205], v[194:197], v[68:71]
	v_mfma_f32_16x16x32_bf16 v[64:67], v[210:213], v[194:197], v[64:67]
	s_mov_b32 m0, s34
	v_lshl_add_u64 v[216:217], s[24:25], 0, v[130:131]
	s_barrier
	ds_read_b128 v[166:169], v147 offset:16384
	ds_read_b128 v[170:173], v147 offset:17408
	ds_read_b128 v[174:177], v147 offset:18432
	ds_read_b128 v[178:181], v147 offset:19456
	ds_read_b128 v[182:185], v147 offset:20480
	ds_read_b128 v[186:189], v147 offset:21504
	ds_read_b128 v[190:193], v147 offset:22528
	ds_read_b128 v[194:197], v147 offset:23552
	global_load_lds_dwordx4 v[216:217], off
	v_lshl_add_u64 v[218:219], s[24:25], 0, v[128:129]
	s_mov_b32 m0, s35
	s_nop 0
	global_load_lds_dwordx4 v[218:219], off
	s_barrier
	s_waitcnt lgkmcnt(0)
	s_waitcnt lgkmcnt(0)
	v_mfma_f32_16x16x32_bf16 v[60:63], v[150:153], v[166:169], v[60:63]
	v_mfma_f32_16x16x32_bf16 v[56:59], v[158:161], v[166:169], v[56:59]
	v_mfma_f32_16x16x32_bf16 v[44:47], v[150:153], v[174:177], v[44:47]
	v_mfma_f32_16x16x32_bf16 v[40:43], v[158:161], v[174:177], v[40:43]
	v_mfma_f32_16x16x32_bf16 v[28:31], v[150:153], v[182:185], v[28:31]
	v_mfma_f32_16x16x32_bf16 v[24:27], v[158:161], v[182:185], v[24:27]
	v_mfma_f32_16x16x32_bf16 v[12:15], v[150:153], v[190:193], v[12:15]
	v_mfma_f32_16x16x32_bf16 v[8:11], v[158:161], v[190:193], v[8:11]
	v_mfma_f32_16x16x32_bf16 v[60:63], v[154:157], v[170:173], v[60:63]
	v_mfma_f32_16x16x32_bf16 v[56:59], v[162:165], v[170:173], v[56:59]
	v_mfma_f32_16x16x32_bf16 v[44:47], v[154:157], v[178:181], v[44:47]
	v_mfma_f32_16x16x32_bf16 v[40:43], v[162:165], v[178:181], v[40:43]
	v_mfma_f32_16x16x32_bf16 v[28:31], v[154:157], v[186:189], v[28:31]
	v_mfma_f32_16x16x32_bf16 v[24:27], v[162:165], v[186:189], v[24:27]
	v_mfma_f32_16x16x32_bf16 v[12:15], v[154:157], v[194:197], v[12:15]
	v_mfma_f32_16x16x32_bf16 v[8:11], v[162:165], v[194:197], v[8:11]
	s_barrier
; #define STG(P, GB) do { const char* _gb = (GB); \
;     _Pragma("unroll") for (int _i = 0; _i < 2; ++_i) { \
;       __builtin_amdgcn_global_load_lds((const unsigned*)(_gb + voff[_i]), \
;         (LAS unsigned*)((LAS char*)(P) + ldsw + _i * 8192), 16, 0, 0); } } while (0)
; #define LDA(dst, b, h) _Pragma("unroll") for (int m = 0; m < 4; ++m) _Pragma("unroll") for (int k = 0; k < 2; ++k) \
;     dst[m][k] = *(const LAS bf16x8*)((LAS char*)SA(b, h) + aoff + m * 2048 + k * 1024)
; #define LDB(dst, b, h) _Pragma("unroll") for (int n = 0; n < 2; ++n) _Pragma("unroll") for (int k = 0; k < 2; ++k) \
;     dst[n][k] = *(const LAS bf16x8*)((LAS char*)SB(b, h) + boff + n * 2048 + k * 1024)
; #define MMA(ai, bj, At_, Bt_) do { __builtin_amdgcn_s_setprio(1); \
;     _Pragma("unroll") for (int m = 0; m < 4; ++m) _Pragma("unroll") for (int n = 0; n < 2; ++n) _Pragma("unroll") for (int k = 0; k < 2; ++k) \
;       acc[ai][bj][m][n] = __builtin_amdgcn_mfma_f32_16x16x32_bf16(Bt_[n][k], At_[m][k], acc[ai][bj][m][n], 0, 0, 0); \
;     __builtin_amdgcn_s_setprio(0); } while (0)
; #define WAIT_V(n) asm volatile("s_waitcnt vmcnt(" #n ")" ::: "memory")
; #define WAIT_L(n) asm volatile("s_waitcnt lgkmcnt(" #n ")" ::: "memory")
; #define BAR __builtin_amdgcn_s_barrier()
; #define SCHED __builtin_amdgcn_sched_barrier(0)
; __device__ __forceinline__ void gemm_phase(const bf16_t* __restrict__ A, const bf16_t* __restrict__ Bt, bf16_t* __restrict__ C, int M, int N, int K,
;                                            int ldc, const int EPI, char* smem, const int wid_u) {
;     ...
;       STG(SB(0, 1), b2 + hstep);
;       WAIT_V(6); BAR; MMA(1, 1, At, B1); BAR;
;       LDB(B0, 1, 0); SCHED; LDA(At, 1, 0); STG(SA(0, 1), a2 + hstep);
;       WAIT_L(8); BAR; WAIT_L(0); MMA(0, 0, At, B0); BAR; SCHED;
;       LDB(B1, 1, 1); STG(SB(1, 0), b3);
;       BAR; WAIT_L(0); MMA(0, 1, At, B1); BAR;
;       LDA(At, 1, 1); STG(SA(1, 0), a3);
	s_add_u32 s18, s22, 0x40000
	s_addc_u32 s19, s23, 0
	s_add_i32 s54, s41, s31
	v_lshl_add_u64 v[150:151], s[18:19], 0, v[130:131]
	s_mov_b32 m0, s54
	s_nop 0
	global_load_lds_dwordx4 v[150:151], off
	v_lshl_add_u64 v[150:151], s[18:19], 0, v[128:129]
	s_add_i32 m0, s54, 0x2000
	s_nop 0
	global_load_lds_dwordx4 v[150:151], off
	s_waitcnt vmcnt(10)
	s_barrier
	v_mfma_f32_16x16x32_bf16 v[52:55], v[198:201], v[166:169], v[52:55]
	v_mfma_f32_16x16x32_bf16 v[48:51], v[206:209], v[166:169], v[48:51]
	v_mfma_f32_16x16x32_bf16 v[36:39], v[198:201], v[174:177], v[36:39]
	v_mfma_f32_16x16x32_bf16 v[32:35], v[206:209], v[174:177], v[32:35]
	v_mfma_f32_16x16x32_bf16 v[20:23], v[198:201], v[182:185], v[20:23]
	v_mfma_f32_16x16x32_bf16 v[16:19], v[206:209], v[182:185], v[16:19]
	v_mfma_f32_16x16x32_bf16 v[4:7], v[198:201], v[190:193], v[4:7]
	v_mfma_f32_16x16x32_bf16 v[0:3], v[206:209], v[190:193], v[0:3]
	v_mfma_f32_16x16x32_bf16 v[52:55], v[202:205], v[170:173], v[52:55]
	v_mfma_f32_16x16x32_bf16 v[48:51], v[210:213], v[170:173], v[48:51]
	v_mfma_f32_16x16x32_bf16 v[36:39], v[202:205], v[178:181], v[36:39]
	v_mfma_f32_16x16x32_bf16 v[32:35], v[210:213], v[178:181], v[32:35]
	v_mfma_f32_16x16x32_bf16 v[20:23], v[202:205], v[186:189], v[20:23]
	v_mfma_f32_16x16x32_bf16 v[16:19], v[210:213], v[186:189], v[16:19]
	v_mfma_f32_16x16x32_bf16 v[4:7], v[202:205], v[194:197], v[4:7]
	v_mfma_f32_16x16x32_bf16 v[0:3], v[210:213], v[194:197], v[0:3]
	s_add_i32 s54, 0, 0x18000
	v_add_u32_e32 v149, s54, v145
	s_barrier
	ds_read_b128 v[150:153], v149
	ds_read_b128 v[154:157], v149 offset:1024
	ds_read_b128 v[158:161], v149 offset:2048
	ds_read_b128 v[162:165], v149 offset:3072
	s_add_u32 s18, s24, 0x40000
	s_addc_u32 s19, s25, 0
	s_mov_b32 m0, s36
	v_lshl_add_u64 v[198:199], s[18:19], 0, v[130:131]
	ds_read_b128 v[166:169], v147 offset:32768
	ds_read_b128 v[170:173], v147 offset:33792
	ds_read_b128 v[174:177], v147 offset:34816
	ds_read_b128 v[178:181], v147 offset:35840
	ds_read_b128 v[182:185], v147 offset:36864
	ds_read_b128 v[186:189], v147 offset:37888
	ds_read_b128 v[190:193], v147 offset:38912
	ds_read_b128 v[194:197], v147 offset:39936
	global_load_lds_dwordx4 v[198:199], off
	v_lshl_add_u64 v[198:199], s[18:19], 0, v[128:129]
	s_mov_b32 m0, s37
	s_nop 0
	global_load_lds_dwordx4 v[198:199], off
	s_waitcnt vmcnt(10)
	s_waitcnt lgkmcnt(8)
	s_barrier
	s_waitcnt lgkmcnt(0)
	s_waitcnt lgkmcnt(0)
	v_mfma_f32_16x16x32_bf16 v[124:127], v[150:153], v[166:169], v[124:127]
	v_mfma_f32_16x16x32_bf16 v[120:123], v[158:161], v[166:169], v[120:123]
	v_mfma_f32_16x16x32_bf16 v[108:111], v[150:153], v[174:177], v[108:111]
	v_mfma_f32_16x16x32_bf16 v[104:107], v[158:161], v[174:177], v[104:107]
	v_mfma_f32_16x16x32_bf16 v[92:95], v[150:153], v[182:185], v[92:95]
	v_mfma_f32_16x16x32_bf16 v[88:91], v[158:161], v[182:185], v[88:91]
	v_mfma_f32_16x16x32_bf16 v[76:79], v[150:153], v[190:193], v[76:79]
	v_mfma_f32_16x16x32_bf16 v[72:75], v[158:161], v[190:193], v[72:75]
	v_mfma_f32_16x16x32_bf16 v[124:127], v[154:157], v[170:173], v[124:127]
	v_mfma_f32_16x16x32_bf16 v[120:123], v[162:165], v[170:173], v[120:123]
	v_mfma_f32_16x16x32_bf16 v[108:111], v[154:157], v[178:181], v[108:111]
	v_mfma_f32_16x16x32_bf16 v[104:107], v[162:165], v[178:181], v[104:107]
	v_mfma_f32_16x16x32_bf16 v[92:95], v[154:157], v[186:189], v[92:95]
	v_mfma_f32_16x16x32_bf16 v[88:91], v[162:165], v[186:189], v[88:91]
	v_mfma_f32_16x16x32_bf16 v[76:79], v[154:157], v[194:197], v[76:79]
	v_mfma_f32_16x16x32_bf16 v[72:75], v[162:165], v[194:197], v[72:75]
	s_barrier
	s_add_i32 s24, 0, 0x1c000
	s_add_i32 s18, s54, s31
	v_add_u32_e32 v149, s24, v145
	v_lshl_add_u64 v[142:143], v[142:143], 0, s[10:11]
	s_mov_b32 m0, s18
	ds_read_b128 v[198:201], v149
	ds_read_b128 v[202:205], v149 offset:1024
	ds_read_b128 v[206:209], v149 offset:2048
	ds_read_b128 v[210:213], v149 offset:3072
	global_load_lds_dwordx4 v[142:143], off
	v_lshl_add_u64 v[142:143], v[214:215], 0, s[10:11]
	s_add_i32 m0, s18, 0x2000
	s_nop 0
	global_load_lds_dwordx4 v[142:143], off
	s_waitcnt vmcnt(10)
	s_barrier
	s_waitcnt lgkmcnt(0)
	s_waitcnt lgkmcnt(0)
	v_mfma_f32_16x16x32_bf16 v[116:119], v[198:201], v[166:169], v[116:119]
	v_mfma_f32_16x16x32_bf16 v[112:115], v[206:209], v[166:169], v[112:115]
	v_mfma_f32_16x16x32_bf16 v[100:103], v[198:201], v[174:177], v[100:103]
	v_mfma_f32_16x16x32_bf16 v[96:99], v[206:209], v[174:177], v[96:99]
	v_mfma_f32_16x16x32_bf16 v[84:87], v[198:201], v[182:185], v[84:87]
	v_mfma_f32_16x16x32_bf16 v[80:83], v[206:209], v[182:185], v[80:83]
	v_mfma_f32_16x16x32_bf16 v[68:71], v[198:201], v[190:193], v[68:71]
	v_mfma_f32_16x16x32_bf16 v[64:67], v[206:209], v[190:193], v[64:67]
	v_mfma_f32_16x16x32_bf16 v[116:119], v[202:205], v[170:173], v[116:119]
	v_mfma_f32_16x16x32_bf16 v[112:115], v[210:213], v[170:173], v[112:115]
	v_mfma_f32_16x16x32_bf16 v[100:103], v[202:205], v[178:181], v[100:103]
	v_mfma_f32_16x16x32_bf16 v[96:99], v[210:213], v[178:181], v[96:99]
	v_mfma_f32_16x16x32_bf16 v[84:87], v[202:205], v[186:189], v[84:87]
	v_mfma_f32_16x16x32_bf16 v[80:83], v[210:213], v[186:189], v[80:83]
	v_mfma_f32_16x16x32_bf16 v[68:71], v[202:205], v[194:197], v[68:71]
	v_mfma_f32_16x16x32_bf16 v[64:67], v[210:213], v[194:197], v[64:67]
	s_mov_b32 m0, s38
	v_lshl_add_u64 v[142:143], v[216:217], 0, s[10:11]
	s_barrier
	ds_read_b128 v[166:169], v147 offset:49152
	ds_read_b128 v[170:173], v147 offset:50176
	ds_read_b128 v[174:177], v147 offset:51200
	ds_read_b128 v[178:181], v147 offset:52224
	ds_read_b128 v[182:185], v147 offset:53248
	ds_read_b128 v[186:189], v147 offset:54272
	ds_read_b128 v[190:193], v147 offset:55296
	ds_read_b128 v[194:197], v147 offset:56320
	global_load_lds_dwordx4 v[142:143], off
	v_lshl_add_u64 v[142:143], v[218:219], 0, s[10:11]
	s_mov_b32 m0, s39
	s_nop 0
	global_load_lds_dwordx4 v[142:143], off
	s_barrier
; #define STG(P, GB) do { const char* _gb = (GB); \
;     _Pragma("unroll") for (int _i = 0; _i < 2; ++_i) { \
;       __builtin_amdgcn_global_load_lds((const unsigned*)(_gb + voff[_i]), \
;         (LAS unsigned*)((LAS char*)(P) + ldsw + _i * 8192), 16, 0, 0); } } while (0)
; #define MMA(ai, bj, At_, Bt_) do { __builtin_amdgcn_s_setprio(1); \
;     _Pragma("unroll") for (int m = 0; m < 4; ++m) _Pragma("unroll") for (int n = 0; n < 2; ++n) _Pragma("unroll") for (int k = 0; k < 2; ++k) \
;       acc[ai][bj][m][n] = __builtin_amdgcn_mfma_f32_16x16x32_bf16(Bt_[n][k], At_[m][k], acc[ai][bj][m][n], 0, 0, 0); \
;     __builtin_amdgcn_s_setprio(0); } while (0)
; #define WAIT_V(n) asm volatile("s_waitcnt vmcnt(" #n ")" ::: "memory")
; #define WAIT_L(n) asm volatile("s_waitcnt lgkmcnt(" #n ")" ::: "memory")
; #define BAR __builtin_amdgcn_s_barrier()
; #define SCHED __builtin_amdgcn_sched_barrier(0)
; __device__ __forceinline__ void gemm_phase(const bf16_t* __restrict__ A, const bf16_t* __restrict__ Bt, bf16_t* __restrict__ C, int M, int N, int K,
;                                            int ldc, const int EPI, char* smem, const int wid_u) {
;     ...
;       BAR; WAIT_L(0); MMA(1, 0, At, B0); BAR; SCHED;
;       STG(SB(1, 1), b3 + hstep);
;       WAIT_V(6); BAR; MMA(1, 1, At, B1); BAR;
;     }
;     {
;       const int brow = pm * BM, bcol = pn * BM;
; #pragma unroll
;       for (int ai = 0; ai < 2; ++ai)
; #pragma unroll
;         for (int m = 0; m < 4; ++m) {
;           const size_t row = (size_t)(brow + ai * HALF + wr * 64 + m * 16 + fr);
;           if (EPI == 0) {
; #pragma unroll
;             for (int bj = 0; bj < 2; ++bj) {
;               const f32x4 v0 = acc[ai][bj][m][0], v1 = acc[ai][bj][m][1];
;               uint4 u; u.x = cvt_pk_bf16(v0[0], v0[1]); u.y = cvt_pk_bf16(v0[2], v0[3]); u.z = cvt_pk_bf16(v1[0], v1[1]); u.w = cvt_pk_bf16(v1[2], v1[3]);
;               *(uint4*)(C + row * ldc + bcol + bj * HALF + wc * 32 + fq * 8) = u;
;             }
;           } else {
;             float o[8];
; #pragma unroll
;             for (int n = 0; n < 2; ++n) {
;               const f32x4 a = acc[ai][0][m][n], b = acc[ai][1][m][n];
; #pragma unroll
;               for (int j = 0; j < 4; ++j) o[n * 4 + j] = a[j] * __builtin_amdgcn_rcpf(1.f + __expf(-a[j])) * b[j];
;             }
;             *(uint4*)(C + row * ldc + (bcol >> 1) + wc * 32 + fq * 8) = pack8(o);
	s_waitcnt lgkmcnt(0)
	s_waitcnt lgkmcnt(0)
	v_mfma_f32_16x16x32_bf16 v[60:63], v[150:153], v[166:169], v[60:63]
	v_mfma_f32_16x16x32_bf16 v[56:59], v[158:161], v[166:169], v[56:59]
	v_mfma_f32_16x16x32_bf16 v[44:47], v[150:153], v[174:177], v[44:47]
	v_mfma_f32_16x16x32_bf16 v[40:43], v[158:161], v[174:177], v[40:43]
	v_mfma_f32_16x16x32_bf16 v[28:31], v[150:153], v[182:185], v[28:31]
	v_mfma_f32_16x16x32_bf16 v[24:27], v[158:161], v[182:185], v[24:27]
	v_mfma_f32_16x16x32_bf16 v[12:15], v[150:153], v[190:193], v[12:15]
	v_mfma_f32_16x16x32_bf16 v[8:11], v[158:161], v[190:193], v[8:11]
	v_mfma_f32_16x16x32_bf16 v[60:63], v[154:157], v[170:173], v[60:63]
	v_mfma_f32_16x16x32_bf16 v[56:59], v[162:165], v[170:173], v[56:59]
	v_mfma_f32_16x16x32_bf16 v[44:47], v[154:157], v[178:181], v[44:47]
	v_mfma_f32_16x16x32_bf16 v[40:43], v[162:165], v[178:181], v[40:43]
	v_mfma_f32_16x16x32_bf16 v[28:31], v[154:157], v[186:189], v[28:31]
	v_mfma_f32_16x16x32_bf16 v[24:27], v[162:165], v[186:189], v[24:27]
	v_mfma_f32_16x16x32_bf16 v[12:15], v[154:157], v[194:197], v[12:15]
	v_mfma_f32_16x16x32_bf16 v[8:11], v[162:165], v[194:197], v[8:11]
	s_barrier
	s_add_u32 s18, s22, 0x40080
	s_addc_u32 s19, s23, 0
	s_add_i32 s22, s24, s31
	v_lshl_add_u64 v[142:143], s[18:19], 0, v[130:131]
	s_mov_b32 m0, s22
	s_nop 0
	global_load_lds_dwordx4 v[142:143], off
	v_lshl_add_u64 v[142:143], s[18:19], 0, v[128:129]
	s_add_i32 m0, s22, 0x2000
	s_nop 0
	global_load_lds_dwordx4 v[142:143], off
	s_waitcnt vmcnt(10)
	s_barrier
	v_mfma_f32_16x16x32_bf16 v[52:55], v[198:201], v[166:169], v[52:55]
	v_mfma_f32_16x16x32_bf16 v[48:51], v[206:209], v[166:169], v[48:51]
	v_mfma_f32_16x16x32_bf16 v[36:39], v[198:201], v[174:177], v[36:39]
	v_mfma_f32_16x16x32_bf16 v[32:35], v[206:209], v[174:177], v[32:35]
	v_mfma_f32_16x16x32_bf16 v[20:23], v[198:201], v[182:185], v[20:23]
	v_mfma_f32_16x16x32_bf16 v[16:19], v[206:209], v[182:185], v[16:19]
	v_mfma_f32_16x16x32_bf16 v[4:7], v[198:201], v[190:193], v[4:7]
	v_mfma_f32_16x16x32_bf16 v[0:3], v[206:209], v[190:193], v[0:3]
	v_mfma_f32_16x16x32_bf16 v[52:55], v[202:205], v[170:173], v[52:55]
	v_mfma_f32_16x16x32_bf16 v[48:51], v[210:213], v[170:173], v[48:51]
	v_mfma_f32_16x16x32_bf16 v[36:39], v[202:205], v[178:181], v[36:39]
	v_mfma_f32_16x16x32_bf16 v[32:35], v[210:213], v[178:181], v[32:35]
	v_mfma_f32_16x16x32_bf16 v[20:23], v[202:205], v[186:189], v[20:23]
	v_mfma_f32_16x16x32_bf16 v[16:19], v[210:213], v[186:189], v[16:19]
	v_mfma_f32_16x16x32_bf16 v[4:7], v[202:205], v[194:197], v[4:7]
	v_mfma_f32_16x16x32_bf16 v[0:3], v[210:213], v[194:197], v[0:3]
	s_add_i32 s53, s53, 2
	s_add_u32 s51, s51, 0x100
	s_addc_u32 s52, s52, 0
	s_cmp_gt_u32 s53, 13
	s_mov_b64 s[18:19], s[20:21]
	s_barrier
	s_cbranch_scc0 .LBB0_1026
	v_mul_f32_e32 v142, 0xbfb8aa3b, v124
	v_exp_f32_e32 v142, v142
	v_mul_f32_e32 v143, 0xbfb8aa3b, v125
	v_exp_f32_e32 v143, v143
	s_lshl_b32 s18, s46, 8
	v_add_f32_e32 v142, 1.0, v142
	v_rcp_f32_e32 v150, v142
	v_add_f32_e32 v142, 1.0, v143
	v_rcp_f32_e32 v151, v142
	s_mov_b32 s19, s9
	v_lshl_add_u32 v149, s47, 8, v144
	v_lshl_add_u64 v[142:143], v[132:133], 0, s[18:19]
	v_pk_mul_f32 v[124:125], v[124:125], v[150:151]
	v_mul_f32_e32 v150, 0xbfb8aa3b, v126
	v_mul_f32_e32 v151, 0xbfb8aa3b, v127
	v_exp_f32_e32 v150, v150
	v_exp_f32_e32 v151, v151
	v_pk_mul_f32 v[116:117], v[124:125], v[116:117]
	s_and_b64 vcc, exec, s[4:5]
	v_add_f32_e32 v124, 1.0, v150
	v_add_f32_e32 v125, 1.0, v151
	v_mul_f32_e32 v150, 0xbfb8aa3b, v120
	v_mul_f32_e32 v151, 0xbfb8aa3b, v121
	v_rcp_f32_e32 v124, v124
	v_rcp_f32_e32 v125, v125
	v_exp_f32_e32 v150, v150
	v_exp_f32_e32 v151, v151
	s_mov_b32 s47, s8
	v_pk_mul_f32 v[124:125], v[126:127], v[124:125]
	v_add_f32_e32 v126, 1.0, v150
	v_add_f32_e32 v127, 1.0, v151
	v_mul_f32_e32 v150, 0xbfb8aa3b, v122
	v_mul_f32_e32 v151, 0xbfb8aa3b, v123
	v_exp_f32_e32 v150, v150
	v_exp_f32_e32 v151, v151
	v_rcp_f32_e32 v126, v126
	v_rcp_f32_e32 v127, v127
	v_add_f32_e32 v150, 1.0, v150
	v_add_f32_e32 v151, 1.0, v151
	v_rcp_f32_e32 v150, v150
	v_rcp_f32_e32 v151, v151
	v_pk_mul_f32 v[120:121], v[120:121], v[126:127]
	v_pk_mul_f32 v[118:119], v[124:125], v[118:119]
	v_pk_mul_f32 v[120:121], v[120:121], v[112:113]
	v_pk_mul_f32 v[112:113], v[122:123], v[150:151]
	s_mov_b32 s46, s12
	v_pk_mul_f32 v[122:123], v[112:113], v[114:115]
	v_mul_f32_e32 v115, 0xbfb8aa3b, v108
	v_cvt_pk_bf16_f32 v112, v116, v117
	v_exp_f32_e32 v116, v115
	v_mul_f32_e32 v115, 0xbfb8aa3b, v109
	v_exp_f32_e32 v117, v115
	v_cvt_pk_bf16_f32 v113, v118, v119
	v_cvt_pk_bf16_f32 v114, v120, v121
	v_cvt_pk_bf16_f32 v115, v122, v123
	v_add_f32_e32 v116, 1.0, v116
	v_add_f32_e32 v117, 1.0, v117
	v_mad_i64_i32 v[118:119], s[18:19], v149, s44, v[142:143]
	v_rcp_f32_e32 v116, v116
	v_rcp_f32_e32 v117, v117
	global_store_dwordx4 v[118:119], v[112:115], off
	s_mov_b64 s[20:21], s[16:17]
	v_pk_mul_f32 v[108:109], v[108:109], v[116:117]
	v_mul_f32_e32 v112, 0xbfb8aa3b, v110
	v_mul_f32_e32 v113, 0xbfb8aa3b, v111
	v_exp_f32_e32 v112, v112
	v_exp_f32_e32 v113, v113
	v_pk_mul_f32 v[100:101], v[108:109], v[100:101]
	v_or_b32_e32 v114, 16, v149
	v_add_f32_e32 v108, 1.0, v112
	v_add_f32_e32 v109, 1.0, v113
	v_mul_f32_e32 v112, 0xbfb8aa3b, v104
	v_mul_f32_e32 v113, 0xbfb8aa3b, v105
	v_rcp_f32_e32 v108, v108
	v_rcp_f32_e32 v109, v109
	v_exp_f32_e32 v112, v112
	v_exp_f32_e32 v113, v113
	v_pk_mul_f32 v[108:109], v[110:111], v[108:109]
	v_add_f32_e32 v110, 1.0, v112
	v_add_f32_e32 v111, 1.0, v113
	v_mul_f32_e32 v112, 0xbfb8aa3b, v106
	v_mul_f32_e32 v113, 0xbfb8aa3b, v107
	v_exp_f32_e32 v112, v112
	v_exp_f32_e32 v113, v113
	v_rcp_f32_e32 v110, v110
	v_rcp_f32_e32 v111, v111
; __device__ __forceinline__ void gemm_phase(const bf16_t* __restrict__ A, const bf16_t* __restrict__ Bt, bf16_t* __restrict__ C, int M, int N, int K,
;                                            int ldc, const int EPI, char* smem, const int wid_u) {
;     ...
;           } else {
;             float o[8];
; #pragma unroll
;             for (int n = 0; n < 2; ++n) {
;               const f32x4 a = acc[ai][0][m][n], b = acc[ai][1][m][n];
; #pragma unroll
;               for (int j = 0; j < 4; ++j) o[n * 4 + j] = a[j] * __builtin_amdgcn_rcpf(1.f + __expf(-a[j])) * b[j];
;             }
;             *(uint4*)(C + row * ldc + (bcol >> 1) + wc * 32 + fq * 8) = pack8(o);
	v_add_f32_e32 v112, 1.0, v112
	v_add_f32_e32 v113, 1.0, v113
	v_rcp_f32_e32 v112, v112
	v_rcp_f32_e32 v113, v113
	v_pk_mul_f32 v[104:105], v[104:105], v[110:111]
	v_pk_mul_f32 v[102:103], v[108:109], v[102:103]
	v_pk_mul_f32 v[104:105], v[104:105], v[96:97]
	v_pk_mul_f32 v[96:97], v[106:107], v[112:113]
	s_nop 0
	v_pk_mul_f32 v[106:107], v[96:97], v[98:99]
	v_mul_f32_e32 v99, 0xbfb8aa3b, v92
	v_cvt_pk_bf16_f32 v96, v100, v101
	v_exp_f32_e32 v100, v99
	v_mul_f32_e32 v99, 0xbfb8aa3b, v93
	v_exp_f32_e32 v101, v99
	v_cvt_pk_bf16_f32 v97, v102, v103
	v_cvt_pk_bf16_f32 v98, v104, v105
	v_cvt_pk_bf16_f32 v99, v106, v107
	v_add_f32_e32 v100, 1.0, v100
	v_add_f32_e32 v101, 1.0, v101
	v_mad_i64_i32 v[102:103], s[18:19], v114, s44, v[142:143]
	v_rcp_f32_e32 v100, v100
	v_rcp_f32_e32 v101, v101
	global_store_dwordx4 v[102:103], v[96:99], off
	v_pk_mul_f32 v[92:93], v[92:93], v[100:101]
	s_nop 0
	v_mul_f32_e32 v96, 0xbfb8aa3b, v94
	v_mul_f32_e32 v97, 0xbfb8aa3b, v95
	v_exp_f32_e32 v96, v96
	v_exp_f32_e32 v97, v97
	v_pk_mul_f32 v[84:85], v[92:93], v[84:85]
	v_or_b32_e32 v98, 32, v149
	v_add_f32_e32 v92, 1.0, v96
	v_add_f32_e32 v93, 1.0, v97
	v_mul_f32_e32 v96, 0xbfb8aa3b, v88
	v_mul_f32_e32 v97, 0xbfb8aa3b, v89
	v_rcp_f32_e32 v92, v92
	v_rcp_f32_e32 v93, v93
	v_exp_f32_e32 v96, v96
	v_exp_f32_e32 v97, v97
	v_pk_mul_f32 v[92:93], v[94:95], v[92:93]
	v_add_f32_e32 v94, 1.0, v96
	v_add_f32_e32 v95, 1.0, v97
	v_mul_f32_e32 v96, 0xbfb8aa3b, v90
	v_mul_f32_e32 v97, 0xbfb8aa3b, v91
	v_exp_f32_e32 v96, v96
	v_exp_f32_e32 v97, v97
	v_rcp_f32_e32 v94, v94
	v_rcp_f32_e32 v95, v95
	v_add_f32_e32 v96, 1.0, v96
	v_add_f32_e32 v97, 1.0, v97
	v_rcp_f32_e32 v96, v96
	v_rcp_f32_e32 v97, v97
	v_pk_mul_f32 v[88:89], v[88:89], v[94:95]
	v_pk_mul_f32 v[86:87], v[92:93], v[86:87]
	v_pk_mul_f32 v[88:89], v[88:89], v[80:81]
	v_pk_mul_f32 v[80:81], v[90:91], v[96:97]
	s_nop 0
	v_pk_mul_f32 v[90:91], v[80:81], v[82:83]
	v_mul_f32_e32 v83, 0xbfb8aa3b, v76
	v_cvt_pk_bf16_f32 v80, v84, v85
	v_exp_f32_e32 v84, v83
	v_mul_f32_e32 v83, 0xbfb8aa3b, v77
	v_exp_f32_e32 v85, v83
	v_cvt_pk_bf16_f32 v81, v86, v87
	v_cvt_pk_bf16_f32 v82, v88, v89
	v_cvt_pk_bf16_f32 v83, v90, v91
	v_add_f32_e32 v84, 1.0, v84
	v_add_f32_e32 v85, 1.0, v85
	v_mad_i64_i32 v[86:87], s[18:19], v98, s44, v[142:143]
	v_rcp_f32_e32 v84, v84
	v_rcp_f32_e32 v85, v85
	global_store_dwordx4 v[86:87], v[80:83], off
	v_pk_mul_f32 v[76:77], v[76:77], v[84:85]
	s_nop 0
	v_mul_f32_e32 v80, 0xbfb8aa3b, v78
	v_mul_f32_e32 v81, 0xbfb8aa3b, v79
	v_exp_f32_e32 v80, v80
	v_exp_f32_e32 v81, v81
	v_pk_mul_f32 v[68:69], v[76:77], v[68:69]
	v_or_b32_e32 v82, 48, v149
	v_add_f32_e32 v76, 1.0, v80
	v_add_f32_e32 v77, 1.0, v81
	v_mul_f32_e32 v80, 0xbfb8aa3b, v72
	v_mul_f32_e32 v81, 0xbfb8aa3b, v73
	v_rcp_f32_e32 v76, v76
	v_rcp_f32_e32 v77, v77
	v_exp_f32_e32 v80, v80
	v_exp_f32_e32 v81, v81
	v_pk_mul_f32 v[76:77], v[78:79], v[76:77]
	v_add_f32_e32 v78, 1.0, v80
	v_add_f32_e32 v79, 1.0, v81
	v_mul_f32_e32 v80, 0xbfb8aa3b, v74
	v_mul_f32_e32 v81, 0xbfb8aa3b, v75
	v_exp_f32_e32 v80, v80
	v_exp_f32_e32 v81, v81
	v_rcp_f32_e32 v78, v78
	v_rcp_f32_e32 v79, v79
	v_add_f32_e32 v80, 1.0, v80
	v_add_f32_e32 v81, 1.0, v81
	v_rcp_f32_e32 v80, v80
	v_rcp_f32_e32 v81, v81
	v_pk_mul_f32 v[72:73], v[72:73], v[78:79]
	v_pk_mul_f32 v[70:71], v[76:77], v[70:71]
	v_pk_mul_f32 v[72:73], v[72:73], v[64:65]
	v_pk_mul_f32 v[64:65], v[74:75], v[80:81]
	s_nop 0
	v_pk_mul_f32 v[74:75], v[64:65], v[66:67]
	v_mul_f32_e32 v67, 0xbfb8aa3b, v60
	v_cvt_pk_bf16_f32 v64, v68, v69
	v_exp_f32_e32 v68, v67
	v_mul_f32_e32 v67, 0xbfb8aa3b, v61
	v_exp_f32_e32 v69, v67
	v_cvt_pk_bf16_f32 v65, v70, v71
	v_cvt_pk_bf16_f32 v66, v72, v73
	v_cvt_pk_bf16_f32 v67, v74, v75
	v_add_f32_e32 v68, 1.0, v68
	v_add_f32_e32 v69, 1.0, v69
	v_mad_i64_i32 v[70:71], s[18:19], v82, s44, v[142:143]
	v_rcp_f32_e32 v68, v68
	v_rcp_f32_e32 v69, v69
	global_store_dwordx4 v[70:71], v[64:67], off
	v_pk_mul_f32 v[60:61], v[60:61], v[68:69]
	s_nop 0
	v_mul_f32_e32 v64, 0xbfb8aa3b, v62
	v_mul_f32_e32 v65, 0xbfb8aa3b, v63
	v_exp_f32_e32 v64, v64
	v_exp_f32_e32 v65, v65
	v_pk_mul_f32 v[52:53], v[60:61], v[52:53]
	v_add_u32_e32 v66, 0x80, v149
	v_add_f32_e32 v60, 1.0, v64
	v_add_f32_e32 v61, 1.0, v65
	v_mul_f32_e32 v64, 0xbfb8aa3b, v56
	v_mul_f32_e32 v65, 0xbfb8aa3b, v57
	v_rcp_f32_e32 v60, v60
	v_rcp_f32_e32 v61, v61
	v_exp_f32_e32 v64, v64
	v_exp_f32_e32 v65, v65
	v_pk_mul_f32 v[60:61], v[62:63], v[60:61]
	v_add_f32_e32 v62, 1.0, v64
	v_add_f32_e32 v63, 1.0, v65
	v_mul_f32_e32 v64, 0xbfb8aa3b, v58
	v_mul_f32_e32 v65, 0xbfb8aa3b, v59
	v_exp_f32_e32 v64, v64
	v_exp_f32_e32 v65, v65
	v_rcp_f32_e32 v62, v62
	v_rcp_f32_e32 v63, v63
	v_add_f32_e32 v64, 1.0, v64
	v_add_f32_e32 v65, 1.0, v65
	v_rcp_f32_e32 v64, v64
	v_rcp_f32_e32 v65, v65
	v_pk_mul_f32 v[56:57], v[56:57], v[62:63]
	v_pk_mul_f32 v[54:55], v[60:61], v[54:55]
	v_pk_mul_f32 v[56:57], v[56:57], v[48:49]
	v_pk_mul_f32 v[48:49], v[58:59], v[64:65]
	s_nop 0
; __device__ __forceinline__ void gemm_phase(const bf16_t* __restrict__ A, const bf16_t* __restrict__ Bt, bf16_t* __restrict__ C, int M, int N, int K,
;                                            int ldc, const int EPI, char* smem, const int wid_u) {
;     ...
;           } else {
;             float o[8];
; #pragma unroll
;             for (int n = 0; n < 2; ++n) {
;               const f32x4 a = acc[ai][0][m][n], b = acc[ai][1][m][n];
; #pragma unroll
;               for (int j = 0; j < 4; ++j) o[n * 4 + j] = a[j] * __builtin_amdgcn_rcpf(1.f + __expf(-a[j])) * b[j];
;             }
;             *(uint4*)(C + row * ldc + (bcol >> 1) + wc * 32 + fq * 8) = pack8(o);
;           }
;         }
;     }
;     if (!has_next) break;
	v_pk_mul_f32 v[58:59], v[48:49], v[50:51]
	v_mul_f32_e32 v51, 0xbfb8aa3b, v44
	v_cvt_pk_bf16_f32 v48, v52, v53
	v_exp_f32_e32 v52, v51
	v_mul_f32_e32 v51, 0xbfb8aa3b, v45
	v_exp_f32_e32 v53, v51
	v_cvt_pk_bf16_f32 v49, v54, v55
	v_cvt_pk_bf16_f32 v50, v56, v57
	v_cvt_pk_bf16_f32 v51, v58, v59
	v_add_f32_e32 v52, 1.0, v52
	v_add_f32_e32 v53, 1.0, v53
	v_mad_i64_i32 v[54:55], s[18:19], v66, s44, v[142:143]
	v_rcp_f32_e32 v52, v52
	v_rcp_f32_e32 v53, v53
	global_store_dwordx4 v[54:55], v[48:51], off
	v_pk_mul_f32 v[44:45], v[44:45], v[52:53]
	s_nop 0
	v_mul_f32_e32 v48, 0xbfb8aa3b, v46
	v_mul_f32_e32 v49, 0xbfb8aa3b, v47
	v_exp_f32_e32 v48, v48
	v_exp_f32_e32 v49, v49
	v_pk_mul_f32 v[36:37], v[44:45], v[36:37]
	v_add_u32_e32 v50, 0x90, v149
	v_add_f32_e32 v44, 1.0, v48
	v_add_f32_e32 v45, 1.0, v49
	v_mul_f32_e32 v48, 0xbfb8aa3b, v40
	v_mul_f32_e32 v49, 0xbfb8aa3b, v41
	v_rcp_f32_e32 v44, v44
	v_rcp_f32_e32 v45, v45
	v_exp_f32_e32 v48, v48
	v_exp_f32_e32 v49, v49
	v_pk_mul_f32 v[44:45], v[46:47], v[44:45]
	v_add_f32_e32 v46, 1.0, v48
	v_add_f32_e32 v47, 1.0, v49
	v_mul_f32_e32 v48, 0xbfb8aa3b, v42
	v_mul_f32_e32 v49, 0xbfb8aa3b, v43
	v_exp_f32_e32 v48, v48
	v_exp_f32_e32 v49, v49
	v_rcp_f32_e32 v46, v46
	v_rcp_f32_e32 v47, v47
	v_add_f32_e32 v48, 1.0, v48
	v_add_f32_e32 v49, 1.0, v49
	v_rcp_f32_e32 v48, v48
	v_rcp_f32_e32 v49, v49
	v_pk_mul_f32 v[40:41], v[40:41], v[46:47]
	v_pk_mul_f32 v[38:39], v[44:45], v[38:39]
	v_pk_mul_f32 v[40:41], v[40:41], v[32:33]
	v_pk_mul_f32 v[32:33], v[42:43], v[48:49]
	s_nop 0
	v_pk_mul_f32 v[42:43], v[32:33], v[34:35]
	v_mul_f32_e32 v35, 0xbfb8aa3b, v28
	v_cvt_pk_bf16_f32 v32, v36, v37
	v_exp_f32_e32 v36, v35
	v_mul_f32_e32 v35, 0xbfb8aa3b, v29
	v_exp_f32_e32 v37, v35
	v_cvt_pk_bf16_f32 v33, v38, v39
	v_cvt_pk_bf16_f32 v34, v40, v41
	v_cvt_pk_bf16_f32 v35, v42, v43
	v_add_f32_e32 v36, 1.0, v36
	v_add_f32_e32 v37, 1.0, v37
	v_mad_i64_i32 v[38:39], s[18:19], v50, s44, v[142:143]
	v_rcp_f32_e32 v36, v36
	v_rcp_f32_e32 v37, v37
	global_store_dwordx4 v[38:39], v[32:35], off
	v_pk_mul_f32 v[28:29], v[28:29], v[36:37]
	s_nop 0
	v_mul_f32_e32 v32, 0xbfb8aa3b, v30
	v_mul_f32_e32 v33, 0xbfb8aa3b, v31
	v_exp_f32_e32 v32, v32
	v_exp_f32_e32 v33, v33
	v_pk_mul_f32 v[20:21], v[28:29], v[20:21]
	v_add_u32_e32 v34, 0xa0, v149
	v_add_f32_e32 v28, 1.0, v32
	v_add_f32_e32 v29, 1.0, v33
	v_mul_f32_e32 v32, 0xbfb8aa3b, v24
	v_mul_f32_e32 v33, 0xbfb8aa3b, v25
	v_rcp_f32_e32 v28, v28
	v_rcp_f32_e32 v29, v29
	v_exp_f32_e32 v32, v32
	v_exp_f32_e32 v33, v33
	v_pk_mul_f32 v[28:29], v[30:31], v[28:29]
	v_add_f32_e32 v30, 1.0, v32
	v_add_f32_e32 v31, 1.0, v33
	v_mul_f32_e32 v32, 0xbfb8aa3b, v26
	v_mul_f32_e32 v33, 0xbfb8aa3b, v27
	v_exp_f32_e32 v32, v32
	v_exp_f32_e32 v33, v33
	v_rcp_f32_e32 v30, v30
	v_rcp_f32_e32 v31, v31
	v_add_f32_e32 v32, 1.0, v32
	v_add_f32_e32 v33, 1.0, v33
	v_rcp_f32_e32 v32, v32
	v_rcp_f32_e32 v33, v33
	v_pk_mul_f32 v[24:25], v[24:25], v[30:31]
	v_pk_mul_f32 v[22:23], v[28:29], v[22:23]
	v_pk_mul_f32 v[24:25], v[24:25], v[16:17]
	v_pk_mul_f32 v[16:17], v[26:27], v[32:33]
	s_nop 0
	v_pk_mul_f32 v[26:27], v[16:17], v[18:19]
	v_mul_f32_e32 v19, 0xbfb8aa3b, v12
	v_cvt_pk_bf16_f32 v16, v20, v21
	v_exp_f32_e32 v20, v19
	v_mul_f32_e32 v19, 0xbfb8aa3b, v13
	v_exp_f32_e32 v21, v19
	v_cvt_pk_bf16_f32 v17, v22, v23
	v_cvt_pk_bf16_f32 v18, v24, v25
	v_cvt_pk_bf16_f32 v19, v26, v27
	v_add_f32_e32 v20, 1.0, v20
	v_add_f32_e32 v21, 1.0, v21
	v_mad_i64_i32 v[22:23], s[18:19], v34, s44, v[142:143]
	v_rcp_f32_e32 v20, v20
	v_rcp_f32_e32 v21, v21
	global_store_dwordx4 v[22:23], v[16:19], off
	v_pk_mul_f32 v[12:13], v[12:13], v[20:21]
	s_nop 0
	v_mul_f32_e32 v16, 0xbfb8aa3b, v14
	v_mul_f32_e32 v17, 0xbfb8aa3b, v15
	v_exp_f32_e32 v16, v16
	v_exp_f32_e32 v17, v17
	v_pk_mul_f32 v[4:5], v[12:13], v[4:5]
	v_add_u32_e32 v18, 0xb0, v149
	v_add_f32_e32 v12, 1.0, v16
	v_add_f32_e32 v13, 1.0, v17
	v_mul_f32_e32 v16, 0xbfb8aa3b, v8
	v_mul_f32_e32 v17, 0xbfb8aa3b, v9
	v_rcp_f32_e32 v12, v12
	v_rcp_f32_e32 v13, v13
	v_exp_f32_e32 v16, v16
	v_exp_f32_e32 v17, v17
	v_pk_mul_f32 v[12:13], v[14:15], v[12:13]
	v_add_f32_e32 v14, 1.0, v16
	v_add_f32_e32 v15, 1.0, v17
	v_mul_f32_e32 v16, 0xbfb8aa3b, v10
	v_mul_f32_e32 v17, 0xbfb8aa3b, v11
	v_exp_f32_e32 v16, v16
	v_exp_f32_e32 v17, v17
	v_rcp_f32_e32 v14, v14
	v_rcp_f32_e32 v15, v15
	v_add_f32_e32 v16, 1.0, v16
	v_add_f32_e32 v17, 1.0, v17
	v_rcp_f32_e32 v16, v16
	v_rcp_f32_e32 v17, v17
	v_pk_mul_f32 v[8:9], v[8:9], v[14:15]
	v_pk_mul_f32 v[6:7], v[12:13], v[6:7]
	v_pk_mul_f32 v[8:9], v[8:9], v[0:1]
	v_pk_mul_f32 v[0:1], v[10:11], v[16:17]
	s_nop 0
	v_pk_mul_f32 v[10:11], v[0:1], v[2:3]
	v_cvt_pk_bf16_f32 v0, v4, v5
	v_mad_i64_i32 v[4:5], s[18:19], v18, s44, v[142:143]
	v_cvt_pk_bf16_f32 v1, v6, v7
	v_cvt_pk_bf16_f32 v2, v8, v9
	v_cvt_pk_bf16_f32 v3, v10, v11
	s_mov_b64 s[18:19], s[14:15]
	global_store_dwordx4 v[4:5], v[0:3], off
	s_cbranch_vccz .LBB0_1023
	s_waitcnt vmcnt(0)
	s_cmpk_gt_u32 s26, 0xff
	s_cbranch_scc1 .LBB0_1030
	s_barrier
